# k9 plus back-edge rotation: K-loop counter/address SALU and exit compare moved in front of the loop-back barrier in all 10 GEMM loops
# speedup vs baseline: 1.0005x; 1.0000x over previous
; #define PG8_STAGE(bufoff, gbase, voff) do { _Pragma("unroll") for (int _i = 0; _i < 2; ++_i) \
;         __builtin_amdgcn_global_load_lds((const unsigned*)((const char*)(gbase) + (voff)[_i]), (PG8_LAS unsigned*)(lds + (bufoff) + ldsw + _i * 8192), 16, 0, 0); } while (0)
; #define PG8_LDA(dst, b, h) do { _Pragma("unroll") for (int m = 0; m < 4; ++m) _Pragma("unroll") for (int k = 0; k < 2; ++k) dst[m][k] = *(const PG8_LAS bf16x8*)(lds + PG8_SA(b, h) + aoff + m * 2048 + k * 1024); } while (0)
; #define PG8_LDB(dst, b, h) do { _Pragma("unroll") for (int n = 0; n < 2; ++n) _Pragma("unroll") for (int k = 0; k < 2; ++k) dst[n][k] = *(const PG8_LAS bf16x8*)(lds + PG8_SB(b, h) + boff + n * 2048 + k * 1024); } while (0)
; template <class Epi, class Sched, bool ALIGN_EPI = false, bool SP2 = false>
; __device__ __forceinline__ void gemm_phase(PG8_LAS unsigned char* lds, const Gemm g, const Sched& S, const Epi& E, const int wv0) {
;     ...
;         for (int t = 0; t < nt; t += 2) {
;             const bool last = (t == nt - 2);
;             const char* a1 = cA + (size_t)(t + 1) * kstep;
;             const char* a2 = last ? nA : cA + (size_t)(t + 2) * kstep; const char* b2 = last ? nB : cB + (size_t)(t + 2) * kstep;
;             const char* a3 = a2 + kstep; const char* b3 = b2 + kstep;
;             if constexpr (SP2) {
;             PG8_LDB(B0, 0, 0); PG8_LDB(B1, 0, 1); PG8_SCHED; PG8_LDA(At, 0, 0); PG8_STAGE(PG8_SA(1, 1), a1 + hstepA, voffA);
;             PG8_WAIT_V(8); PG8_WAIT_L(0); PG8_BAR; PG8_MMA(0, 0, At, B0); PG8_MMA(0, 1, At, B1); PG8_BAR; PG8_SCHED;
;             PG8_LDA(At, 0, 1); PG8_STAGE(PG8_SB(0, 0), b2, voffB); PG8_STAGE(PG8_SB(0, 1), b2 + hstepB, voffB); PG8_STAGE(PG8_SA(0, 0), a2, voffA);
;             PG8_WAIT_V(8); PG8_WAIT_L(0); PG8_BAR; PG8_MMA(1, 0, At, B0); PG8_MMA(1, 1, At, B1); PG8_BAR; PG8_SCHED;
;             PG8_LDB(B0, 1, 0); PG8_LDB(B1, 1, 1); PG8_SCHED; PG8_LDA(At, 1, 0); PG8_STAGE(PG8_SA(0, 1), a2 + hstepA, voffA);
;             PG8_WAIT_V(8); PG8_WAIT_L(0); PG8_BAR; PG8_MMA(0, 0, At, B0); PG8_MMA(0, 1, At, B1); PG8_BAR; PG8_SCHED;
;             PG8_LDA(At, 1, 1); PG8_STAGE(PG8_SB(1, 0), b3, voffB); PG8_STAGE(PG8_SB(1, 1), b3 + hstepB, voffB); PG8_STAGE(PG8_SA(1, 0), a3, voffA);
;             PG8_WAIT_V(8); PG8_WAIT_L(0); PG8_BAR; PG8_MMA(1, 0, At, B0); PG8_MMA(1, 1, At, B1); PG8_BAR; PG8_SCHED;
.LBB0_82:
	ds_read_b128 v[156:159], v152
	ds_read_b128 v[160:163], v152 offset:1024
	ds_read_b128 v[164:167], v152 offset:2048
	ds_read_b128 v[168:171], v152 offset:3072
	ds_read_b128 v[172:175], v153
	ds_read_b128 v[176:179], v153 offset:1024
	ds_read_b128 v[180:183], v153 offset:2048
	ds_read_b128 v[184:187], v153 offset:3072
	s_add_u32 s34, s30, 0xfff80080
	s_addc_u32 s35, s31, -1
	s_cmp_eq_u32 s38, 28
	s_cselect_b32 s37, s25, s35
	s_cselect_b32 s36, s24, s34
	s_cselect_b32 s35, s27, s23
	s_cselect_b32 s34, s26, s21
	v_lshl_add_u64 v[146:147], s[30:31], 0, v[140:141]
	s_add_i32 m0, s29, 0xc000
	ds_read_b128 v[188:191], v154
	ds_read_b128 v[192:195], v154 offset:1024
	ds_read_b128 v[196:199], v154 offset:2048
	ds_read_b128 v[200:203], v154 offset:3072
	ds_read_b128 v[206:209], v154 offset:4096
	ds_read_b128 v[210:213], v154 offset:5120
	ds_read_b128 v[214:217], v154 offset:6144
	ds_read_b128 v[218:221], v154 offset:7168
	global_load_lds_dwordx4 v[146:147], off
	v_lshl_add_u64 v[146:147], s[30:31], 0, v[138:139]
	s_add_i32 m0, s29, 0xe000
	s_nop 0
	global_load_lds_dwordx4 v[146:147], off
	s_waitcnt vmcnt(8)
	s_waitcnt lgkmcnt(0)
	s_barrier
	s_setprio 1
	v_mfma_f32_16x16x32_bf16 v[124:127], v[156:159], v[188:191], v[124:127]
	v_mfma_f32_16x16x32_bf16 v[120:123], v[164:167], v[188:191], v[120:123]
	v_mfma_f32_16x16x32_bf16 v[116:119], v[156:159], v[196:199], v[116:119]
	v_mfma_f32_16x16x32_bf16 v[108:111], v[164:167], v[196:199], v[108:111]
	v_mfma_f32_16x16x32_bf16 v[100:103], v[156:159], v[206:209], v[100:103]
	v_mfma_f32_16x16x32_bf16 v[92:95], v[164:167], v[206:209], v[92:95]
	v_mfma_f32_16x16x32_bf16 v[84:87], v[156:159], v[214:217], v[84:87]
	v_mfma_f32_16x16x32_bf16 v[76:79], v[164:167], v[214:217], v[76:79]
	v_mfma_f32_16x16x32_bf16 v[124:127], v[160:163], v[192:195], v[124:127]
	v_mfma_f32_16x16x32_bf16 v[120:123], v[168:171], v[192:195], v[120:123]
	v_mfma_f32_16x16x32_bf16 v[116:119], v[160:163], v[200:203], v[116:119]
	v_mfma_f32_16x16x32_bf16 v[108:111], v[168:171], v[200:203], v[108:111]
	v_mfma_f32_16x16x32_bf16 v[100:103], v[160:163], v[210:213], v[100:103]
	v_mfma_f32_16x16x32_bf16 v[92:95], v[168:171], v[210:213], v[92:95]
	v_mfma_f32_16x16x32_bf16 v[84:87], v[160:163], v[218:221], v[84:87]
	v_mfma_f32_16x16x32_bf16 v[76:79], v[168:171], v[218:221], v[76:79]
	v_mfma_f32_16x16x32_bf16 v[112:115], v[172:175], v[188:191], v[112:115]
	v_mfma_f32_16x16x32_bf16 v[104:107], v[180:183], v[188:191], v[104:107]
	v_mfma_f32_16x16x32_bf16 v[96:99], v[172:175], v[196:199], v[96:99]
	v_mfma_f32_16x16x32_bf16 v[88:91], v[180:183], v[196:199], v[88:91]
	v_mfma_f32_16x16x32_bf16 v[80:83], v[172:175], v[206:209], v[80:83]
	v_mfma_f32_16x16x32_bf16 v[72:75], v[180:183], v[206:209], v[72:75]
	v_mfma_f32_16x16x32_bf16 v[68:71], v[172:175], v[214:217], v[68:71]
	v_mfma_f32_16x16x32_bf16 v[64:67], v[180:183], v[214:217], v[64:67]
	v_mfma_f32_16x16x32_bf16 v[112:115], v[176:179], v[192:195], v[112:115]
	v_mfma_f32_16x16x32_bf16 v[104:107], v[184:187], v[192:195], v[104:107]
	v_mfma_f32_16x16x32_bf16 v[96:99], v[176:179], v[200:203], v[96:99]
	v_mfma_f32_16x16x32_bf16 v[88:91], v[184:187], v[200:203], v[88:91]
	v_mfma_f32_16x16x32_bf16 v[80:83], v[176:179], v[210:213], v[80:83]
	v_mfma_f32_16x16x32_bf16 v[72:75], v[184:187], v[210:213], v[72:75]
	v_mfma_f32_16x16x32_bf16 v[68:71], v[176:179], v[218:221], v[68:71]
	v_mfma_f32_16x16x32_bf16 v[64:67], v[184:187], v[218:221], v[64:67]
	s_setprio 0
	s_barrier
	s_add_i32 s39, s62, s47
	v_lshl_add_u64 v[146:147], s[34:35], 0, v[132:133]
	s_mov_b32 m0, s39
	ds_read_b128 v[188:191], v154 offset:16384
	ds_read_b128 v[192:195], v154 offset:17408
	ds_read_b128 v[196:199], v154 offset:18432
	ds_read_b128 v[200:203], v154 offset:19456
	ds_read_b128 v[206:209], v154 offset:20480
	ds_read_b128 v[210:213], v154 offset:21504
	ds_read_b128 v[214:217], v154 offset:22528
	ds_read_b128 v[218:221], v154 offset:23552
	global_load_lds_dwordx4 v[146:147], off
	s_add_i32 m0, s39, 0x2000
	s_add_u32 s68, s34, 0x80000
	v_lshl_add_u64 v[222:223], s[34:35], 0, v[128:129]
	s_addc_u32 s69, s35, 0
	s_add_i32 s39, s63, s47
	global_load_lds_dwordx4 v[222:223], off
	v_lshl_add_u64 v[224:225], s[68:69], 0, v[132:133]
	s_mov_b32 m0, s39
	v_lshl_add_u64 v[226:227], s[36:37], 0, v[130:131]
	global_load_lds_dwordx4 v[224:225], off
	v_lshl_add_u64 v[224:225], s[68:69], 0, v[128:129]
	s_add_i32 m0, s39, 0x2000
	s_nop 0
	global_load_lds_dwordx4 v[224:225], off
	v_lshl_add_u64 v[224:225], s[36:37], 0, v[134:135]
	s_mov_b32 m0, s29
	s_nop 0
	global_load_lds_dwordx4 v[224:225], off
	s_mov_b32 m0, s49
	s_nop 0
	global_load_lds_dwordx4 v[226:227], off
	s_waitcnt vmcnt(8)
	s_waitcnt lgkmcnt(0)
	s_barrier
; #define PG8_STAGE(bufoff, gbase, voff) do { _Pragma("unroll") for (int _i = 0; _i < 2; ++_i) \
;         __builtin_amdgcn_global_load_lds((const unsigned*)((const char*)(gbase) + (voff)[_i]), (PG8_LAS unsigned*)(lds + (bufoff) + ldsw + _i * 8192), 16, 0, 0); } while (0)
; #define PG8_LDA(dst, b, h) do { _Pragma("unroll") for (int m = 0; m < 4; ++m) _Pragma("unroll") for (int k = 0; k < 2; ++k) dst[m][k] = *(const PG8_LAS bf16x8*)(lds + PG8_SA(b, h) + aoff + m * 2048 + k * 1024); } while (0)
; #define PG8_LDB(dst, b, h) do { _Pragma("unroll") for (int n = 0; n < 2; ++n) _Pragma("unroll") for (int k = 0; k < 2; ++k) dst[n][k] = *(const PG8_LAS bf16x8*)(lds + PG8_SB(b, h) + boff + n * 2048 + k * 1024); } while (0)
; #define PG8_MMA(ai, bj, At, Bt) do { __builtin_amdgcn_s_setprio(1); _Pragma("unroll") for (int m = 0; m < 4; ++m) _Pragma("unroll") for (int n = 0; n < 2; ++n) _Pragma("unroll") for (int k = 0; k < 2; ++k) \
;         acc[ai][bj][m][n] = __builtin_amdgcn_mfma_f32_16x16x32_bf16(Bt[n][k], At[m][k], acc[ai][bj][m][n], 0, 0, 0); __builtin_amdgcn_s_setprio(0); } while (0)
; #define PG8_WAIT_V(n) asm volatile("s_waitcnt vmcnt(" #n ")" ::: "memory")
; #define PG8_WAIT_L(n) asm volatile("s_waitcnt lgkmcnt(" #n ")" ::: "memory")
; #define PG8_BAR __builtin_amdgcn_s_barrier()
; #define PG8_SCHED __builtin_amdgcn_sched_barrier(0)
; template <class Epi, class Sched, bool ALIGN_EPI = false, bool SP2 = false>
; __device__ __forceinline__ void gemm_phase(PG8_LAS unsigned char* lds, const Gemm g, const Sched& S, const Epi& E, const int wv0) {
;     ...
;             PG8_WAIT_V(8); PG8_WAIT_L(0); PG8_BAR; PG8_MMA(1, 0, At, B0); PG8_MMA(1, 1, At, B1); PG8_BAR; PG8_SCHED;
;             PG8_LDB(B0, 1, 0); PG8_LDB(B1, 1, 1); PG8_SCHED; PG8_LDA(At, 1, 0); PG8_STAGE(PG8_SA(0, 1), a2 + hstepA, voffA);
;             PG8_WAIT_V(8); PG8_WAIT_L(0); PG8_BAR; PG8_MMA(0, 0, At, B0); PG8_MMA(0, 1, At, B1); PG8_BAR; PG8_SCHED;
	s_setprio 1
	v_mfma_f32_16x16x32_bf16 v[60:63], v[156:159], v[188:191], v[60:63]
	v_mfma_f32_16x16x32_bf16 v[56:59], v[164:167], v[188:191], v[56:59]
	v_mfma_f32_16x16x32_bf16 v[52:55], v[156:159], v[196:199], v[52:55]
	v_mfma_f32_16x16x32_bf16 v[44:47], v[164:167], v[196:199], v[44:47]
	v_mfma_f32_16x16x32_bf16 v[36:39], v[156:159], v[206:209], v[36:39]
	v_mfma_f32_16x16x32_bf16 v[28:31], v[164:167], v[206:209], v[28:31]
	v_mfma_f32_16x16x32_bf16 v[20:23], v[156:159], v[214:217], v[20:23]
	v_mfma_f32_16x16x32_bf16 v[12:15], v[164:167], v[214:217], v[12:15]
	v_mfma_f32_16x16x32_bf16 v[60:63], v[160:163], v[192:195], v[60:63]
	v_mfma_f32_16x16x32_bf16 v[56:59], v[168:171], v[192:195], v[56:59]
	v_mfma_f32_16x16x32_bf16 v[52:55], v[160:163], v[200:203], v[52:55]
	v_mfma_f32_16x16x32_bf16 v[44:47], v[168:171], v[200:203], v[44:47]
	v_mfma_f32_16x16x32_bf16 v[36:39], v[160:163], v[210:213], v[36:39]
	v_mfma_f32_16x16x32_bf16 v[28:31], v[168:171], v[210:213], v[28:31]
	v_mfma_f32_16x16x32_bf16 v[20:23], v[160:163], v[218:221], v[20:23]
	v_mfma_f32_16x16x32_bf16 v[12:15], v[168:171], v[218:221], v[12:15]
	v_mfma_f32_16x16x32_bf16 v[48:51], v[172:175], v[188:191], v[48:51]
	v_mfma_f32_16x16x32_bf16 v[40:43], v[180:183], v[188:191], v[40:43]
	v_mfma_f32_16x16x32_bf16 v[32:35], v[172:175], v[196:199], v[32:35]
	v_mfma_f32_16x16x32_bf16 v[24:27], v[180:183], v[196:199], v[24:27]
	v_mfma_f32_16x16x32_bf16 v[16:19], v[172:175], v[206:209], v[16:19]
	v_mfma_f32_16x16x32_bf16 v[8:11], v[180:183], v[206:209], v[8:11]
	v_mfma_f32_16x16x32_bf16 v[4:7], v[172:175], v[214:217], v[4:7]
	v_mfma_f32_16x16x32_bf16 v[0:3], v[180:183], v[214:217], v[0:3]
	v_mfma_f32_16x16x32_bf16 v[48:51], v[176:179], v[192:195], v[48:51]
	v_mfma_f32_16x16x32_bf16 v[40:43], v[184:187], v[192:195], v[40:43]
	v_mfma_f32_16x16x32_bf16 v[32:35], v[176:179], v[200:203], v[32:35]
	v_mfma_f32_16x16x32_bf16 v[24:27], v[184:187], v[200:203], v[24:27]
	v_mfma_f32_16x16x32_bf16 v[16:19], v[176:179], v[210:213], v[16:19]
	v_mfma_f32_16x16x32_bf16 v[8:11], v[184:187], v[210:213], v[8:11]
	v_mfma_f32_16x16x32_bf16 v[4:7], v[176:179], v[218:221], v[4:7]
	v_mfma_f32_16x16x32_bf16 v[0:3], v[184:187], v[218:221], v[0:3]
	s_setprio 0
	s_barrier
	s_add_i32 s39, 0, 0x18000
	v_add_u32_e32 v155, s39, v150
	s_add_i32 s68, 0, 0x1c000
	ds_read_b128 v[156:159], v155
	ds_read_b128 v[160:163], v155 offset:1024
	ds_read_b128 v[164:167], v155 offset:2048
	ds_read_b128 v[168:171], v155 offset:3072
	v_add_u32_e32 v155, s68, v150
	ds_read_b128 v[172:175], v155
	ds_read_b128 v[176:179], v155 offset:1024
	ds_read_b128 v[180:183], v155 offset:2048
	ds_read_b128 v[184:187], v155 offset:3072
	s_add_u32 s36, s36, 0x80000
	s_addc_u32 s37, s37, 0
	s_mov_b32 m0, s50
	v_lshl_add_u64 v[228:229], s[36:37], 0, v[134:135]
	ds_read_b128 v[188:191], v154 offset:32768
	ds_read_b128 v[192:195], v154 offset:33792
	ds_read_b128 v[196:199], v154 offset:34816
	ds_read_b128 v[200:203], v154 offset:35840
	ds_read_b128 v[206:209], v154 offset:36864
	ds_read_b128 v[210:213], v154 offset:37888
	ds_read_b128 v[214:217], v154 offset:38912
	ds_read_b128 v[218:221], v154 offset:39936
	global_load_lds_dwordx4 v[228:229], off
	v_lshl_add_u64 v[228:229], s[36:37], 0, v[130:131]
	s_mov_b32 m0, s51
	s_nop 0
	global_load_lds_dwordx4 v[228:229], off
	s_waitcnt vmcnt(8)
	s_waitcnt lgkmcnt(0)
	s_barrier
	s_setprio 1
	v_mfma_f32_16x16x32_bf16 v[124:127], v[156:159], v[188:191], v[124:127]
	v_mfma_f32_16x16x32_bf16 v[120:123], v[164:167], v[188:191], v[120:123]
	v_mfma_f32_16x16x32_bf16 v[116:119], v[156:159], v[196:199], v[116:119]
	v_mfma_f32_16x16x32_bf16 v[108:111], v[164:167], v[196:199], v[108:111]
	v_mfma_f32_16x16x32_bf16 v[100:103], v[156:159], v[206:209], v[100:103]
	v_mfma_f32_16x16x32_bf16 v[92:95], v[164:167], v[206:209], v[92:95]
	v_mfma_f32_16x16x32_bf16 v[84:87], v[156:159], v[214:217], v[84:87]
	v_mfma_f32_16x16x32_bf16 v[76:79], v[164:167], v[214:217], v[76:79]
	v_mfma_f32_16x16x32_bf16 v[124:127], v[160:163], v[192:195], v[124:127]
	v_mfma_f32_16x16x32_bf16 v[120:123], v[168:171], v[192:195], v[120:123]
	v_mfma_f32_16x16x32_bf16 v[116:119], v[160:163], v[200:203], v[116:119]
	v_mfma_f32_16x16x32_bf16 v[108:111], v[168:171], v[200:203], v[108:111]
	v_mfma_f32_16x16x32_bf16 v[100:103], v[160:163], v[210:213], v[100:103]
	v_mfma_f32_16x16x32_bf16 v[92:95], v[168:171], v[210:213], v[92:95]
	v_mfma_f32_16x16x32_bf16 v[84:87], v[160:163], v[218:221], v[84:87]
	v_mfma_f32_16x16x32_bf16 v[76:79], v[168:171], v[218:221], v[76:79]
	v_mfma_f32_16x16x32_bf16 v[112:115], v[172:175], v[188:191], v[112:115]
	v_mfma_f32_16x16x32_bf16 v[104:107], v[180:183], v[188:191], v[104:107]
	v_mfma_f32_16x16x32_bf16 v[96:99], v[172:175], v[196:199], v[96:99]
	v_mfma_f32_16x16x32_bf16 v[88:91], v[180:183], v[196:199], v[88:91]
	v_mfma_f32_16x16x32_bf16 v[80:83], v[172:175], v[206:209], v[80:83]
	v_mfma_f32_16x16x32_bf16 v[72:75], v[180:183], v[206:209], v[72:75]
	v_mfma_f32_16x16x32_bf16 v[68:71], v[172:175], v[214:217], v[68:71]
	v_mfma_f32_16x16x32_bf16 v[64:67], v[180:183], v[214:217], v[64:67]
	v_mfma_f32_16x16x32_bf16 v[112:115], v[176:179], v[192:195], v[112:115]
	v_mfma_f32_16x16x32_bf16 v[104:107], v[184:187], v[192:195], v[104:107]
	v_mfma_f32_16x16x32_bf16 v[96:99], v[176:179], v[200:203], v[96:99]
	v_mfma_f32_16x16x32_bf16 v[88:91], v[184:187], v[200:203], v[88:91]
	v_mfma_f32_16x16x32_bf16 v[80:83], v[176:179], v[210:213], v[80:83]
	v_mfma_f32_16x16x32_bf16 v[72:75], v[184:187], v[210:213], v[72:75]
	v_mfma_f32_16x16x32_bf16 v[68:71], v[176:179], v[218:221], v[68:71]
	v_mfma_f32_16x16x32_bf16 v[64:67], v[184:187], v[218:221], v[64:67]
	s_setprio 0
	s_barrier
; #define PG8_STAGE(bufoff, gbase, voff) do { _Pragma("unroll") for (int _i = 0; _i < 2; ++_i) \
;         __builtin_amdgcn_global_load_lds((const unsigned*)((const char*)(gbase) + (voff)[_i]), (PG8_LAS unsigned*)(lds + (bufoff) + ldsw + _i * 8192), 16, 0, 0); } while (0)
; #define PG8_LDA(dst, b, h) do { _Pragma("unroll") for (int m = 0; m < 4; ++m) _Pragma("unroll") for (int k = 0; k < 2; ++k) dst[m][k] = *(const PG8_LAS bf16x8*)(lds + PG8_SA(b, h) + aoff + m * 2048 + k * 1024); } while (0)
; #define PG8_MMA(ai, bj, At, Bt) do { __builtin_amdgcn_s_setprio(1); _Pragma("unroll") for (int m = 0; m < 4; ++m) _Pragma("unroll") for (int n = 0; n < 2; ++n) _Pragma("unroll") for (int k = 0; k < 2; ++k) \
;         acc[ai][bj][m][n] = __builtin_amdgcn_mfma_f32_16x16x32_bf16(Bt[n][k], At[m][k], acc[ai][bj][m][n], 0, 0, 0); __builtin_amdgcn_s_setprio(0); } while (0)
; #define PG8_WAIT_V(n) asm volatile("s_waitcnt vmcnt(" #n ")" ::: "memory")
; #define PG8_WAIT_L(n) asm volatile("s_waitcnt lgkmcnt(" #n ")" ::: "memory")
; #define PG8_BAR __builtin_amdgcn_s_barrier()
; #define PG8_SCHED __builtin_amdgcn_sched_barrier(0)
; template <class Epi, class Sched, bool ALIGN_EPI = false, bool SP2 = false>
; __device__ __forceinline__ void gemm_phase(PG8_LAS unsigned char* lds, const Gemm g, const Sched& S, const Epi& E, const int wv0) {
;     ...
;         for (int t = 0; t < nt; t += 2) {
;             const bool last = (t == nt - 2);
;     ...
;             PG8_LDA(At, 1, 1); PG8_STAGE(PG8_SB(1, 0), b3, voffB); PG8_STAGE(PG8_SB(1, 1), b3 + hstepB, voffB); PG8_STAGE(PG8_SA(1, 0), a3, voffA);
;             PG8_WAIT_V(8); PG8_WAIT_L(0); PG8_BAR; PG8_MMA(1, 0, At, B0); PG8_MMA(1, 1, At, B1); PG8_BAR; PG8_SCHED;
	s_add_i32 s36, s39, s47
	v_lshl_add_u64 v[146:147], v[146:147], 0, s[14:15]
	s_mov_b32 m0, s36
	ds_read_b128 v[188:191], v154 offset:49152
	ds_read_b128 v[192:195], v154 offset:50176
	ds_read_b128 v[196:199], v154 offset:51200
	ds_read_b128 v[200:203], v154 offset:52224
	ds_read_b128 v[206:209], v154 offset:53248
	ds_read_b128 v[210:213], v154 offset:54272
	ds_read_b128 v[214:217], v154 offset:55296
	ds_read_b128 v[218:221], v154 offset:56320
	global_load_lds_dwordx4 v[146:147], off
	s_add_i32 m0, s36, 0x2000
	s_add_u32 s34, s34, 0x80080
	v_lshl_add_u64 v[146:147], v[222:223], 0, s[14:15]
	s_addc_u32 s35, s35, 0
	s_add_i32 s36, s68, s47
	global_load_lds_dwordx4 v[146:147], off
	v_lshl_add_u64 v[146:147], s[34:35], 0, v[132:133]
	s_mov_b32 m0, s36
	s_nop 0
	global_load_lds_dwordx4 v[146:147], off
	v_lshl_add_u64 v[146:147], s[34:35], 0, v[128:129]
	s_add_i32 m0, s36, 0x2000
	s_nop 0
	global_load_lds_dwordx4 v[146:147], off
	v_lshl_add_u64 v[146:147], v[224:225], 0, s[14:15]
	s_mov_b32 m0, s58
	s_nop 0
	global_load_lds_dwordx4 v[146:147], off
	v_lshl_add_u64 v[146:147], v[226:227], 0, s[14:15]
	s_mov_b32 m0, s59
	s_nop 0
	global_load_lds_dwordx4 v[146:147], off
	s_waitcnt vmcnt(8)
	s_waitcnt lgkmcnt(0)
	s_barrier
	s_setprio 1
	v_mfma_f32_16x16x32_bf16 v[60:63], v[156:159], v[188:191], v[60:63]
	v_mfma_f32_16x16x32_bf16 v[56:59], v[164:167], v[188:191], v[56:59]
	v_mfma_f32_16x16x32_bf16 v[52:55], v[156:159], v[196:199], v[52:55]
	v_mfma_f32_16x16x32_bf16 v[44:47], v[164:167], v[196:199], v[44:47]
	v_mfma_f32_16x16x32_bf16 v[36:39], v[156:159], v[206:209], v[36:39]
	v_mfma_f32_16x16x32_bf16 v[28:31], v[164:167], v[206:209], v[28:31]
	v_mfma_f32_16x16x32_bf16 v[20:23], v[156:159], v[214:217], v[20:23]
	v_mfma_f32_16x16x32_bf16 v[12:15], v[164:167], v[214:217], v[12:15]
	v_mfma_f32_16x16x32_bf16 v[60:63], v[160:163], v[192:195], v[60:63]
	v_mfma_f32_16x16x32_bf16 v[56:59], v[168:171], v[192:195], v[56:59]
	v_mfma_f32_16x16x32_bf16 v[52:55], v[160:163], v[200:203], v[52:55]
	v_mfma_f32_16x16x32_bf16 v[44:47], v[168:171], v[200:203], v[44:47]
	v_mfma_f32_16x16x32_bf16 v[36:39], v[160:163], v[210:213], v[36:39]
	v_mfma_f32_16x16x32_bf16 v[28:31], v[168:171], v[210:213], v[28:31]
	v_mfma_f32_16x16x32_bf16 v[20:23], v[160:163], v[218:221], v[20:23]
	v_mfma_f32_16x16x32_bf16 v[12:15], v[168:171], v[218:221], v[12:15]
	v_mfma_f32_16x16x32_bf16 v[48:51], v[172:175], v[188:191], v[48:51]
	v_mfma_f32_16x16x32_bf16 v[40:43], v[180:183], v[188:191], v[40:43]
	v_mfma_f32_16x16x32_bf16 v[32:35], v[172:175], v[196:199], v[32:35]
	v_mfma_f32_16x16x32_bf16 v[24:27], v[180:183], v[196:199], v[24:27]
	v_mfma_f32_16x16x32_bf16 v[16:19], v[172:175], v[206:209], v[16:19]
	v_mfma_f32_16x16x32_bf16 v[8:11], v[180:183], v[206:209], v[8:11]
	v_mfma_f32_16x16x32_bf16 v[4:7], v[172:175], v[214:217], v[4:7]
	v_mfma_f32_16x16x32_bf16 v[0:3], v[180:183], v[214:217], v[0:3]
	v_mfma_f32_16x16x32_bf16 v[48:51], v[176:179], v[192:195], v[48:51]
	v_mfma_f32_16x16x32_bf16 v[40:43], v[184:187], v[192:195], v[40:43]
	v_mfma_f32_16x16x32_bf16 v[32:35], v[176:179], v[200:203], v[32:35]
	v_mfma_f32_16x16x32_bf16 v[24:27], v[184:187], v[200:203], v[24:27]
	v_mfma_f32_16x16x32_bf16 v[16:19], v[176:179], v[210:213], v[16:19]
	v_mfma_f32_16x16x32_bf16 v[8:11], v[184:187], v[210:213], v[8:11]
	v_mfma_f32_16x16x32_bf16 v[4:7], v[176:179], v[218:221], v[4:7]
	v_mfma_f32_16x16x32_bf16 v[0:3], v[184:187], v[218:221], v[0:3]
	s_setprio 0
	s_add_i32 s38, s38, 2
	s_add_u32 s21, s21, 0x100
	s_addc_u32 s23, s23, 0
	s_add_u32 s30, s30, 0x100
	s_addc_u32 s31, s31, 0
	s_cmp_gt_u32 s38, 29
	s_barrier
	s_cbranch_scc0 .LBB0_82
	s_and_b64 vcc, exec, s[18:19]
	s_cbranch_vccz .LBB0_85
	s_barrier

; #define PG8_STAGE(bufoff, gbase, voff) do { _Pragma("unroll") for (int _i = 0; _i < 2; ++_i) \
;         __builtin_amdgcn_global_load_lds((const unsigned*)((const char*)(gbase) + (voff)[_i]), (PG8_LAS unsigned*)(lds + (bufoff) + ldsw + _i * 8192), 16, 0, 0); } while (0)
; #define PG8_LDA(dst, b, h) do { _Pragma("unroll") for (int m = 0; m < 4; ++m) _Pragma("unroll") for (int k = 0; k < 2; ++k) dst[m][k] = *(const PG8_LAS bf16x8*)(lds + PG8_SA(b, h) + aoff + m * 2048 + k * 1024); } while (0)
; #define PG8_LDB(dst, b, h) do { _Pragma("unroll") for (int n = 0; n < 2; ++n) _Pragma("unroll") for (int k = 0; k < 2; ++k) dst[n][k] = *(const PG8_LAS bf16x8*)(lds + PG8_SB(b, h) + boff + n * 2048 + k * 1024); } while (0)
; template <class Epi, class Sched, bool ALIGN_EPI = false, bool SP2 = false>
; __device__ __forceinline__ void gemm_phase(PG8_LAS unsigned char* lds, const Gemm g, const Sched& S, const Epi& E, const int wv0) {
;     ...
;         for (int t = 0; t < nt; t += 2) {
;             const bool last = (t == nt - 2);
;             const char* a1 = cA + (size_t)(t + 1) * kstep;
;             const char* a2 = last ? nA : cA + (size_t)(t + 2) * kstep; const char* b2 = last ? nB : cB + (size_t)(t + 2) * kstep;
;             const char* a3 = a2 + kstep; const char* b3 = b2 + kstep;
;             if constexpr (SP2) {
;             PG8_LDB(B0, 0, 0); PG8_LDB(B1, 0, 1); PG8_SCHED; PG8_LDA(At, 0, 0); PG8_STAGE(PG8_SA(1, 1), a1 + hstepA, voffA);
;             PG8_WAIT_V(8); PG8_WAIT_L(0); PG8_BAR; PG8_MMA(0, 0, At, B0); PG8_MMA(0, 1, At, B1); PG8_BAR; PG8_SCHED;
;             PG8_LDA(At, 0, 1); PG8_STAGE(PG8_SB(0, 0), b2, voffB); PG8_STAGE(PG8_SB(0, 1), b2 + hstepB, voffB); PG8_STAGE(PG8_SA(0, 0), a2, voffA);
;             PG8_WAIT_V(8); PG8_WAIT_L(0); PG8_BAR; PG8_MMA(1, 0, At, B0); PG8_MMA(1, 1, At, B1); PG8_BAR; PG8_SCHED;
;             PG8_LDB(B0, 1, 0); PG8_LDB(B1, 1, 1); PG8_SCHED; PG8_LDA(At, 1, 0); PG8_STAGE(PG8_SA(0, 1), a2 + hstepA, voffA);
;             PG8_WAIT_V(8); PG8_WAIT_L(0); PG8_BAR; PG8_MMA(0, 0, At, B0); PG8_MMA(0, 1, At, B1); PG8_BAR; PG8_SCHED;
;             PG8_LDA(At, 1, 1); PG8_STAGE(PG8_SB(1, 0), b3, voffB); PG8_STAGE(PG8_SB(1, 1), b3 + hstepB, voffB); PG8_STAGE(PG8_SA(1, 0), a3, voffA);
;             PG8_WAIT_V(8); PG8_WAIT_L(0); PG8_BAR; PG8_MMA(1, 0, At, B0); PG8_MMA(1, 1, At, B1); PG8_BAR; PG8_SCHED;
.LBB0_494:
	v_add_u32_e32 v158, s61, v207
	v_add_u32_e32 v174, s62, v207
	ds_read_b128 v[146:149], v158
	ds_read_b128 v[150:153], v158 offset:1024
	ds_read_b128 v[154:157], v158 offset:2048
	ds_read_b128 v[158:161], v158 offset:3072
	ds_read_b128 v[162:165], v174
	ds_read_b128 v[166:169], v174 offset:1024
	ds_read_b128 v[170:173], v174 offset:2048
	ds_read_b128 v[174:177], v174 offset:3072
	s_add_u32 s41, s38, 0xfffc0080
	s_addc_u32 s44, s39, -1
	s_cmp_eq_u32 s29, 12
	s_cselect_b32 s47, s5, s44
	s_cselect_b32 s46, s4, s41
	s_cselect_b32 s45, s37, s27
	s_cselect_b32 s44, s36, s25
	v_lshl_add_u64 v[202:203], s[38:39], 0, v[140:141]
	s_add_i32 m0, s55, 0xc000
	ds_read_b128 v[178:181], v209
	ds_read_b128 v[182:185], v209 offset:1024
	ds_read_b128 v[186:189], v209 offset:2048
	ds_read_b128 v[190:193], v209 offset:3072
	ds_read_b128 v[194:197], v209 offset:4096
	ds_read_b128 v[198:201], v209 offset:5120
	ds_read_b128 v[210:213], v209 offset:6144
	ds_read_b128 v[214:217], v209 offset:7168
	global_load_lds_dwordx4 v[202:203], off
	v_lshl_add_u64 v[202:203], s[38:39], 0, v[138:139]
	s_add_i32 m0, s55, 0xe000
	s_nop 0
	global_load_lds_dwordx4 v[202:203], off
	s_waitcnt vmcnt(8)
	s_waitcnt lgkmcnt(0)
	s_barrier
	s_setprio 1
	v_mfma_f32_16x16x32_bf16 v[124:127], v[146:149], v[178:181], v[124:127]
	v_mfma_f32_16x16x32_bf16 v[120:123], v[154:157], v[178:181], v[120:123]
	v_mfma_f32_16x16x32_bf16 v[108:111], v[146:149], v[186:189], v[108:111]
	v_mfma_f32_16x16x32_bf16 v[104:107], v[154:157], v[186:189], v[104:107]
	v_mfma_f32_16x16x32_bf16 v[92:95], v[146:149], v[194:197], v[92:95]
	v_mfma_f32_16x16x32_bf16 v[88:91], v[154:157], v[194:197], v[88:91]
	v_mfma_f32_16x16x32_bf16 v[76:79], v[146:149], v[210:213], v[76:79]
	v_mfma_f32_16x16x32_bf16 v[72:75], v[154:157], v[210:213], v[72:75]
	v_mfma_f32_16x16x32_bf16 v[124:127], v[150:153], v[182:185], v[124:127]
	v_mfma_f32_16x16x32_bf16 v[120:123], v[158:161], v[182:185], v[120:123]
	v_mfma_f32_16x16x32_bf16 v[108:111], v[150:153], v[190:193], v[108:111]
	v_mfma_f32_16x16x32_bf16 v[104:107], v[158:161], v[190:193], v[104:107]
	v_mfma_f32_16x16x32_bf16 v[92:95], v[150:153], v[198:201], v[92:95]
	v_mfma_f32_16x16x32_bf16 v[88:91], v[158:161], v[198:201], v[88:91]
	v_mfma_f32_16x16x32_bf16 v[76:79], v[150:153], v[214:217], v[76:79]
	v_mfma_f32_16x16x32_bf16 v[72:75], v[158:161], v[214:217], v[72:75]
	v_mfma_f32_16x16x32_bf16 v[116:119], v[162:165], v[178:181], v[116:119]
	v_mfma_f32_16x16x32_bf16 v[112:115], v[170:173], v[178:181], v[112:115]
	v_mfma_f32_16x16x32_bf16 v[100:103], v[162:165], v[186:189], v[100:103]
	v_mfma_f32_16x16x32_bf16 v[96:99], v[170:173], v[186:189], v[96:99]
	v_mfma_f32_16x16x32_bf16 v[84:87], v[162:165], v[194:197], v[84:87]
	v_mfma_f32_16x16x32_bf16 v[80:83], v[170:173], v[194:197], v[80:83]
	v_mfma_f32_16x16x32_bf16 v[68:71], v[162:165], v[210:213], v[68:71]
	v_mfma_f32_16x16x32_bf16 v[64:67], v[170:173], v[210:213], v[64:67]
	v_mfma_f32_16x16x32_bf16 v[116:119], v[166:169], v[182:185], v[116:119]
	v_mfma_f32_16x16x32_bf16 v[112:115], v[174:177], v[182:185], v[112:115]
	v_mfma_f32_16x16x32_bf16 v[100:103], v[166:169], v[190:193], v[100:103]
	v_mfma_f32_16x16x32_bf16 v[96:99], v[174:177], v[190:193], v[96:99]
	v_mfma_f32_16x16x32_bf16 v[84:87], v[166:169], v[198:201], v[84:87]
	v_mfma_f32_16x16x32_bf16 v[80:83], v[174:177], v[198:201], v[80:83]
	v_mfma_f32_16x16x32_bf16 v[68:71], v[166:169], v[214:217], v[68:71]
	v_mfma_f32_16x16x32_bf16 v[64:67], v[174:177], v[214:217], v[64:67]
	s_setprio 0
	s_barrier
	s_add_i32 s41, s61, s54
	v_lshl_add_u64 v[202:203], s[44:45], 0, v[130:131]
	s_mov_b32 m0, s41
	ds_read_b128 v[178:181], v209 offset:16384
	ds_read_b128 v[182:185], v209 offset:17408
	ds_read_b128 v[186:189], v209 offset:18432
	ds_read_b128 v[190:193], v209 offset:19456
	ds_read_b128 v[194:197], v209 offset:20480
	ds_read_b128 v[198:201], v209 offset:21504
	ds_read_b128 v[210:213], v209 offset:22528
	ds_read_b128 v[214:217], v209 offset:23552
	global_load_lds_dwordx4 v[202:203], off
	s_add_i32 m0, s41, 0x2000
	s_add_u32 s64, s44, 0x40000
	v_lshl_add_u64 v[218:219], s[44:45], 0, v[134:135]
	s_addc_u32 s65, s45, 0
	s_add_i32 s41, s62, s54
	global_load_lds_dwordx4 v[218:219], off
	v_lshl_add_u64 v[220:221], s[64:65], 0, v[130:131]
	s_mov_b32 m0, s41
	v_lshl_add_u64 v[222:223], s[46:47], 0, v[132:133]
	global_load_lds_dwordx4 v[220:221], off
	v_lshl_add_u64 v[220:221], s[64:65], 0, v[134:135]
	s_add_i32 m0, s41, 0x2000
	s_nop 0
	global_load_lds_dwordx4 v[220:221], off
	v_lshl_add_u64 v[220:221], s[46:47], 0, v[128:129]
	s_mov_b32 m0, s55
	s_nop 0
	global_load_lds_dwordx4 v[220:221], off
	s_mov_b32 m0, s56
	s_nop 0
	global_load_lds_dwordx4 v[222:223], off
	s_waitcnt vmcnt(8)
	s_waitcnt lgkmcnt(0)
	s_barrier
; #define PG8_STAGE(bufoff, gbase, voff) do { _Pragma("unroll") for (int _i = 0; _i < 2; ++_i) \
;         __builtin_amdgcn_global_load_lds((const unsigned*)((const char*)(gbase) + (voff)[_i]), (PG8_LAS unsigned*)(lds + (bufoff) + ldsw + _i * 8192), 16, 0, 0); } while (0)
; #define PG8_LDA(dst, b, h) do { _Pragma("unroll") for (int m = 0; m < 4; ++m) _Pragma("unroll") for (int k = 0; k < 2; ++k) dst[m][k] = *(const PG8_LAS bf16x8*)(lds + PG8_SA(b, h) + aoff + m * 2048 + k * 1024); } while (0)
; #define PG8_LDB(dst, b, h) do { _Pragma("unroll") for (int n = 0; n < 2; ++n) _Pragma("unroll") for (int k = 0; k < 2; ++k) dst[n][k] = *(const PG8_LAS bf16x8*)(lds + PG8_SB(b, h) + boff + n * 2048 + k * 1024); } while (0)
; #define PG8_MMA(ai, bj, At, Bt) do { __builtin_amdgcn_s_setprio(1); _Pragma("unroll") for (int m = 0; m < 4; ++m) _Pragma("unroll") for (int n = 0; n < 2; ++n) _Pragma("unroll") for (int k = 0; k < 2; ++k) \
;         acc[ai][bj][m][n] = __builtin_amdgcn_mfma_f32_16x16x32_bf16(Bt[n][k], At[m][k], acc[ai][bj][m][n], 0, 0, 0); __builtin_amdgcn_s_setprio(0); } while (0)
; #define PG8_WAIT_V(n) asm volatile("s_waitcnt vmcnt(" #n ")" ::: "memory")
; #define PG8_WAIT_L(n) asm volatile("s_waitcnt lgkmcnt(" #n ")" ::: "memory")
; #define PG8_BAR __builtin_amdgcn_s_barrier()
; #define PG8_SCHED __builtin_amdgcn_sched_barrier(0)
; template <class Epi, class Sched, bool ALIGN_EPI = false, bool SP2 = false>
; __device__ __forceinline__ void gemm_phase(PG8_LAS unsigned char* lds, const Gemm g, const Sched& S, const Epi& E, const int wv0) {
;     ...
;             PG8_WAIT_V(8); PG8_WAIT_L(0); PG8_BAR; PG8_MMA(1, 0, At, B0); PG8_MMA(1, 1, At, B1); PG8_BAR; PG8_SCHED;
;             PG8_LDB(B0, 1, 0); PG8_LDB(B1, 1, 1); PG8_SCHED; PG8_LDA(At, 1, 0); PG8_STAGE(PG8_SA(0, 1), a2 + hstepA, voffA);
;             PG8_WAIT_V(8); PG8_WAIT_L(0); PG8_BAR; PG8_MMA(0, 0, At, B0); PG8_MMA(0, 1, At, B1); PG8_BAR; PG8_SCHED;
	s_setprio 1
	v_mfma_f32_16x16x32_bf16 v[60:63], v[146:149], v[178:181], v[60:63]
	v_mfma_f32_16x16x32_bf16 v[56:59], v[154:157], v[178:181], v[56:59]
	v_mfma_f32_16x16x32_bf16 v[44:47], v[146:149], v[186:189], v[44:47]
	v_mfma_f32_16x16x32_bf16 v[40:43], v[154:157], v[186:189], v[40:43]
	v_mfma_f32_16x16x32_bf16 v[28:31], v[146:149], v[194:197], v[28:31]
	v_mfma_f32_16x16x32_bf16 v[24:27], v[154:157], v[194:197], v[24:27]
	v_mfma_f32_16x16x32_bf16 v[12:15], v[146:149], v[210:213], v[12:15]
	v_mfma_f32_16x16x32_bf16 v[8:11], v[154:157], v[210:213], v[8:11]
	v_mfma_f32_16x16x32_bf16 v[60:63], v[150:153], v[182:185], v[60:63]
	v_mfma_f32_16x16x32_bf16 v[56:59], v[158:161], v[182:185], v[56:59]
	v_mfma_f32_16x16x32_bf16 v[44:47], v[150:153], v[190:193], v[44:47]
	v_mfma_f32_16x16x32_bf16 v[40:43], v[158:161], v[190:193], v[40:43]
	v_mfma_f32_16x16x32_bf16 v[28:31], v[150:153], v[198:201], v[28:31]
	v_mfma_f32_16x16x32_bf16 v[24:27], v[158:161], v[198:201], v[24:27]
	v_mfma_f32_16x16x32_bf16 v[12:15], v[150:153], v[214:217], v[12:15]
	v_mfma_f32_16x16x32_bf16 v[8:11], v[158:161], v[214:217], v[8:11]
	v_mfma_f32_16x16x32_bf16 v[52:55], v[162:165], v[178:181], v[52:55]
	v_mfma_f32_16x16x32_bf16 v[48:51], v[170:173], v[178:181], v[48:51]
	v_mfma_f32_16x16x32_bf16 v[36:39], v[162:165], v[186:189], v[36:39]
	v_mfma_f32_16x16x32_bf16 v[32:35], v[170:173], v[186:189], v[32:35]
	v_mfma_f32_16x16x32_bf16 v[20:23], v[162:165], v[194:197], v[20:23]
	v_mfma_f32_16x16x32_bf16 v[16:19], v[170:173], v[194:197], v[16:19]
	v_mfma_f32_16x16x32_bf16 v[4:7], v[162:165], v[210:213], v[4:7]
	v_mfma_f32_16x16x32_bf16 v[0:3], v[170:173], v[210:213], v[0:3]
	v_mfma_f32_16x16x32_bf16 v[52:55], v[166:169], v[182:185], v[52:55]
	v_mfma_f32_16x16x32_bf16 v[48:51], v[174:177], v[182:185], v[48:51]
	v_mfma_f32_16x16x32_bf16 v[36:39], v[166:169], v[190:193], v[36:39]
	v_mfma_f32_16x16x32_bf16 v[32:35], v[174:177], v[190:193], v[32:35]
	v_mfma_f32_16x16x32_bf16 v[20:23], v[166:169], v[198:201], v[20:23]
	v_mfma_f32_16x16x32_bf16 v[16:19], v[174:177], v[198:201], v[16:19]
	v_mfma_f32_16x16x32_bf16 v[4:7], v[166:169], v[214:217], v[4:7]
	v_mfma_f32_16x16x32_bf16 v[0:3], v[174:177], v[214:217], v[0:3]
	s_setprio 0
	s_barrier
	s_add_i32 s41, 0, 0x18000
	s_add_i32 s64, 0, 0x1c000
	v_add_u32_e32 v158, s41, v207
	v_add_u32_e32 v174, s64, v207
	ds_read_b128 v[146:149], v158
	ds_read_b128 v[150:153], v158 offset:1024
	ds_read_b128 v[154:157], v158 offset:2048
	ds_read_b128 v[158:161], v158 offset:3072
	ds_read_b128 v[162:165], v174
	ds_read_b128 v[166:169], v174 offset:1024
	ds_read_b128 v[170:173], v174 offset:2048
	ds_read_b128 v[174:177], v174 offset:3072
	s_add_u32 s46, s46, 0x40000
	s_addc_u32 s47, s47, 0
	s_mov_b32 m0, s57
	v_lshl_add_u64 v[224:225], s[46:47], 0, v[128:129]
	ds_read_b128 v[178:181], v209 offset:32768
	ds_read_b128 v[182:185], v209 offset:33792
	ds_read_b128 v[186:189], v209 offset:34816
	ds_read_b128 v[190:193], v209 offset:35840
	ds_read_b128 v[194:197], v209 offset:36864
	ds_read_b128 v[198:201], v209 offset:37888
	ds_read_b128 v[210:213], v209 offset:38912
	ds_read_b128 v[214:217], v209 offset:39936
	global_load_lds_dwordx4 v[224:225], off
	v_lshl_add_u64 v[224:225], s[46:47], 0, v[132:133]
	s_mov_b32 m0, s58
	s_nop 0
	global_load_lds_dwordx4 v[224:225], off
	s_waitcnt vmcnt(8)
	s_waitcnt lgkmcnt(0)
	s_barrier
	s_setprio 1
	v_mfma_f32_16x16x32_bf16 v[124:127], v[146:149], v[178:181], v[124:127]
	v_mfma_f32_16x16x32_bf16 v[120:123], v[154:157], v[178:181], v[120:123]
	v_mfma_f32_16x16x32_bf16 v[108:111], v[146:149], v[186:189], v[108:111]
	v_mfma_f32_16x16x32_bf16 v[104:107], v[154:157], v[186:189], v[104:107]
	v_mfma_f32_16x16x32_bf16 v[92:95], v[146:149], v[194:197], v[92:95]
	v_mfma_f32_16x16x32_bf16 v[88:91], v[154:157], v[194:197], v[88:91]
	v_mfma_f32_16x16x32_bf16 v[76:79], v[146:149], v[210:213], v[76:79]
	v_mfma_f32_16x16x32_bf16 v[72:75], v[154:157], v[210:213], v[72:75]
	v_mfma_f32_16x16x32_bf16 v[124:127], v[150:153], v[182:185], v[124:127]
	v_mfma_f32_16x16x32_bf16 v[120:123], v[158:161], v[182:185], v[120:123]
	v_mfma_f32_16x16x32_bf16 v[108:111], v[150:153], v[190:193], v[108:111]
	v_mfma_f32_16x16x32_bf16 v[104:107], v[158:161], v[190:193], v[104:107]
	v_mfma_f32_16x16x32_bf16 v[92:95], v[150:153], v[198:201], v[92:95]
	v_mfma_f32_16x16x32_bf16 v[88:91], v[158:161], v[198:201], v[88:91]
	v_mfma_f32_16x16x32_bf16 v[76:79], v[150:153], v[214:217], v[76:79]
	v_mfma_f32_16x16x32_bf16 v[72:75], v[158:161], v[214:217], v[72:75]
	v_mfma_f32_16x16x32_bf16 v[116:119], v[162:165], v[178:181], v[116:119]
	v_mfma_f32_16x16x32_bf16 v[112:115], v[170:173], v[178:181], v[112:115]
	v_mfma_f32_16x16x32_bf16 v[100:103], v[162:165], v[186:189], v[100:103]
	v_mfma_f32_16x16x32_bf16 v[96:99], v[170:173], v[186:189], v[96:99]
	v_mfma_f32_16x16x32_bf16 v[84:87], v[162:165], v[194:197], v[84:87]
	v_mfma_f32_16x16x32_bf16 v[80:83], v[170:173], v[194:197], v[80:83]
	v_mfma_f32_16x16x32_bf16 v[68:71], v[162:165], v[210:213], v[68:71]
	v_mfma_f32_16x16x32_bf16 v[64:67], v[170:173], v[210:213], v[64:67]
	v_mfma_f32_16x16x32_bf16 v[116:119], v[166:169], v[182:185], v[116:119]
	v_mfma_f32_16x16x32_bf16 v[112:115], v[174:177], v[182:185], v[112:115]
	v_mfma_f32_16x16x32_bf16 v[100:103], v[166:169], v[190:193], v[100:103]
	v_mfma_f32_16x16x32_bf16 v[96:99], v[174:177], v[190:193], v[96:99]
	v_mfma_f32_16x16x32_bf16 v[84:87], v[166:169], v[198:201], v[84:87]
	v_mfma_f32_16x16x32_bf16 v[80:83], v[174:177], v[198:201], v[80:83]
	v_mfma_f32_16x16x32_bf16 v[68:71], v[166:169], v[214:217], v[68:71]
	v_mfma_f32_16x16x32_bf16 v[64:67], v[174:177], v[214:217], v[64:67]
	s_setprio 0
	s_barrier
; #define PG8_STAGE(bufoff, gbase, voff) do { _Pragma("unroll") for (int _i = 0; _i < 2; ++_i) \
;         __builtin_amdgcn_global_load_lds((const unsigned*)((const char*)(gbase) + (voff)[_i]), (PG8_LAS unsigned*)(lds + (bufoff) + ldsw + _i * 8192), 16, 0, 0); } while (0)
; #define PG8_LDA(dst, b, h) do { _Pragma("unroll") for (int m = 0; m < 4; ++m) _Pragma("unroll") for (int k = 0; k < 2; ++k) dst[m][k] = *(const PG8_LAS bf16x8*)(lds + PG8_SA(b, h) + aoff + m * 2048 + k * 1024); } while (0)
; #define PG8_MMA(ai, bj, At, Bt) do { __builtin_amdgcn_s_setprio(1); _Pragma("unroll") for (int m = 0; m < 4; ++m) _Pragma("unroll") for (int n = 0; n < 2; ++n) _Pragma("unroll") for (int k = 0; k < 2; ++k) \
;         acc[ai][bj][m][n] = __builtin_amdgcn_mfma_f32_16x16x32_bf16(Bt[n][k], At[m][k], acc[ai][bj][m][n], 0, 0, 0); __builtin_amdgcn_s_setprio(0); } while (0)
; #define PG8_WAIT_V(n) asm volatile("s_waitcnt vmcnt(" #n ")" ::: "memory")
; #define PG8_WAIT_L(n) asm volatile("s_waitcnt lgkmcnt(" #n ")" ::: "memory")
; #define PG8_BAR __builtin_amdgcn_s_barrier()
; #define PG8_SCHED __builtin_amdgcn_sched_barrier(0)
; template <class Epi, class Sched, bool ALIGN_EPI = false, bool SP2 = false>
; __device__ __forceinline__ void gemm_phase(PG8_LAS unsigned char* lds, const Gemm g, const Sched& S, const Epi& E, const int wv0) {
;     ...
;         for (int t = 0; t < nt; t += 2) {
;             const bool last = (t == nt - 2);
;     ...
;             PG8_LDA(At, 1, 1); PG8_STAGE(PG8_SB(1, 0), b3, voffB); PG8_STAGE(PG8_SB(1, 1), b3 + hstepB, voffB); PG8_STAGE(PG8_SA(1, 0), a3, voffA);
;             PG8_WAIT_V(8); PG8_WAIT_L(0); PG8_BAR; PG8_MMA(1, 0, At, B0); PG8_MMA(1, 1, At, B1); PG8_BAR; PG8_SCHED;
	s_add_i32 s41, s41, s54
	v_lshl_add_u64 v[202:203], v[202:203], 0, s[10:11]
	s_mov_b32 m0, s41
	ds_read_b128 v[178:181], v209 offset:49152
	ds_read_b128 v[182:185], v209 offset:50176
	ds_read_b128 v[186:189], v209 offset:51200
	ds_read_b128 v[190:193], v209 offset:52224
	ds_read_b128 v[194:197], v209 offset:53248
	ds_read_b128 v[198:201], v209 offset:54272
	ds_read_b128 v[210:213], v209 offset:55296
	ds_read_b128 v[214:217], v209 offset:56320
	global_load_lds_dwordx4 v[202:203], off
	s_add_i32 m0, s41, 0x2000
	s_add_u32 s44, s44, 0x40080
	v_lshl_add_u64 v[202:203], v[218:219], 0, s[10:11]
	s_addc_u32 s45, s45, 0
	s_add_i32 s41, s64, s54
	global_load_lds_dwordx4 v[202:203], off
	v_lshl_add_u64 v[202:203], s[44:45], 0, v[130:131]
	s_mov_b32 m0, s41
	s_nop 0
	global_load_lds_dwordx4 v[202:203], off
	v_lshl_add_u64 v[202:203], s[44:45], 0, v[134:135]
	s_add_i32 m0, s41, 0x2000
	s_nop 0
	global_load_lds_dwordx4 v[202:203], off
	v_lshl_add_u64 v[202:203], v[220:221], 0, s[10:11]
	s_mov_b32 m0, s59
	s_nop 0
	global_load_lds_dwordx4 v[202:203], off
	v_lshl_add_u64 v[202:203], v[222:223], 0, s[10:11]
	s_mov_b32 m0, s60
	s_nop 0
	global_load_lds_dwordx4 v[202:203], off
	s_waitcnt vmcnt(8)
	s_waitcnt lgkmcnt(0)
	s_barrier
	s_setprio 1
	v_mfma_f32_16x16x32_bf16 v[60:63], v[146:149], v[178:181], v[60:63]
	v_mfma_f32_16x16x32_bf16 v[56:59], v[154:157], v[178:181], v[56:59]
	v_mfma_f32_16x16x32_bf16 v[44:47], v[146:149], v[186:189], v[44:47]
	v_mfma_f32_16x16x32_bf16 v[40:43], v[154:157], v[186:189], v[40:43]
	v_mfma_f32_16x16x32_bf16 v[28:31], v[146:149], v[194:197], v[28:31]
	v_mfma_f32_16x16x32_bf16 v[24:27], v[154:157], v[194:197], v[24:27]
	v_mfma_f32_16x16x32_bf16 v[12:15], v[146:149], v[210:213], v[12:15]
	v_mfma_f32_16x16x32_bf16 v[8:11], v[154:157], v[210:213], v[8:11]
	v_mfma_f32_16x16x32_bf16 v[60:63], v[150:153], v[182:185], v[60:63]
	v_mfma_f32_16x16x32_bf16 v[56:59], v[158:161], v[182:185], v[56:59]
	v_mfma_f32_16x16x32_bf16 v[44:47], v[150:153], v[190:193], v[44:47]
	v_mfma_f32_16x16x32_bf16 v[40:43], v[158:161], v[190:193], v[40:43]
	v_mfma_f32_16x16x32_bf16 v[28:31], v[150:153], v[198:201], v[28:31]
	v_mfma_f32_16x16x32_bf16 v[24:27], v[158:161], v[198:201], v[24:27]
	v_mfma_f32_16x16x32_bf16 v[12:15], v[150:153], v[214:217], v[12:15]
	v_mfma_f32_16x16x32_bf16 v[8:11], v[158:161], v[214:217], v[8:11]
	v_mfma_f32_16x16x32_bf16 v[52:55], v[162:165], v[178:181], v[52:55]
	v_mfma_f32_16x16x32_bf16 v[48:51], v[170:173], v[178:181], v[48:51]
	v_mfma_f32_16x16x32_bf16 v[36:39], v[162:165], v[186:189], v[36:39]
	v_mfma_f32_16x16x32_bf16 v[32:35], v[170:173], v[186:189], v[32:35]
	v_mfma_f32_16x16x32_bf16 v[20:23], v[162:165], v[194:197], v[20:23]
	v_mfma_f32_16x16x32_bf16 v[16:19], v[170:173], v[194:197], v[16:19]
	v_mfma_f32_16x16x32_bf16 v[4:7], v[162:165], v[210:213], v[4:7]
	v_mfma_f32_16x16x32_bf16 v[0:3], v[170:173], v[210:213], v[0:3]
	v_mfma_f32_16x16x32_bf16 v[52:55], v[166:169], v[182:185], v[52:55]
	v_mfma_f32_16x16x32_bf16 v[48:51], v[174:177], v[182:185], v[48:51]
	v_mfma_f32_16x16x32_bf16 v[36:39], v[166:169], v[190:193], v[36:39]
	v_mfma_f32_16x16x32_bf16 v[32:35], v[174:177], v[190:193], v[32:35]
	v_mfma_f32_16x16x32_bf16 v[20:23], v[166:169], v[198:201], v[20:23]
	v_mfma_f32_16x16x32_bf16 v[16:19], v[174:177], v[198:201], v[16:19]
	v_mfma_f32_16x16x32_bf16 v[4:7], v[166:169], v[214:217], v[4:7]
	v_mfma_f32_16x16x32_bf16 v[0:3], v[174:177], v[214:217], v[0:3]
	s_setprio 0
	s_add_i32 s29, s29, 2
	s_add_u32 s25, s25, 0x100
	s_addc_u32 s27, s27, 0
	s_add_u32 s38, s38, 0x100
	s_addc_u32 s39, s39, 0
	s_cmp_gt_u32 s29, 13
	s_barrier
	s_cbranch_scc0 .LBB0_494
	s_and_b64 vcc, exec, s[12:13]
	s_cbranch_vccz .LBB0_497
	s_barrier

; #define PG8_STAGE(bufoff, gbase, voff) do { _Pragma("unroll") for (int _i = 0; _i < 2; ++_i) \
;         __builtin_amdgcn_global_load_lds((const unsigned*)((const char*)(gbase) + (voff)[_i]), (PG8_LAS unsigned*)(lds + (bufoff) + ldsw + _i * 8192), 16, 0, 0); } while (0)
; #define PG8_LDA(dst, b, h) do { _Pragma("unroll") for (int m = 0; m < 4; ++m) _Pragma("unroll") for (int k = 0; k < 2; ++k) dst[m][k] = *(const PG8_LAS bf16x8*)(lds + PG8_SA(b, h) + aoff + m * 2048 + k * 1024); } while (0)
; #define PG8_LDB(dst, b, h) do { _Pragma("unroll") for (int n = 0; n < 2; ++n) _Pragma("unroll") for (int k = 0; k < 2; ++k) dst[n][k] = *(const PG8_LAS bf16x8*)(lds + PG8_SB(b, h) + boff + n * 2048 + k * 1024); } while (0)
; template <class Epi, class Sched, bool ALIGN_EPI = false, bool SP2 = false>
; __device__ __forceinline__ void gemm_phase(PG8_LAS unsigned char* lds, const Gemm g, const Sched& S, const Epi& E, const int wv0) {
;     ...
;         for (int t = 0; t < nt; t += 2) {
;             const bool last = (t == nt - 2);
;             const char* a1 = cA + (size_t)(t + 1) * kstep;
;             const char* a2 = last ? nA : cA + (size_t)(t + 2) * kstep; const char* b2 = last ? nB : cB + (size_t)(t + 2) * kstep;
;             const char* a3 = a2 + kstep; const char* b3 = b2 + kstep;
;             if constexpr (SP2) {
;             PG8_LDB(B0, 0, 0); PG8_LDB(B1, 0, 1); PG8_SCHED; PG8_LDA(At, 0, 0); PG8_STAGE(PG8_SA(1, 1), a1 + hstepA, voffA);
;             PG8_WAIT_V(8); PG8_WAIT_L(0); PG8_BAR; PG8_MMA(0, 0, At, B0); PG8_MMA(0, 1, At, B1); PG8_BAR; PG8_SCHED;
;             PG8_LDA(At, 0, 1); PG8_STAGE(PG8_SB(0, 0), b2, voffB); PG8_STAGE(PG8_SB(0, 1), b2 + hstepB, voffB); PG8_STAGE(PG8_SA(0, 0), a2, voffA);
;             PG8_WAIT_V(8); PG8_WAIT_L(0); PG8_BAR; PG8_MMA(1, 0, At, B0); PG8_MMA(1, 1, At, B1); PG8_BAR; PG8_SCHED;
;             PG8_LDB(B0, 1, 0); PG8_LDB(B1, 1, 1); PG8_SCHED; PG8_LDA(At, 1, 0); PG8_STAGE(PG8_SA(0, 1), a2 + hstepA, voffA);
;             PG8_WAIT_V(8); PG8_WAIT_L(0); PG8_BAR; PG8_MMA(0, 0, At, B0); PG8_MMA(0, 1, At, B1); PG8_BAR; PG8_SCHED;
;             PG8_LDA(At, 1, 1); PG8_STAGE(PG8_SB(1, 0), b3, voffB); PG8_STAGE(PG8_SB(1, 1), b3 + hstepB, voffB); PG8_STAGE(PG8_SA(1, 0), a3, voffA);
;             PG8_WAIT_V(8); PG8_WAIT_L(0); PG8_BAR; PG8_MMA(1, 0, At, B0); PG8_MMA(1, 1, At, B1); PG8_BAR; PG8_SCHED;
.LBB0_667:
	ds_read_b128 v[144:147], v153
	ds_read_b128 v[156:159], v153 offset:1024
	ds_read_b128 v[160:163], v153 offset:2048
	ds_read_b128 v[164:167], v153 offset:3072
	ds_read_b128 v[168:171], v154
	ds_read_b128 v[172:175], v154 offset:1024
	ds_read_b128 v[176:179], v154 offset:2048
	ds_read_b128 v[180:183], v154 offset:3072
	s_add_u32 s24, s22, 0xfff80080
	s_addc_u32 s25, s23, -1
	s_cmp_eq_u32 s50, 28
	s_cselect_b32 s27, s17, s25
	s_cselect_b32 s26, s16, s24
	s_cselect_b32 s25, s19, s15
	s_cselect_b32 s24, s18, s13
	v_lshl_add_u64 v[148:149], s[22:23], 0, v[138:139]
	s_add_i32 m0, s21, 0xc000
	ds_read_b128 v[184:187], v155
	ds_read_b128 v[188:191], v155 offset:1024
	ds_read_b128 v[192:195], v155 offset:2048
	ds_read_b128 v[196:199], v155 offset:3072
	ds_read_b128 v[200:203], v155 offset:4096
	ds_read_b128 v[206:209], v155 offset:5120
	ds_read_b128 v[210:213], v155 offset:6144
	ds_read_b128 v[214:217], v155 offset:7168
	global_load_lds_dwordx4 v[148:149], off
	v_lshl_add_u64 v[148:149], s[22:23], 0, v[136:137]
	s_add_i32 m0, s21, 0xe000
	s_nop 0
	global_load_lds_dwordx4 v[148:149], off
	s_waitcnt vmcnt(8)
	s_waitcnt lgkmcnt(0)
	s_barrier
	s_setprio 1
	v_mfma_f32_16x16x32_bf16 v[124:127], v[144:147], v[184:187], v[124:127]
	v_mfma_f32_16x16x32_bf16 v[120:123], v[160:163], v[184:187], v[120:123]
	v_mfma_f32_16x16x32_bf16 v[116:119], v[144:147], v[192:195], v[116:119]
	v_mfma_f32_16x16x32_bf16 v[112:115], v[160:163], v[192:195], v[112:115]
	v_mfma_f32_16x16x32_bf16 v[92:95], v[144:147], v[200:203], v[92:95]
	v_mfma_f32_16x16x32_bf16 v[88:91], v[160:163], v[200:203], v[88:91]
	v_mfma_f32_16x16x32_bf16 v[84:87], v[144:147], v[210:213], v[84:87]
	v_mfma_f32_16x16x32_bf16 v[80:83], v[160:163], v[210:213], v[80:83]
	v_mfma_f32_16x16x32_bf16 v[124:127], v[156:159], v[188:191], v[124:127]
	v_mfma_f32_16x16x32_bf16 v[120:123], v[164:167], v[188:191], v[120:123]
	v_mfma_f32_16x16x32_bf16 v[116:119], v[156:159], v[196:199], v[116:119]
	v_mfma_f32_16x16x32_bf16 v[112:115], v[164:167], v[196:199], v[112:115]
	v_mfma_f32_16x16x32_bf16 v[92:95], v[156:159], v[206:209], v[92:95]
	v_mfma_f32_16x16x32_bf16 v[88:91], v[164:167], v[206:209], v[88:91]
	v_mfma_f32_16x16x32_bf16 v[84:87], v[156:159], v[214:217], v[84:87]
	v_mfma_f32_16x16x32_bf16 v[80:83], v[164:167], v[214:217], v[80:83]
	v_mfma_f32_16x16x32_bf16 v[108:111], v[168:171], v[184:187], v[108:111]
	v_mfma_f32_16x16x32_bf16 v[104:107], v[176:179], v[184:187], v[104:107]
	v_mfma_f32_16x16x32_bf16 v[100:103], v[168:171], v[192:195], v[100:103]
	v_mfma_f32_16x16x32_bf16 v[96:99], v[176:179], v[192:195], v[96:99]
	v_mfma_f32_16x16x32_bf16 v[76:79], v[168:171], v[200:203], v[76:79]
	v_mfma_f32_16x16x32_bf16 v[72:75], v[176:179], v[200:203], v[72:75]
	v_mfma_f32_16x16x32_bf16 v[68:71], v[168:171], v[210:213], v[68:71]
	v_mfma_f32_16x16x32_bf16 v[64:67], v[176:179], v[210:213], v[64:67]
	v_mfma_f32_16x16x32_bf16 v[108:111], v[172:175], v[188:191], v[108:111]
	v_mfma_f32_16x16x32_bf16 v[104:107], v[180:183], v[188:191], v[104:107]
	v_mfma_f32_16x16x32_bf16 v[100:103], v[172:175], v[196:199], v[100:103]
	v_mfma_f32_16x16x32_bf16 v[96:99], v[180:183], v[196:199], v[96:99]
	v_mfma_f32_16x16x32_bf16 v[76:79], v[172:175], v[206:209], v[76:79]
	v_mfma_f32_16x16x32_bf16 v[72:75], v[180:183], v[206:209], v[72:75]
	v_mfma_f32_16x16x32_bf16 v[68:71], v[172:175], v[214:217], v[68:71]
	v_mfma_f32_16x16x32_bf16 v[64:67], v[180:183], v[214:217], v[64:67]
	s_setprio 0
	s_barrier
	s_add_i32 s51, s47, s37
	v_lshl_add_u64 v[148:149], s[24:25], 0, v[130:131]
	s_mov_b32 m0, s51
	ds_read_b128 v[184:187], v155 offset:16384
	ds_read_b128 v[188:191], v155 offset:17408
	ds_read_b128 v[192:195], v155 offset:18432
	ds_read_b128 v[196:199], v155 offset:19456
	ds_read_b128 v[200:203], v155 offset:20480
	ds_read_b128 v[206:209], v155 offset:21504
	ds_read_b128 v[210:213], v155 offset:22528
	ds_read_b128 v[214:217], v155 offset:23552
	global_load_lds_dwordx4 v[148:149], off
	s_add_i32 m0, s51, 0x2000
	s_add_u32 s52, s24, 0x80000
	v_lshl_add_u64 v[218:219], s[24:25], 0, v[134:135]
	s_addc_u32 s53, s25, 0
	s_add_i32 s51, s48, s37
	global_load_lds_dwordx4 v[218:219], off
	v_lshl_add_u64 v[220:221], s[52:53], 0, v[130:131]
	s_mov_b32 m0, s51
	v_lshl_add_u64 v[222:223], s[26:27], 0, v[132:133]
	global_load_lds_dwordx4 v[220:221], off
	v_lshl_add_u64 v[220:221], s[52:53], 0, v[134:135]
	s_add_i32 m0, s51, 0x2000
	s_nop 0
	global_load_lds_dwordx4 v[220:221], off
	v_lshl_add_u64 v[220:221], s[26:27], 0, v[128:129]
	s_mov_b32 m0, s21
	s_nop 0
	global_load_lds_dwordx4 v[220:221], off
	s_mov_b32 m0, s38
	s_nop 0
	global_load_lds_dwordx4 v[222:223], off
	s_waitcnt vmcnt(8)
	s_waitcnt lgkmcnt(0)
	s_barrier
; #define PG8_STAGE(bufoff, gbase, voff) do { _Pragma("unroll") for (int _i = 0; _i < 2; ++_i) \
;         __builtin_amdgcn_global_load_lds((const unsigned*)((const char*)(gbase) + (voff)[_i]), (PG8_LAS unsigned*)(lds + (bufoff) + ldsw + _i * 8192), 16, 0, 0); } while (0)
; #define PG8_LDA(dst, b, h) do { _Pragma("unroll") for (int m = 0; m < 4; ++m) _Pragma("unroll") for (int k = 0; k < 2; ++k) dst[m][k] = *(const PG8_LAS bf16x8*)(lds + PG8_SA(b, h) + aoff + m * 2048 + k * 1024); } while (0)
; #define PG8_LDB(dst, b, h) do { _Pragma("unroll") for (int n = 0; n < 2; ++n) _Pragma("unroll") for (int k = 0; k < 2; ++k) dst[n][k] = *(const PG8_LAS bf16x8*)(lds + PG8_SB(b, h) + boff + n * 2048 + k * 1024); } while (0)
; #define PG8_MMA(ai, bj, At, Bt) do { __builtin_amdgcn_s_setprio(1); _Pragma("unroll") for (int m = 0; m < 4; ++m) _Pragma("unroll") for (int n = 0; n < 2; ++n) _Pragma("unroll") for (int k = 0; k < 2; ++k) \
;         acc[ai][bj][m][n] = __builtin_amdgcn_mfma_f32_16x16x32_bf16(Bt[n][k], At[m][k], acc[ai][bj][m][n], 0, 0, 0); __builtin_amdgcn_s_setprio(0); } while (0)
; #define PG8_WAIT_V(n) asm volatile("s_waitcnt vmcnt(" #n ")" ::: "memory")
; #define PG8_WAIT_L(n) asm volatile("s_waitcnt lgkmcnt(" #n ")" ::: "memory")
; #define PG8_BAR __builtin_amdgcn_s_barrier()
; #define PG8_SCHED __builtin_amdgcn_sched_barrier(0)
; template <class Epi, class Sched, bool ALIGN_EPI = false, bool SP2 = false>
; __device__ __forceinline__ void gemm_phase(PG8_LAS unsigned char* lds, const Gemm g, const Sched& S, const Epi& E, const int wv0) {
;     ...
;             PG8_WAIT_V(8); PG8_WAIT_L(0); PG8_BAR; PG8_MMA(1, 0, At, B0); PG8_MMA(1, 1, At, B1); PG8_BAR; PG8_SCHED;
;             PG8_LDB(B0, 1, 0); PG8_LDB(B1, 1, 1); PG8_SCHED; PG8_LDA(At, 1, 0); PG8_STAGE(PG8_SA(0, 1), a2 + hstepA, voffA);
;             PG8_WAIT_V(8); PG8_WAIT_L(0); PG8_BAR; PG8_MMA(0, 0, At, B0); PG8_MMA(0, 1, At, B1); PG8_BAR; PG8_SCHED;
	s_setprio 1
	v_mfma_f32_16x16x32_bf16 v[60:63], v[144:147], v[184:187], v[60:63]
	v_mfma_f32_16x16x32_bf16 v[56:59], v[160:163], v[184:187], v[56:59]
	v_mfma_f32_16x16x32_bf16 v[52:55], v[144:147], v[192:195], v[52:55]
	v_mfma_f32_16x16x32_bf16 v[48:51], v[160:163], v[192:195], v[48:51]
	v_mfma_f32_16x16x32_bf16 v[28:31], v[144:147], v[200:203], v[28:31]
	v_mfma_f32_16x16x32_bf16 v[24:27], v[160:163], v[200:203], v[24:27]
	v_mfma_f32_16x16x32_bf16 v[20:23], v[144:147], v[210:213], v[20:23]
	v_mfma_f32_16x16x32_bf16 v[16:19], v[160:163], v[210:213], v[16:19]
	v_mfma_f32_16x16x32_bf16 v[60:63], v[156:159], v[188:191], v[60:63]
	v_mfma_f32_16x16x32_bf16 v[56:59], v[164:167], v[188:191], v[56:59]
	v_mfma_f32_16x16x32_bf16 v[52:55], v[156:159], v[196:199], v[52:55]
	v_mfma_f32_16x16x32_bf16 v[48:51], v[164:167], v[196:199], v[48:51]
	v_mfma_f32_16x16x32_bf16 v[28:31], v[156:159], v[206:209], v[28:31]
	v_mfma_f32_16x16x32_bf16 v[24:27], v[164:167], v[206:209], v[24:27]
	v_mfma_f32_16x16x32_bf16 v[20:23], v[156:159], v[214:217], v[20:23]
	v_mfma_f32_16x16x32_bf16 v[16:19], v[164:167], v[214:217], v[16:19]
	v_mfma_f32_16x16x32_bf16 v[44:47], v[168:171], v[184:187], v[44:47]
	v_mfma_f32_16x16x32_bf16 v[40:43], v[176:179], v[184:187], v[40:43]
	v_mfma_f32_16x16x32_bf16 v[36:39], v[168:171], v[192:195], v[36:39]
	v_mfma_f32_16x16x32_bf16 v[32:35], v[176:179], v[192:195], v[32:35]
	v_mfma_f32_16x16x32_bf16 v[12:15], v[168:171], v[200:203], v[12:15]
	v_mfma_f32_16x16x32_bf16 v[8:11], v[176:179], v[200:203], v[8:11]
	v_mfma_f32_16x16x32_bf16 v[4:7], v[168:171], v[210:213], v[4:7]
	v_mfma_f32_16x16x32_bf16 v[0:3], v[176:179], v[210:213], v[0:3]
	v_mfma_f32_16x16x32_bf16 v[44:47], v[172:175], v[188:191], v[44:47]
	v_mfma_f32_16x16x32_bf16 v[40:43], v[180:183], v[188:191], v[40:43]
	v_mfma_f32_16x16x32_bf16 v[36:39], v[172:175], v[196:199], v[36:39]
	v_mfma_f32_16x16x32_bf16 v[32:35], v[180:183], v[196:199], v[32:35]
	v_mfma_f32_16x16x32_bf16 v[12:15], v[172:175], v[206:209], v[12:15]
	v_mfma_f32_16x16x32_bf16 v[8:11], v[180:183], v[206:209], v[8:11]
	v_mfma_f32_16x16x32_bf16 v[4:7], v[172:175], v[214:217], v[4:7]
	v_mfma_f32_16x16x32_bf16 v[0:3], v[180:183], v[214:217], v[0:3]
	s_setprio 0
	s_barrier
	s_add_i32 s51, 0, 0x18000
	s_add_i32 s52, 0, 0x1c000
	v_add_u32_e32 v164, s51, v151
	v_add_u32_e32 v180, s52, v151
	ds_read_b128 v[144:147], v164
	ds_read_b128 v[156:159], v164 offset:1024
	ds_read_b128 v[160:163], v164 offset:2048
	ds_read_b128 v[164:167], v164 offset:3072
	ds_read_b128 v[168:171], v180
	ds_read_b128 v[172:175], v180 offset:1024
	ds_read_b128 v[176:179], v180 offset:2048
	ds_read_b128 v[180:183], v180 offset:3072
	s_add_u32 s26, s26, 0x80000
	s_addc_u32 s27, s27, 0
	s_mov_b32 m0, s39
	v_lshl_add_u64 v[224:225], s[26:27], 0, v[128:129]
	ds_read_b128 v[184:187], v155 offset:32768
	ds_read_b128 v[188:191], v155 offset:33792
	ds_read_b128 v[192:195], v155 offset:34816
	ds_read_b128 v[196:199], v155 offset:35840
	ds_read_b128 v[200:203], v155 offset:36864
	ds_read_b128 v[206:209], v155 offset:37888
	ds_read_b128 v[210:213], v155 offset:38912
	ds_read_b128 v[214:217], v155 offset:39936
	global_load_lds_dwordx4 v[224:225], off
	v_lshl_add_u64 v[224:225], s[26:27], 0, v[132:133]
	s_mov_b32 m0, s40
	s_nop 0
	global_load_lds_dwordx4 v[224:225], off
	s_waitcnt vmcnt(8)
	s_waitcnt lgkmcnt(0)
	s_barrier
	s_setprio 1
	v_mfma_f32_16x16x32_bf16 v[124:127], v[144:147], v[184:187], v[124:127]
	v_mfma_f32_16x16x32_bf16 v[120:123], v[160:163], v[184:187], v[120:123]
	v_mfma_f32_16x16x32_bf16 v[116:119], v[144:147], v[192:195], v[116:119]
	v_mfma_f32_16x16x32_bf16 v[112:115], v[160:163], v[192:195], v[112:115]
	v_mfma_f32_16x16x32_bf16 v[92:95], v[144:147], v[200:203], v[92:95]
	v_mfma_f32_16x16x32_bf16 v[88:91], v[160:163], v[200:203], v[88:91]
	v_mfma_f32_16x16x32_bf16 v[84:87], v[144:147], v[210:213], v[84:87]
	v_mfma_f32_16x16x32_bf16 v[80:83], v[160:163], v[210:213], v[80:83]
	v_mfma_f32_16x16x32_bf16 v[124:127], v[156:159], v[188:191], v[124:127]
	v_mfma_f32_16x16x32_bf16 v[120:123], v[164:167], v[188:191], v[120:123]
	v_mfma_f32_16x16x32_bf16 v[116:119], v[156:159], v[196:199], v[116:119]
	v_mfma_f32_16x16x32_bf16 v[112:115], v[164:167], v[196:199], v[112:115]
	v_mfma_f32_16x16x32_bf16 v[92:95], v[156:159], v[206:209], v[92:95]
	v_mfma_f32_16x16x32_bf16 v[88:91], v[164:167], v[206:209], v[88:91]
	v_mfma_f32_16x16x32_bf16 v[84:87], v[156:159], v[214:217], v[84:87]
	v_mfma_f32_16x16x32_bf16 v[80:83], v[164:167], v[214:217], v[80:83]
	v_mfma_f32_16x16x32_bf16 v[108:111], v[168:171], v[184:187], v[108:111]
	v_mfma_f32_16x16x32_bf16 v[104:107], v[176:179], v[184:187], v[104:107]
	v_mfma_f32_16x16x32_bf16 v[100:103], v[168:171], v[192:195], v[100:103]
	v_mfma_f32_16x16x32_bf16 v[96:99], v[176:179], v[192:195], v[96:99]
	v_mfma_f32_16x16x32_bf16 v[76:79], v[168:171], v[200:203], v[76:79]
	v_mfma_f32_16x16x32_bf16 v[72:75], v[176:179], v[200:203], v[72:75]
	v_mfma_f32_16x16x32_bf16 v[68:71], v[168:171], v[210:213], v[68:71]
	v_mfma_f32_16x16x32_bf16 v[64:67], v[176:179], v[210:213], v[64:67]
	v_mfma_f32_16x16x32_bf16 v[108:111], v[172:175], v[188:191], v[108:111]
	v_mfma_f32_16x16x32_bf16 v[104:107], v[180:183], v[188:191], v[104:107]
	v_mfma_f32_16x16x32_bf16 v[100:103], v[172:175], v[196:199], v[100:103]
	v_mfma_f32_16x16x32_bf16 v[96:99], v[180:183], v[196:199], v[96:99]
	v_mfma_f32_16x16x32_bf16 v[76:79], v[172:175], v[206:209], v[76:79]
	v_mfma_f32_16x16x32_bf16 v[72:75], v[180:183], v[206:209], v[72:75]
	v_mfma_f32_16x16x32_bf16 v[68:71], v[172:175], v[214:217], v[68:71]
	v_mfma_f32_16x16x32_bf16 v[64:67], v[180:183], v[214:217], v[64:67]
	s_setprio 0
	s_barrier
; #define PG8_STAGE(bufoff, gbase, voff) do { _Pragma("unroll") for (int _i = 0; _i < 2; ++_i) \
;         __builtin_amdgcn_global_load_lds((const unsigned*)((const char*)(gbase) + (voff)[_i]), (PG8_LAS unsigned*)(lds + (bufoff) + ldsw + _i * 8192), 16, 0, 0); } while (0)
; #define PG8_LDA(dst, b, h) do { _Pragma("unroll") for (int m = 0; m < 4; ++m) _Pragma("unroll") for (int k = 0; k < 2; ++k) dst[m][k] = *(const PG8_LAS bf16x8*)(lds + PG8_SA(b, h) + aoff + m * 2048 + k * 1024); } while (0)
; #define PG8_MMA(ai, bj, At, Bt) do { __builtin_amdgcn_s_setprio(1); _Pragma("unroll") for (int m = 0; m < 4; ++m) _Pragma("unroll") for (int n = 0; n < 2; ++n) _Pragma("unroll") for (int k = 0; k < 2; ++k) \
;         acc[ai][bj][m][n] = __builtin_amdgcn_mfma_f32_16x16x32_bf16(Bt[n][k], At[m][k], acc[ai][bj][m][n], 0, 0, 0); __builtin_amdgcn_s_setprio(0); } while (0)
; #define PG8_WAIT_V(n) asm volatile("s_waitcnt vmcnt(" #n ")" ::: "memory")
; #define PG8_WAIT_L(n) asm volatile("s_waitcnt lgkmcnt(" #n ")" ::: "memory")
; #define PG8_BAR __builtin_amdgcn_s_barrier()
; #define PG8_SCHED __builtin_amdgcn_sched_barrier(0)
; template <class Epi, class Sched, bool ALIGN_EPI = false, bool SP2 = false>
; __device__ __forceinline__ void gemm_phase(PG8_LAS unsigned char* lds, const Gemm g, const Sched& S, const Epi& E, const int wv0) {
;     ...
;         for (int t = 0; t < nt; t += 2) {
;             const bool last = (t == nt - 2);
;     ...
;             PG8_LDA(At, 1, 1); PG8_STAGE(PG8_SB(1, 0), b3, voffB); PG8_STAGE(PG8_SB(1, 1), b3 + hstepB, voffB); PG8_STAGE(PG8_SA(1, 0), a3, voffA);
;             PG8_WAIT_V(8); PG8_WAIT_L(0); PG8_BAR; PG8_MMA(1, 0, At, B0); PG8_MMA(1, 1, At, B1); PG8_BAR; PG8_SCHED;
	s_add_i32 s26, s51, s37
	v_lshl_add_u64 v[148:149], v[148:149], 0, s[8:9]
	s_mov_b32 m0, s26
	ds_read_b128 v[184:187], v155 offset:49152
	ds_read_b128 v[188:191], v155 offset:50176
	ds_read_b128 v[192:195], v155 offset:51200
	ds_read_b128 v[196:199], v155 offset:52224
	ds_read_b128 v[200:203], v155 offset:53248
	ds_read_b128 v[206:209], v155 offset:54272
	ds_read_b128 v[210:213], v155 offset:55296
	ds_read_b128 v[214:217], v155 offset:56320
	global_load_lds_dwordx4 v[148:149], off
	s_add_i32 m0, s26, 0x2000
	s_add_u32 s24, s24, 0x80080
	v_lshl_add_u64 v[148:149], v[218:219], 0, s[8:9]
	s_addc_u32 s25, s25, 0
	s_add_i32 s26, s52, s37
	global_load_lds_dwordx4 v[148:149], off
	v_lshl_add_u64 v[148:149], s[24:25], 0, v[130:131]
	s_mov_b32 m0, s26
	s_nop 0
	global_load_lds_dwordx4 v[148:149], off
	v_lshl_add_u64 v[148:149], s[24:25], 0, v[134:135]
	s_add_i32 m0, s26, 0x2000
	s_nop 0
	global_load_lds_dwordx4 v[148:149], off
	v_lshl_add_u64 v[148:149], v[220:221], 0, s[8:9]
	s_mov_b32 m0, s44
	s_nop 0
	global_load_lds_dwordx4 v[148:149], off
	v_lshl_add_u64 v[148:149], v[222:223], 0, s[8:9]
	s_mov_b32 m0, s45
	s_nop 0
	global_load_lds_dwordx4 v[148:149], off
	s_waitcnt vmcnt(8)
	s_waitcnt lgkmcnt(0)
	s_barrier
	s_setprio 1
	v_mfma_f32_16x16x32_bf16 v[60:63], v[144:147], v[184:187], v[60:63]
	v_mfma_f32_16x16x32_bf16 v[56:59], v[160:163], v[184:187], v[56:59]
	v_mfma_f32_16x16x32_bf16 v[52:55], v[144:147], v[192:195], v[52:55]
	v_mfma_f32_16x16x32_bf16 v[48:51], v[160:163], v[192:195], v[48:51]
	v_mfma_f32_16x16x32_bf16 v[28:31], v[144:147], v[200:203], v[28:31]
	v_mfma_f32_16x16x32_bf16 v[24:27], v[160:163], v[200:203], v[24:27]
	v_mfma_f32_16x16x32_bf16 v[20:23], v[144:147], v[210:213], v[20:23]
	v_mfma_f32_16x16x32_bf16 v[16:19], v[160:163], v[210:213], v[16:19]
	v_mfma_f32_16x16x32_bf16 v[60:63], v[156:159], v[188:191], v[60:63]
	v_mfma_f32_16x16x32_bf16 v[56:59], v[164:167], v[188:191], v[56:59]
	v_mfma_f32_16x16x32_bf16 v[52:55], v[156:159], v[196:199], v[52:55]
	v_mfma_f32_16x16x32_bf16 v[48:51], v[164:167], v[196:199], v[48:51]
	v_mfma_f32_16x16x32_bf16 v[28:31], v[156:159], v[206:209], v[28:31]
	v_mfma_f32_16x16x32_bf16 v[24:27], v[164:167], v[206:209], v[24:27]
	v_mfma_f32_16x16x32_bf16 v[20:23], v[156:159], v[214:217], v[20:23]
	v_mfma_f32_16x16x32_bf16 v[16:19], v[164:167], v[214:217], v[16:19]
	v_mfma_f32_16x16x32_bf16 v[44:47], v[168:171], v[184:187], v[44:47]
	v_mfma_f32_16x16x32_bf16 v[40:43], v[176:179], v[184:187], v[40:43]
	v_mfma_f32_16x16x32_bf16 v[36:39], v[168:171], v[192:195], v[36:39]
	v_mfma_f32_16x16x32_bf16 v[32:35], v[176:179], v[192:195], v[32:35]
	v_mfma_f32_16x16x32_bf16 v[12:15], v[168:171], v[200:203], v[12:15]
	v_mfma_f32_16x16x32_bf16 v[8:11], v[176:179], v[200:203], v[8:11]
	v_mfma_f32_16x16x32_bf16 v[4:7], v[168:171], v[210:213], v[4:7]
	v_mfma_f32_16x16x32_bf16 v[0:3], v[176:179], v[210:213], v[0:3]
	v_mfma_f32_16x16x32_bf16 v[44:47], v[172:175], v[188:191], v[44:47]
	v_mfma_f32_16x16x32_bf16 v[40:43], v[180:183], v[188:191], v[40:43]
	v_mfma_f32_16x16x32_bf16 v[36:39], v[172:175], v[196:199], v[36:39]
	v_mfma_f32_16x16x32_bf16 v[32:35], v[180:183], v[196:199], v[32:35]
	v_mfma_f32_16x16x32_bf16 v[12:15], v[172:175], v[206:209], v[12:15]
	v_mfma_f32_16x16x32_bf16 v[8:11], v[180:183], v[206:209], v[8:11]
	v_mfma_f32_16x16x32_bf16 v[4:7], v[172:175], v[214:217], v[4:7]
	v_mfma_f32_16x16x32_bf16 v[0:3], v[180:183], v[214:217], v[0:3]
	s_setprio 0
	s_add_i32 s50, s50, 2
	s_add_u32 s13, s13, 0x100
	s_addc_u32 s15, s15, 0
	s_add_u32 s22, s22, 0x100
	s_addc_u32 s23, s23, 0
	s_cmp_gt_u32 s50, 29
	s_barrier
	s_cbranch_scc0 .LBB0_667
	s_and_b64 vcc, exec, s[10:11]
	s_cbranch_vccz .LBB0_670
	s_barrier

; #define PG8_STAGE(bufoff, gbase, voff) do { _Pragma("unroll") for (int _i = 0; _i < 2; ++_i) \
;         __builtin_amdgcn_global_load_lds((const unsigned*)((const char*)(gbase) + (voff)[_i]), (PG8_LAS unsigned*)(lds + (bufoff) + ldsw + _i * 8192), 16, 0, 0); } while (0)
; #define PG8_LDA(dst, b, h) do { _Pragma("unroll") for (int m = 0; m < 4; ++m) _Pragma("unroll") for (int k = 0; k < 2; ++k) dst[m][k] = *(const PG8_LAS bf16x8*)(lds + PG8_SA(b, h) + aoff + m * 2048 + k * 1024); } while (0)
; #define PG8_LDB(dst, b, h) do { _Pragma("unroll") for (int n = 0; n < 2; ++n) _Pragma("unroll") for (int k = 0; k < 2; ++k) dst[n][k] = *(const PG8_LAS bf16x8*)(lds + PG8_SB(b, h) + boff + n * 2048 + k * 1024); } while (0)
; template <class Epi, class Sched, bool ALIGN_EPI = false, bool SP2 = false>
; __device__ __forceinline__ void gemm_phase(PG8_LAS unsigned char* lds, const Gemm g, const Sched& S, const Epi& E, const int wv0) {
;     ...
;         for (int t = 0; t < nt; t += 2) {
;             const bool last = (t == nt - 2);
;             const char* a1 = cA + (size_t)(t + 1) * kstep;
;             const char* a2 = last ? nA : cA + (size_t)(t + 2) * kstep; const char* b2 = last ? nB : cB + (size_t)(t + 2) * kstep;
;             const char* a3 = a2 + kstep; const char* b3 = b2 + kstep;
;             if constexpr (SP2) {
;             PG8_LDB(B0, 0, 0); PG8_LDB(B1, 0, 1); PG8_SCHED; PG8_LDA(At, 0, 0); PG8_STAGE(PG8_SA(1, 1), a1 + hstepA, voffA);
;             PG8_WAIT_V(8); PG8_WAIT_L(0); PG8_BAR; PG8_MMA(0, 0, At, B0); PG8_MMA(0, 1, At, B1); PG8_BAR; PG8_SCHED;
;             PG8_LDA(At, 0, 1); PG8_STAGE(PG8_SB(0, 0), b2, voffB); PG8_STAGE(PG8_SB(0, 1), b2 + hstepB, voffB); PG8_STAGE(PG8_SA(0, 0), a2, voffA);
;             PG8_WAIT_V(8); PG8_WAIT_L(0); PG8_BAR; PG8_MMA(1, 0, At, B0); PG8_MMA(1, 1, At, B1); PG8_BAR; PG8_SCHED;
;             PG8_LDB(B0, 1, 0); PG8_LDB(B1, 1, 1); PG8_SCHED; PG8_LDA(At, 1, 0); PG8_STAGE(PG8_SA(0, 1), a2 + hstepA, voffA);
;             PG8_WAIT_V(8); PG8_WAIT_L(0); PG8_BAR; PG8_MMA(0, 0, At, B0); PG8_MMA(0, 1, At, B1); PG8_BAR; PG8_SCHED;
;             PG8_LDA(At, 1, 1); PG8_STAGE(PG8_SB(1, 0), b3, voffB); PG8_STAGE(PG8_SB(1, 1), b3 + hstepB, voffB); PG8_STAGE(PG8_SA(1, 0), a3, voffA);
;             PG8_WAIT_V(8); PG8_WAIT_L(0); PG8_BAR; PG8_MMA(1, 0, At, B0); PG8_MMA(1, 1, At, B1); PG8_BAR; PG8_SCHED;
.LBB0_790:
	ds_read_b128 v[152:155], v149
	ds_read_b128 v[156:159], v149 offset:1024
	ds_read_b128 v[160:163], v149 offset:2048
	ds_read_b128 v[164:167], v149 offset:3072
	ds_read_b128 v[168:171], v150
	ds_read_b128 v[172:175], v150 offset:1024
	ds_read_b128 v[176:179], v150 offset:2048
	ds_read_b128 v[180:183], v150 offset:3072
	s_add_u32 s22, s20, 0xfff80080
	s_addc_u32 s23, s21, -1
	s_cmp_eq_u32 s50, 28
	s_cselect_b32 s25, s15, s23
	s_cselect_b32 s24, s14, s22
	s_cselect_b32 s23, s17, s13
	s_cselect_b32 s22, s16, s11
	v_lshl_add_u64 v[144:145], s[20:21], 0, v[138:139]
	s_add_i32 m0, s19, 0xc000
	ds_read_b128 v[184:187], v151
	ds_read_b128 v[188:191], v151 offset:1024
	ds_read_b128 v[192:195], v151 offset:2048
	ds_read_b128 v[196:199], v151 offset:3072
	ds_read_b128 v[200:203], v151 offset:4096
	ds_read_b128 v[206:209], v151 offset:5120
	ds_read_b128 v[210:213], v151 offset:6144
	ds_read_b128 v[214:217], v151 offset:7168
	global_load_lds_dwordx4 v[144:145], off
	v_lshl_add_u64 v[144:145], s[20:21], 0, v[136:137]
	s_add_i32 m0, s19, 0xe000
	s_nop 0
	global_load_lds_dwordx4 v[144:145], off
	s_waitcnt vmcnt(8)
	s_waitcnt lgkmcnt(0)
	s_barrier
	s_setprio 1
	v_mfma_f32_16x16x32_bf16 v[124:127], v[152:155], v[184:187], v[124:127]
	v_mfma_f32_16x16x32_bf16 v[120:123], v[160:163], v[184:187], v[120:123]
	v_mfma_f32_16x16x32_bf16 v[108:111], v[152:155], v[192:195], v[108:111]
	v_mfma_f32_16x16x32_bf16 v[104:107], v[160:163], v[192:195], v[104:107]
	v_mfma_f32_16x16x32_bf16 v[92:95], v[152:155], v[200:203], v[92:95]
	v_mfma_f32_16x16x32_bf16 v[88:91], v[160:163], v[200:203], v[88:91]
	v_mfma_f32_16x16x32_bf16 v[76:79], v[152:155], v[210:213], v[76:79]
	v_mfma_f32_16x16x32_bf16 v[72:75], v[160:163], v[210:213], v[72:75]
	v_mfma_f32_16x16x32_bf16 v[124:127], v[156:159], v[188:191], v[124:127]
	v_mfma_f32_16x16x32_bf16 v[120:123], v[164:167], v[188:191], v[120:123]
	v_mfma_f32_16x16x32_bf16 v[108:111], v[156:159], v[196:199], v[108:111]
	v_mfma_f32_16x16x32_bf16 v[104:107], v[164:167], v[196:199], v[104:107]
	v_mfma_f32_16x16x32_bf16 v[92:95], v[156:159], v[206:209], v[92:95]
	v_mfma_f32_16x16x32_bf16 v[88:91], v[164:167], v[206:209], v[88:91]
	v_mfma_f32_16x16x32_bf16 v[76:79], v[156:159], v[214:217], v[76:79]
	v_mfma_f32_16x16x32_bf16 v[72:75], v[164:167], v[214:217], v[72:75]
	v_mfma_f32_16x16x32_bf16 v[116:119], v[168:171], v[184:187], v[116:119]
	v_mfma_f32_16x16x32_bf16 v[112:115], v[176:179], v[184:187], v[112:115]
	v_mfma_f32_16x16x32_bf16 v[100:103], v[168:171], v[192:195], v[100:103]
	v_mfma_f32_16x16x32_bf16 v[96:99], v[176:179], v[192:195], v[96:99]
	v_mfma_f32_16x16x32_bf16 v[84:87], v[168:171], v[200:203], v[84:87]
	v_mfma_f32_16x16x32_bf16 v[80:83], v[176:179], v[200:203], v[80:83]
	v_mfma_f32_16x16x32_bf16 v[68:71], v[168:171], v[210:213], v[68:71]
	v_mfma_f32_16x16x32_bf16 v[64:67], v[176:179], v[210:213], v[64:67]
	v_mfma_f32_16x16x32_bf16 v[116:119], v[172:175], v[188:191], v[116:119]
	v_mfma_f32_16x16x32_bf16 v[112:115], v[180:183], v[188:191], v[112:115]
	v_mfma_f32_16x16x32_bf16 v[100:103], v[172:175], v[196:199], v[100:103]
	v_mfma_f32_16x16x32_bf16 v[96:99], v[180:183], v[196:199], v[96:99]
	v_mfma_f32_16x16x32_bf16 v[84:87], v[172:175], v[206:209], v[84:87]
	v_mfma_f32_16x16x32_bf16 v[80:83], v[180:183], v[206:209], v[80:83]
	v_mfma_f32_16x16x32_bf16 v[68:71], v[172:175], v[214:217], v[68:71]
	v_mfma_f32_16x16x32_bf16 v[64:67], v[180:183], v[214:217], v[64:67]
	s_setprio 0
	s_barrier
	s_add_i32 s51, s46, s35
	v_lshl_add_u64 v[144:145], s[22:23], 0, v[132:133]
	s_mov_b32 m0, s51
	ds_read_b128 v[184:187], v151 offset:16384
	ds_read_b128 v[188:191], v151 offset:17408
	ds_read_b128 v[192:195], v151 offset:18432
	ds_read_b128 v[196:199], v151 offset:19456
	ds_read_b128 v[200:203], v151 offset:20480
	ds_read_b128 v[206:209], v151 offset:21504
	ds_read_b128 v[210:213], v151 offset:22528
	ds_read_b128 v[214:217], v151 offset:23552
	global_load_lds_dwordx4 v[144:145], off
	s_add_i32 m0, s51, 0x2000
	s_add_u32 s52, s22, 0x80000
	v_lshl_add_u64 v[218:219], s[22:23], 0, v[128:129]
	s_addc_u32 s53, s23, 0
	s_add_i32 s51, s47, s35
	global_load_lds_dwordx4 v[218:219], off
	v_lshl_add_u64 v[220:221], s[52:53], 0, v[132:133]
	s_mov_b32 m0, s51
	v_lshl_add_u64 v[222:223], s[24:25], 0, v[130:131]
	global_load_lds_dwordx4 v[220:221], off
	v_lshl_add_u64 v[220:221], s[52:53], 0, v[128:129]
	s_add_i32 m0, s51, 0x2000
	s_nop 0
	global_load_lds_dwordx4 v[220:221], off
	v_lshl_add_u64 v[220:221], s[24:25], 0, v[134:135]
	s_mov_b32 m0, s19
	s_nop 0
	global_load_lds_dwordx4 v[220:221], off
	s_mov_b32 m0, s37
	s_nop 0
	global_load_lds_dwordx4 v[222:223], off
	s_waitcnt vmcnt(8)
	s_waitcnt lgkmcnt(0)
	s_barrier
; #define PG8_STAGE(bufoff, gbase, voff) do { _Pragma("unroll") for (int _i = 0; _i < 2; ++_i) \
;         __builtin_amdgcn_global_load_lds((const unsigned*)((const char*)(gbase) + (voff)[_i]), (PG8_LAS unsigned*)(lds + (bufoff) + ldsw + _i * 8192), 16, 0, 0); } while (0)
; #define PG8_LDA(dst, b, h) do { _Pragma("unroll") for (int m = 0; m < 4; ++m) _Pragma("unroll") for (int k = 0; k < 2; ++k) dst[m][k] = *(const PG8_LAS bf16x8*)(lds + PG8_SA(b, h) + aoff + m * 2048 + k * 1024); } while (0)
; #define PG8_LDB(dst, b, h) do { _Pragma("unroll") for (int n = 0; n < 2; ++n) _Pragma("unroll") for (int k = 0; k < 2; ++k) dst[n][k] = *(const PG8_LAS bf16x8*)(lds + PG8_SB(b, h) + boff + n * 2048 + k * 1024); } while (0)
; #define PG8_MMA(ai, bj, At, Bt) do { __builtin_amdgcn_s_setprio(1); _Pragma("unroll") for (int m = 0; m < 4; ++m) _Pragma("unroll") for (int n = 0; n < 2; ++n) _Pragma("unroll") for (int k = 0; k < 2; ++k) \
;         acc[ai][bj][m][n] = __builtin_amdgcn_mfma_f32_16x16x32_bf16(Bt[n][k], At[m][k], acc[ai][bj][m][n], 0, 0, 0); __builtin_amdgcn_s_setprio(0); } while (0)
; #define PG8_WAIT_V(n) asm volatile("s_waitcnt vmcnt(" #n ")" ::: "memory")
; #define PG8_WAIT_L(n) asm volatile("s_waitcnt lgkmcnt(" #n ")" ::: "memory")
; #define PG8_BAR __builtin_amdgcn_s_barrier()
; #define PG8_SCHED __builtin_amdgcn_sched_barrier(0)
; template <class Epi, class Sched, bool ALIGN_EPI = false, bool SP2 = false>
; __device__ __forceinline__ void gemm_phase(PG8_LAS unsigned char* lds, const Gemm g, const Sched& S, const Epi& E, const int wv0) {
;     ...
;             PG8_WAIT_V(8); PG8_WAIT_L(0); PG8_BAR; PG8_MMA(1, 0, At, B0); PG8_MMA(1, 1, At, B1); PG8_BAR; PG8_SCHED;
;             PG8_LDB(B0, 1, 0); PG8_LDB(B1, 1, 1); PG8_SCHED; PG8_LDA(At, 1, 0); PG8_STAGE(PG8_SA(0, 1), a2 + hstepA, voffA);
;             PG8_WAIT_V(8); PG8_WAIT_L(0); PG8_BAR; PG8_MMA(0, 0, At, B0); PG8_MMA(0, 1, At, B1); PG8_BAR; PG8_SCHED;
	s_setprio 1
	v_mfma_f32_16x16x32_bf16 v[60:63], v[152:155], v[184:187], v[60:63]
	v_mfma_f32_16x16x32_bf16 v[56:59], v[160:163], v[184:187], v[56:59]
	v_mfma_f32_16x16x32_bf16 v[44:47], v[152:155], v[192:195], v[44:47]
	v_mfma_f32_16x16x32_bf16 v[40:43], v[160:163], v[192:195], v[40:43]
	v_mfma_f32_16x16x32_bf16 v[28:31], v[152:155], v[200:203], v[28:31]
	v_mfma_f32_16x16x32_bf16 v[24:27], v[160:163], v[200:203], v[24:27]
	v_mfma_f32_16x16x32_bf16 v[12:15], v[152:155], v[210:213], v[12:15]
	v_mfma_f32_16x16x32_bf16 v[8:11], v[160:163], v[210:213], v[8:11]
	v_mfma_f32_16x16x32_bf16 v[60:63], v[156:159], v[188:191], v[60:63]
	v_mfma_f32_16x16x32_bf16 v[56:59], v[164:167], v[188:191], v[56:59]
	v_mfma_f32_16x16x32_bf16 v[44:47], v[156:159], v[196:199], v[44:47]
	v_mfma_f32_16x16x32_bf16 v[40:43], v[164:167], v[196:199], v[40:43]
	v_mfma_f32_16x16x32_bf16 v[28:31], v[156:159], v[206:209], v[28:31]
	v_mfma_f32_16x16x32_bf16 v[24:27], v[164:167], v[206:209], v[24:27]
	v_mfma_f32_16x16x32_bf16 v[12:15], v[156:159], v[214:217], v[12:15]
	v_mfma_f32_16x16x32_bf16 v[8:11], v[164:167], v[214:217], v[8:11]
	v_mfma_f32_16x16x32_bf16 v[52:55], v[168:171], v[184:187], v[52:55]
	v_mfma_f32_16x16x32_bf16 v[48:51], v[176:179], v[184:187], v[48:51]
	v_mfma_f32_16x16x32_bf16 v[36:39], v[168:171], v[192:195], v[36:39]
	v_mfma_f32_16x16x32_bf16 v[32:35], v[176:179], v[192:195], v[32:35]
	v_mfma_f32_16x16x32_bf16 v[20:23], v[168:171], v[200:203], v[20:23]
	v_mfma_f32_16x16x32_bf16 v[16:19], v[176:179], v[200:203], v[16:19]
	v_mfma_f32_16x16x32_bf16 v[4:7], v[168:171], v[210:213], v[4:7]
	v_mfma_f32_16x16x32_bf16 v[0:3], v[176:179], v[210:213], v[0:3]
	v_mfma_f32_16x16x32_bf16 v[52:55], v[172:175], v[188:191], v[52:55]
	v_mfma_f32_16x16x32_bf16 v[48:51], v[180:183], v[188:191], v[48:51]
	v_mfma_f32_16x16x32_bf16 v[36:39], v[172:175], v[196:199], v[36:39]
	v_mfma_f32_16x16x32_bf16 v[32:35], v[180:183], v[196:199], v[32:35]
	v_mfma_f32_16x16x32_bf16 v[20:23], v[172:175], v[206:209], v[20:23]
	v_mfma_f32_16x16x32_bf16 v[16:19], v[180:183], v[206:209], v[16:19]
	v_mfma_f32_16x16x32_bf16 v[4:7], v[172:175], v[214:217], v[4:7]
	v_mfma_f32_16x16x32_bf16 v[0:3], v[180:183], v[214:217], v[0:3]
	s_setprio 0
	s_barrier
	s_add_i32 s51, 0, 0x18000
	s_add_i32 s52, 0, 0x1c000
	v_add_u32_e32 v164, s51, v147
	v_add_u32_e32 v180, s52, v147
	ds_read_b128 v[152:155], v164
	ds_read_b128 v[156:159], v164 offset:1024
	ds_read_b128 v[160:163], v164 offset:2048
	ds_read_b128 v[164:167], v164 offset:3072
	ds_read_b128 v[168:171], v180
	ds_read_b128 v[172:175], v180 offset:1024
	ds_read_b128 v[176:179], v180 offset:2048
	ds_read_b128 v[180:183], v180 offset:3072
	s_add_u32 s24, s24, 0x80000
	s_addc_u32 s25, s25, 0
	s_mov_b32 m0, s38
	v_lshl_add_u64 v[224:225], s[24:25], 0, v[134:135]
	ds_read_b128 v[184:187], v151 offset:32768
	ds_read_b128 v[188:191], v151 offset:33792
	ds_read_b128 v[192:195], v151 offset:34816
	ds_read_b128 v[196:199], v151 offset:35840
	ds_read_b128 v[200:203], v151 offset:36864
	ds_read_b128 v[206:209], v151 offset:37888
	ds_read_b128 v[210:213], v151 offset:38912
	ds_read_b128 v[214:217], v151 offset:39936
	global_load_lds_dwordx4 v[224:225], off
	v_lshl_add_u64 v[224:225], s[24:25], 0, v[130:131]
	s_mov_b32 m0, s39
	s_nop 0
	global_load_lds_dwordx4 v[224:225], off
	s_waitcnt vmcnt(8)
	s_waitcnt lgkmcnt(0)
	s_barrier
	s_setprio 1
	v_mfma_f32_16x16x32_bf16 v[124:127], v[152:155], v[184:187], v[124:127]
	v_mfma_f32_16x16x32_bf16 v[120:123], v[160:163], v[184:187], v[120:123]
	v_mfma_f32_16x16x32_bf16 v[108:111], v[152:155], v[192:195], v[108:111]
	v_mfma_f32_16x16x32_bf16 v[104:107], v[160:163], v[192:195], v[104:107]
	v_mfma_f32_16x16x32_bf16 v[92:95], v[152:155], v[200:203], v[92:95]
	v_mfma_f32_16x16x32_bf16 v[88:91], v[160:163], v[200:203], v[88:91]
	v_mfma_f32_16x16x32_bf16 v[76:79], v[152:155], v[210:213], v[76:79]
	v_mfma_f32_16x16x32_bf16 v[72:75], v[160:163], v[210:213], v[72:75]
	v_mfma_f32_16x16x32_bf16 v[124:127], v[156:159], v[188:191], v[124:127]
	v_mfma_f32_16x16x32_bf16 v[120:123], v[164:167], v[188:191], v[120:123]
	v_mfma_f32_16x16x32_bf16 v[108:111], v[156:159], v[196:199], v[108:111]
	v_mfma_f32_16x16x32_bf16 v[104:107], v[164:167], v[196:199], v[104:107]
	v_mfma_f32_16x16x32_bf16 v[92:95], v[156:159], v[206:209], v[92:95]
	v_mfma_f32_16x16x32_bf16 v[88:91], v[164:167], v[206:209], v[88:91]
	v_mfma_f32_16x16x32_bf16 v[76:79], v[156:159], v[214:217], v[76:79]
	v_mfma_f32_16x16x32_bf16 v[72:75], v[164:167], v[214:217], v[72:75]
	v_mfma_f32_16x16x32_bf16 v[116:119], v[168:171], v[184:187], v[116:119]
	v_mfma_f32_16x16x32_bf16 v[112:115], v[176:179], v[184:187], v[112:115]
	v_mfma_f32_16x16x32_bf16 v[100:103], v[168:171], v[192:195], v[100:103]
	v_mfma_f32_16x16x32_bf16 v[96:99], v[176:179], v[192:195], v[96:99]
	v_mfma_f32_16x16x32_bf16 v[84:87], v[168:171], v[200:203], v[84:87]
	v_mfma_f32_16x16x32_bf16 v[80:83], v[176:179], v[200:203], v[80:83]
	v_mfma_f32_16x16x32_bf16 v[68:71], v[168:171], v[210:213], v[68:71]
	v_mfma_f32_16x16x32_bf16 v[64:67], v[176:179], v[210:213], v[64:67]
	v_mfma_f32_16x16x32_bf16 v[116:119], v[172:175], v[188:191], v[116:119]
	v_mfma_f32_16x16x32_bf16 v[112:115], v[180:183], v[188:191], v[112:115]
	v_mfma_f32_16x16x32_bf16 v[100:103], v[172:175], v[196:199], v[100:103]
	v_mfma_f32_16x16x32_bf16 v[96:99], v[180:183], v[196:199], v[96:99]
	v_mfma_f32_16x16x32_bf16 v[84:87], v[172:175], v[206:209], v[84:87]
	v_mfma_f32_16x16x32_bf16 v[80:83], v[180:183], v[206:209], v[80:83]
	v_mfma_f32_16x16x32_bf16 v[68:71], v[172:175], v[214:217], v[68:71]
	v_mfma_f32_16x16x32_bf16 v[64:67], v[180:183], v[214:217], v[64:67]
	s_setprio 0
	s_barrier
; #define PG8_STAGE(bufoff, gbase, voff) do { _Pragma("unroll") for (int _i = 0; _i < 2; ++_i) \
;         __builtin_amdgcn_global_load_lds((const unsigned*)((const char*)(gbase) + (voff)[_i]), (PG8_LAS unsigned*)(lds + (bufoff) + ldsw + _i * 8192), 16, 0, 0); } while (0)
; #define PG8_LDA(dst, b, h) do { _Pragma("unroll") for (int m = 0; m < 4; ++m) _Pragma("unroll") for (int k = 0; k < 2; ++k) dst[m][k] = *(const PG8_LAS bf16x8*)(lds + PG8_SA(b, h) + aoff + m * 2048 + k * 1024); } while (0)
; #define PG8_MMA(ai, bj, At, Bt) do { __builtin_amdgcn_s_setprio(1); _Pragma("unroll") for (int m = 0; m < 4; ++m) _Pragma("unroll") for (int n = 0; n < 2; ++n) _Pragma("unroll") for (int k = 0; k < 2; ++k) \
;         acc[ai][bj][m][n] = __builtin_amdgcn_mfma_f32_16x16x32_bf16(Bt[n][k], At[m][k], acc[ai][bj][m][n], 0, 0, 0); __builtin_amdgcn_s_setprio(0); } while (0)
; #define PG8_WAIT_V(n) asm volatile("s_waitcnt vmcnt(" #n ")" ::: "memory")
; #define PG8_WAIT_L(n) asm volatile("s_waitcnt lgkmcnt(" #n ")" ::: "memory")
; #define PG8_BAR __builtin_amdgcn_s_barrier()
; #define PG8_SCHED __builtin_amdgcn_sched_barrier(0)
; template <class Epi, class Sched, bool ALIGN_EPI = false, bool SP2 = false>
; __device__ __forceinline__ void gemm_phase(PG8_LAS unsigned char* lds, const Gemm g, const Sched& S, const Epi& E, const int wv0) {
;     ...
;         for (int t = 0; t < nt; t += 2) {
;             const bool last = (t == nt - 2);
;     ...
;             PG8_LDA(At, 1, 1); PG8_STAGE(PG8_SB(1, 0), b3, voffB); PG8_STAGE(PG8_SB(1, 1), b3 + hstepB, voffB); PG8_STAGE(PG8_SA(1, 0), a3, voffA);
;             PG8_WAIT_V(8); PG8_WAIT_L(0); PG8_BAR; PG8_MMA(1, 0, At, B0); PG8_MMA(1, 1, At, B1); PG8_BAR; PG8_SCHED;
	s_add_i32 s24, s51, s35
	v_lshl_add_u64 v[144:145], v[144:145], 0, s[6:7]
	s_mov_b32 m0, s24
	ds_read_b128 v[184:187], v151 offset:49152
	ds_read_b128 v[188:191], v151 offset:50176
	ds_read_b128 v[192:195], v151 offset:51200
	ds_read_b128 v[196:199], v151 offset:52224
	ds_read_b128 v[200:203], v151 offset:53248
	ds_read_b128 v[206:209], v151 offset:54272
	ds_read_b128 v[210:213], v151 offset:55296
	ds_read_b128 v[214:217], v151 offset:56320
	global_load_lds_dwordx4 v[144:145], off
	s_add_i32 m0, s24, 0x2000
	s_add_u32 s22, s22, 0x80080
	v_lshl_add_u64 v[144:145], v[218:219], 0, s[6:7]
	s_addc_u32 s23, s23, 0
	s_add_i32 s24, s52, s35
	global_load_lds_dwordx4 v[144:145], off
	v_lshl_add_u64 v[144:145], s[22:23], 0, v[132:133]
	s_mov_b32 m0, s24
	s_nop 0
	global_load_lds_dwordx4 v[144:145], off
	v_lshl_add_u64 v[144:145], s[22:23], 0, v[128:129]
	s_add_i32 m0, s24, 0x2000
	s_nop 0
	global_load_lds_dwordx4 v[144:145], off
	v_lshl_add_u64 v[144:145], v[220:221], 0, s[6:7]
	s_mov_b32 m0, s41
	s_nop 0
	global_load_lds_dwordx4 v[144:145], off
	v_lshl_add_u64 v[144:145], v[222:223], 0, s[6:7]
	s_mov_b32 m0, s44
	s_nop 0
	global_load_lds_dwordx4 v[144:145], off
	s_waitcnt vmcnt(8)
	s_waitcnt lgkmcnt(0)
	s_barrier
	s_setprio 1
	v_mfma_f32_16x16x32_bf16 v[60:63], v[152:155], v[184:187], v[60:63]
	v_mfma_f32_16x16x32_bf16 v[56:59], v[160:163], v[184:187], v[56:59]
	v_mfma_f32_16x16x32_bf16 v[44:47], v[152:155], v[192:195], v[44:47]
	v_mfma_f32_16x16x32_bf16 v[40:43], v[160:163], v[192:195], v[40:43]
	v_mfma_f32_16x16x32_bf16 v[28:31], v[152:155], v[200:203], v[28:31]
	v_mfma_f32_16x16x32_bf16 v[24:27], v[160:163], v[200:203], v[24:27]
	v_mfma_f32_16x16x32_bf16 v[12:15], v[152:155], v[210:213], v[12:15]
	v_mfma_f32_16x16x32_bf16 v[8:11], v[160:163], v[210:213], v[8:11]
	v_mfma_f32_16x16x32_bf16 v[60:63], v[156:159], v[188:191], v[60:63]
	v_mfma_f32_16x16x32_bf16 v[56:59], v[164:167], v[188:191], v[56:59]
	v_mfma_f32_16x16x32_bf16 v[44:47], v[156:159], v[196:199], v[44:47]
	v_mfma_f32_16x16x32_bf16 v[40:43], v[164:167], v[196:199], v[40:43]
	v_mfma_f32_16x16x32_bf16 v[28:31], v[156:159], v[206:209], v[28:31]
	v_mfma_f32_16x16x32_bf16 v[24:27], v[164:167], v[206:209], v[24:27]
	v_mfma_f32_16x16x32_bf16 v[12:15], v[156:159], v[214:217], v[12:15]
	v_mfma_f32_16x16x32_bf16 v[8:11], v[164:167], v[214:217], v[8:11]
	v_mfma_f32_16x16x32_bf16 v[52:55], v[168:171], v[184:187], v[52:55]
	v_mfma_f32_16x16x32_bf16 v[48:51], v[176:179], v[184:187], v[48:51]
	v_mfma_f32_16x16x32_bf16 v[36:39], v[168:171], v[192:195], v[36:39]
	v_mfma_f32_16x16x32_bf16 v[32:35], v[176:179], v[192:195], v[32:35]
	v_mfma_f32_16x16x32_bf16 v[20:23], v[168:171], v[200:203], v[20:23]
	v_mfma_f32_16x16x32_bf16 v[16:19], v[176:179], v[200:203], v[16:19]
	v_mfma_f32_16x16x32_bf16 v[4:7], v[168:171], v[210:213], v[4:7]
	v_mfma_f32_16x16x32_bf16 v[0:3], v[176:179], v[210:213], v[0:3]
	v_mfma_f32_16x16x32_bf16 v[52:55], v[172:175], v[188:191], v[52:55]
	v_mfma_f32_16x16x32_bf16 v[48:51], v[180:183], v[188:191], v[48:51]
	v_mfma_f32_16x16x32_bf16 v[36:39], v[172:175], v[196:199], v[36:39]
	v_mfma_f32_16x16x32_bf16 v[32:35], v[180:183], v[196:199], v[32:35]
	v_mfma_f32_16x16x32_bf16 v[20:23], v[172:175], v[206:209], v[20:23]
	v_mfma_f32_16x16x32_bf16 v[16:19], v[180:183], v[206:209], v[16:19]
	v_mfma_f32_16x16x32_bf16 v[4:7], v[172:175], v[214:217], v[4:7]
	v_mfma_f32_16x16x32_bf16 v[0:3], v[180:183], v[214:217], v[0:3]
	s_setprio 0
	s_add_i32 s50, s50, 2
	s_add_u32 s11, s11, 0x100
	s_addc_u32 s13, s13, 0
	s_add_u32 s20, s20, 0x100
	s_addc_u32 s21, s21, 0
	s_cmp_gt_u32 s50, 29
	s_barrier
	s_cbranch_scc0 .LBB0_790
	s_and_b64 vcc, exec, s[8:9]
	s_cbranch_vccz .LBB0_793
	s_barrier

; #define PG8_STAGE(bufoff, gbase, voff) do { _Pragma("unroll") for (int _i = 0; _i < 2; ++_i) \
;         __builtin_amdgcn_global_load_lds((const unsigned*)((const char*)(gbase) + (voff)[_i]), (PG8_LAS unsigned*)(lds + (bufoff) + ldsw + _i * 8192), 16, 0, 0); } while (0)
; #define PG8_LDA(dst, b, h) do { _Pragma("unroll") for (int m = 0; m < 4; ++m) _Pragma("unroll") for (int k = 0; k < 2; ++k) dst[m][k] = *(const PG8_LAS bf16x8*)(lds + PG8_SA(b, h) + aoff + m * 2048 + k * 1024); } while (0)
; #define PG8_LDB(dst, b, h) do { _Pragma("unroll") for (int n = 0; n < 2; ++n) _Pragma("unroll") for (int k = 0; k < 2; ++k) dst[n][k] = *(const PG8_LAS bf16x8*)(lds + PG8_SB(b, h) + boff + n * 2048 + k * 1024); } while (0)
; template <class Epi, class Sched, bool ALIGN_EPI = false, bool SP2 = false>
; __device__ __forceinline__ void gemm_phase(PG8_LAS unsigned char* lds, const Gemm g, const Sched& S, const Epi& E, const int wv0) {
;     ...
;         for (int t = 0; t < nt; t += 2) {
;             const bool last = (t == nt - 2);
;             const char* a1 = cA + (size_t)(t + 1) * kstep;
;             const char* a2 = last ? nA : cA + (size_t)(t + 2) * kstep; const char* b2 = last ? nB : cB + (size_t)(t + 2) * kstep;
;             const char* a3 = a2 + kstep; const char* b3 = b2 + kstep;
;             if constexpr (SP2) {
;             PG8_LDB(B0, 0, 0); PG8_LDB(B1, 0, 1); PG8_SCHED; PG8_LDA(At, 0, 0); PG8_STAGE(PG8_SA(1, 1), a1 + hstepA, voffA);
;             PG8_WAIT_V(8); PG8_WAIT_L(0); PG8_BAR; PG8_MMA(0, 0, At, B0); PG8_MMA(0, 1, At, B1); PG8_BAR; PG8_SCHED;
;             PG8_LDA(At, 0, 1); PG8_STAGE(PG8_SB(0, 0), b2, voffB); PG8_STAGE(PG8_SB(0, 1), b2 + hstepB, voffB); PG8_STAGE(PG8_SA(0, 0), a2, voffA);
;             PG8_WAIT_V(8); PG8_WAIT_L(0); PG8_BAR; PG8_MMA(1, 0, At, B0); PG8_MMA(1, 1, At, B1); PG8_BAR; PG8_SCHED;
;             PG8_LDB(B0, 1, 0); PG8_LDB(B1, 1, 1); PG8_SCHED; PG8_LDA(At, 1, 0); PG8_STAGE(PG8_SA(0, 1), a2 + hstepA, voffA);
;             PG8_WAIT_V(8); PG8_WAIT_L(0); PG8_BAR; PG8_MMA(0, 0, At, B0); PG8_MMA(0, 1, At, B1); PG8_BAR; PG8_SCHED;
;             PG8_LDA(At, 1, 1); PG8_STAGE(PG8_SB(1, 0), b3, voffB); PG8_STAGE(PG8_SB(1, 1), b3 + hstepB, voffB); PG8_STAGE(PG8_SA(1, 0), a3, voffA);
;             PG8_WAIT_V(8); PG8_WAIT_L(0); PG8_BAR; PG8_MMA(1, 0, At, B0); PG8_MMA(1, 1, At, B1); PG8_BAR; PG8_SCHED;
.LBB0_867:
	ds_read_b128 v[144:147], v155
	ds_read_b128 v[148:151], v155 offset:1024
	ds_read_b128 v[158:161], v155 offset:2048
	ds_read_b128 v[162:165], v155 offset:3072
	ds_read_b128 v[166:169], v156
	ds_read_b128 v[170:173], v156 offset:1024
	ds_read_b128 v[174:177], v156 offset:2048
	ds_read_b128 v[178:181], v156 offset:3072
	s_add_u32 s24, s22, 0x100
	s_addc_u32 s25, s23, 0
	s_cmpk_eq_i32 s58, 0x54
	s_cselect_b32 s29, s19, s25
	s_cselect_b32 s28, s18, s24
	s_cselect_b32 s27, s21, s57
	s_cselect_b32 s26, s20, s56
	v_lshl_add_u64 v[202:203], s[22:23], 0, v[138:139]
	s_add_i32 m0, s40, 0xc000
	ds_read_b128 v[182:185], v157
	ds_read_b128 v[186:189], v157 offset:1024
	ds_read_b128 v[190:193], v157 offset:2048
	ds_read_b128 v[194:197], v157 offset:3072
	ds_read_b128 v[198:201], v157 offset:4096
	ds_read_b128 v[206:209], v157 offset:5120
	ds_read_b128 v[210:213], v157 offset:6144
	ds_read_b128 v[214:217], v157 offset:7168
	global_load_lds_dwordx4 v[202:203], off
	v_lshl_add_u64 v[202:203], s[22:23], 0, v[136:137]
	s_add_i32 m0, s40, 0xe000
	s_nop 0
	global_load_lds_dwordx4 v[202:203], off
	s_waitcnt vmcnt(8)
	s_waitcnt lgkmcnt(0)
	s_barrier
	s_setprio 1
	v_mfma_f32_16x16x32_bf16 v[124:127], v[144:147], v[182:185], v[124:127]
	v_mfma_f32_16x16x32_bf16 v[120:123], v[158:161], v[182:185], v[120:123]
	v_mfma_f32_16x16x32_bf16 v[116:119], v[144:147], v[190:193], v[116:119]
	v_mfma_f32_16x16x32_bf16 v[112:115], v[158:161], v[190:193], v[112:115]
	v_mfma_f32_16x16x32_bf16 v[92:95], v[144:147], v[198:201], v[92:95]
	v_mfma_f32_16x16x32_bf16 v[88:91], v[158:161], v[198:201], v[88:91]
	v_mfma_f32_16x16x32_bf16 v[84:87], v[144:147], v[210:213], v[84:87]
	v_mfma_f32_16x16x32_bf16 v[80:83], v[158:161], v[210:213], v[80:83]
	v_mfma_f32_16x16x32_bf16 v[124:127], v[148:151], v[186:189], v[124:127]
	v_mfma_f32_16x16x32_bf16 v[120:123], v[162:165], v[186:189], v[120:123]
	v_mfma_f32_16x16x32_bf16 v[116:119], v[148:151], v[194:197], v[116:119]
	v_mfma_f32_16x16x32_bf16 v[112:115], v[162:165], v[194:197], v[112:115]
	v_mfma_f32_16x16x32_bf16 v[92:95], v[148:151], v[206:209], v[92:95]
	v_mfma_f32_16x16x32_bf16 v[88:91], v[162:165], v[206:209], v[88:91]
	v_mfma_f32_16x16x32_bf16 v[84:87], v[148:151], v[214:217], v[84:87]
	v_mfma_f32_16x16x32_bf16 v[80:83], v[162:165], v[214:217], v[80:83]
	v_mfma_f32_16x16x32_bf16 v[108:111], v[166:169], v[182:185], v[108:111]
	v_mfma_f32_16x16x32_bf16 v[104:107], v[174:177], v[182:185], v[104:107]
	v_mfma_f32_16x16x32_bf16 v[100:103], v[166:169], v[190:193], v[100:103]
	v_mfma_f32_16x16x32_bf16 v[96:99], v[174:177], v[190:193], v[96:99]
	v_mfma_f32_16x16x32_bf16 v[76:79], v[166:169], v[198:201], v[76:79]
	v_mfma_f32_16x16x32_bf16 v[72:75], v[174:177], v[198:201], v[72:75]
	v_mfma_f32_16x16x32_bf16 v[68:71], v[166:169], v[210:213], v[68:71]
	v_mfma_f32_16x16x32_bf16 v[64:67], v[174:177], v[210:213], v[64:67]
	v_mfma_f32_16x16x32_bf16 v[108:111], v[170:173], v[186:189], v[108:111]
	v_mfma_f32_16x16x32_bf16 v[104:107], v[178:181], v[186:189], v[104:107]
	v_mfma_f32_16x16x32_bf16 v[100:103], v[170:173], v[194:197], v[100:103]
	v_mfma_f32_16x16x32_bf16 v[96:99], v[178:181], v[194:197], v[96:99]
	v_mfma_f32_16x16x32_bf16 v[76:79], v[170:173], v[206:209], v[76:79]
	v_mfma_f32_16x16x32_bf16 v[72:75], v[178:181], v[206:209], v[72:75]
	v_mfma_f32_16x16x32_bf16 v[68:71], v[170:173], v[214:217], v[68:71]
	v_mfma_f32_16x16x32_bf16 v[64:67], v[178:181], v[214:217], v[64:67]
	s_setprio 0
	s_barrier
	s_add_i32 s22, s50, s39
	v_lshl_add_u64 v[202:203], s[26:27], 0, v[130:131]
	s_mov_b32 m0, s22
	ds_read_b128 v[182:185], v157 offset:16384
	ds_read_b128 v[186:189], v157 offset:17408
	ds_read_b128 v[190:193], v157 offset:18432
	ds_read_b128 v[194:197], v157 offset:19456
	ds_read_b128 v[198:201], v157 offset:20480
	ds_read_b128 v[206:209], v157 offset:21504
	ds_read_b128 v[210:213], v157 offset:22528
	ds_read_b128 v[214:217], v157 offset:23552
	global_load_lds_dwordx4 v[202:203], off
	s_add_i32 m0, s22, 0x2000
	s_add_u32 s22, s26, 0x160000
	v_lshl_add_u64 v[218:219], s[26:27], 0, v[134:135]
	s_addc_u32 s23, s27, 0
	s_add_i32 s59, s51, s39
	global_load_lds_dwordx4 v[218:219], off
	v_lshl_add_u64 v[220:221], s[22:23], 0, v[130:131]
	s_mov_b32 m0, s59
	v_lshl_add_u64 v[222:223], s[28:29], 0, v[132:133]
	global_load_lds_dwordx4 v[220:221], off
	v_lshl_add_u64 v[220:221], s[22:23], 0, v[134:135]
	s_add_i32 m0, s59, 0x2000
	s_nop 0
	global_load_lds_dwordx4 v[220:221], off
	v_lshl_add_u64 v[220:221], s[28:29], 0, v[128:129]
	s_mov_b32 m0, s40
	s_nop 0
	global_load_lds_dwordx4 v[220:221], off
	s_mov_b32 m0, s41
	s_nop 0
	global_load_lds_dwordx4 v[222:223], off
	s_waitcnt vmcnt(8)
	s_waitcnt lgkmcnt(0)
	s_barrier
; #define PG8_STAGE(bufoff, gbase, voff) do { _Pragma("unroll") for (int _i = 0; _i < 2; ++_i) \
;         __builtin_amdgcn_global_load_lds((const unsigned*)((const char*)(gbase) + (voff)[_i]), (PG8_LAS unsigned*)(lds + (bufoff) + ldsw + _i * 8192), 16, 0, 0); } while (0)
; #define PG8_LDA(dst, b, h) do { _Pragma("unroll") for (int m = 0; m < 4; ++m) _Pragma("unroll") for (int k = 0; k < 2; ++k) dst[m][k] = *(const PG8_LAS bf16x8*)(lds + PG8_SA(b, h) + aoff + m * 2048 + k * 1024); } while (0)
; #define PG8_LDB(dst, b, h) do { _Pragma("unroll") for (int n = 0; n < 2; ++n) _Pragma("unroll") for (int k = 0; k < 2; ++k) dst[n][k] = *(const PG8_LAS bf16x8*)(lds + PG8_SB(b, h) + boff + n * 2048 + k * 1024); } while (0)
; #define PG8_MMA(ai, bj, At, Bt) do { __builtin_amdgcn_s_setprio(1); _Pragma("unroll") for (int m = 0; m < 4; ++m) _Pragma("unroll") for (int n = 0; n < 2; ++n) _Pragma("unroll") for (int k = 0; k < 2; ++k) \
;         acc[ai][bj][m][n] = __builtin_amdgcn_mfma_f32_16x16x32_bf16(Bt[n][k], At[m][k], acc[ai][bj][m][n], 0, 0, 0); __builtin_amdgcn_s_setprio(0); } while (0)
; #define PG8_WAIT_V(n) asm volatile("s_waitcnt vmcnt(" #n ")" ::: "memory")
; #define PG8_WAIT_L(n) asm volatile("s_waitcnt lgkmcnt(" #n ")" ::: "memory")
; #define PG8_BAR __builtin_amdgcn_s_barrier()
; #define PG8_SCHED __builtin_amdgcn_sched_barrier(0)
; template <class Epi, class Sched, bool ALIGN_EPI = false, bool SP2 = false>
; __device__ __forceinline__ void gemm_phase(PG8_LAS unsigned char* lds, const Gemm g, const Sched& S, const Epi& E, const int wv0) {
;     ...
;             PG8_WAIT_V(8); PG8_WAIT_L(0); PG8_BAR; PG8_MMA(1, 0, At, B0); PG8_MMA(1, 1, At, B1); PG8_BAR; PG8_SCHED;
;             PG8_LDB(B0, 1, 0); PG8_LDB(B1, 1, 1); PG8_SCHED; PG8_LDA(At, 1, 0); PG8_STAGE(PG8_SA(0, 1), a2 + hstepA, voffA);
;             PG8_WAIT_V(8); PG8_WAIT_L(0); PG8_BAR; PG8_MMA(0, 0, At, B0); PG8_MMA(0, 1, At, B1); PG8_BAR; PG8_SCHED;
	s_setprio 1
	v_mfma_f32_16x16x32_bf16 v[60:63], v[144:147], v[182:185], v[60:63]
	v_mfma_f32_16x16x32_bf16 v[56:59], v[158:161], v[182:185], v[56:59]
	v_mfma_f32_16x16x32_bf16 v[52:55], v[144:147], v[190:193], v[52:55]
	v_mfma_f32_16x16x32_bf16 v[48:51], v[158:161], v[190:193], v[48:51]
	v_mfma_f32_16x16x32_bf16 v[28:31], v[144:147], v[198:201], v[28:31]
	v_mfma_f32_16x16x32_bf16 v[24:27], v[158:161], v[198:201], v[24:27]
	v_mfma_f32_16x16x32_bf16 v[20:23], v[144:147], v[210:213], v[20:23]
	v_mfma_f32_16x16x32_bf16 v[16:19], v[158:161], v[210:213], v[16:19]
	v_mfma_f32_16x16x32_bf16 v[60:63], v[148:151], v[186:189], v[60:63]
	v_mfma_f32_16x16x32_bf16 v[56:59], v[162:165], v[186:189], v[56:59]
	v_mfma_f32_16x16x32_bf16 v[52:55], v[148:151], v[194:197], v[52:55]
	v_mfma_f32_16x16x32_bf16 v[48:51], v[162:165], v[194:197], v[48:51]
	v_mfma_f32_16x16x32_bf16 v[28:31], v[148:151], v[206:209], v[28:31]
	v_mfma_f32_16x16x32_bf16 v[24:27], v[162:165], v[206:209], v[24:27]
	v_mfma_f32_16x16x32_bf16 v[20:23], v[148:151], v[214:217], v[20:23]
	v_mfma_f32_16x16x32_bf16 v[16:19], v[162:165], v[214:217], v[16:19]
	v_mfma_f32_16x16x32_bf16 v[44:47], v[166:169], v[182:185], v[44:47]
	v_mfma_f32_16x16x32_bf16 v[40:43], v[174:177], v[182:185], v[40:43]
	v_mfma_f32_16x16x32_bf16 v[36:39], v[166:169], v[190:193], v[36:39]
	v_mfma_f32_16x16x32_bf16 v[32:35], v[174:177], v[190:193], v[32:35]
	v_mfma_f32_16x16x32_bf16 v[12:15], v[166:169], v[198:201], v[12:15]
	v_mfma_f32_16x16x32_bf16 v[8:11], v[174:177], v[198:201], v[8:11]
	v_mfma_f32_16x16x32_bf16 v[4:7], v[166:169], v[210:213], v[4:7]
	v_mfma_f32_16x16x32_bf16 v[0:3], v[174:177], v[210:213], v[0:3]
	v_mfma_f32_16x16x32_bf16 v[44:47], v[170:173], v[186:189], v[44:47]
	v_mfma_f32_16x16x32_bf16 v[40:43], v[178:181], v[186:189], v[40:43]
	v_mfma_f32_16x16x32_bf16 v[36:39], v[170:173], v[194:197], v[36:39]
	v_mfma_f32_16x16x32_bf16 v[32:35], v[178:181], v[194:197], v[32:35]
	v_mfma_f32_16x16x32_bf16 v[12:15], v[170:173], v[206:209], v[12:15]
	v_mfma_f32_16x16x32_bf16 v[8:11], v[178:181], v[206:209], v[8:11]
	v_mfma_f32_16x16x32_bf16 v[4:7], v[170:173], v[214:217], v[4:7]
	v_mfma_f32_16x16x32_bf16 v[0:3], v[178:181], v[214:217], v[0:3]
	s_setprio 0
	s_barrier
	s_add_i32 s59, 0, 0x18000
	s_add_i32 s60, 0, 0x1c000
	v_add_u32_e32 v162, s59, v153
	v_add_u32_e32 v178, s60, v153
	ds_read_b128 v[144:147], v162
	ds_read_b128 v[148:151], v162 offset:1024
	ds_read_b128 v[158:161], v162 offset:2048
	ds_read_b128 v[162:165], v162 offset:3072
	ds_read_b128 v[166:169], v178
	ds_read_b128 v[170:173], v178 offset:1024
	ds_read_b128 v[174:177], v178 offset:2048
	ds_read_b128 v[178:181], v178 offset:3072
	s_add_u32 s22, s28, 0x160000
	s_addc_u32 s23, s29, 0
	s_mov_b32 m0, s44
	v_lshl_add_u64 v[224:225], s[22:23], 0, v[128:129]
	ds_read_b128 v[182:185], v157 offset:32768
	ds_read_b128 v[186:189], v157 offset:33792
	ds_read_b128 v[190:193], v157 offset:34816
	ds_read_b128 v[194:197], v157 offset:35840
	ds_read_b128 v[198:201], v157 offset:36864
	ds_read_b128 v[206:209], v157 offset:37888
	ds_read_b128 v[210:213], v157 offset:38912
	ds_read_b128 v[214:217], v157 offset:39936
	global_load_lds_dwordx4 v[224:225], off
	v_lshl_add_u64 v[224:225], s[22:23], 0, v[132:133]
	s_mov_b32 m0, s45
	s_nop 0
	global_load_lds_dwordx4 v[224:225], off
	s_waitcnt vmcnt(8)
	s_waitcnt lgkmcnt(0)
	s_barrier
	s_setprio 1
	v_mfma_f32_16x16x32_bf16 v[124:127], v[144:147], v[182:185], v[124:127]
	v_mfma_f32_16x16x32_bf16 v[120:123], v[158:161], v[182:185], v[120:123]
	v_mfma_f32_16x16x32_bf16 v[116:119], v[144:147], v[190:193], v[116:119]
	v_mfma_f32_16x16x32_bf16 v[112:115], v[158:161], v[190:193], v[112:115]
	v_mfma_f32_16x16x32_bf16 v[92:95], v[144:147], v[198:201], v[92:95]
	v_mfma_f32_16x16x32_bf16 v[88:91], v[158:161], v[198:201], v[88:91]
	v_mfma_f32_16x16x32_bf16 v[84:87], v[144:147], v[210:213], v[84:87]
	v_mfma_f32_16x16x32_bf16 v[80:83], v[158:161], v[210:213], v[80:83]
	v_mfma_f32_16x16x32_bf16 v[124:127], v[148:151], v[186:189], v[124:127]
	v_mfma_f32_16x16x32_bf16 v[120:123], v[162:165], v[186:189], v[120:123]
	v_mfma_f32_16x16x32_bf16 v[116:119], v[148:151], v[194:197], v[116:119]
	v_mfma_f32_16x16x32_bf16 v[112:115], v[162:165], v[194:197], v[112:115]
	v_mfma_f32_16x16x32_bf16 v[92:95], v[148:151], v[206:209], v[92:95]
	v_mfma_f32_16x16x32_bf16 v[88:91], v[162:165], v[206:209], v[88:91]
	v_mfma_f32_16x16x32_bf16 v[84:87], v[148:151], v[214:217], v[84:87]
	v_mfma_f32_16x16x32_bf16 v[80:83], v[162:165], v[214:217], v[80:83]
	v_mfma_f32_16x16x32_bf16 v[108:111], v[166:169], v[182:185], v[108:111]
	v_mfma_f32_16x16x32_bf16 v[104:107], v[174:177], v[182:185], v[104:107]
	v_mfma_f32_16x16x32_bf16 v[100:103], v[166:169], v[190:193], v[100:103]
	v_mfma_f32_16x16x32_bf16 v[96:99], v[174:177], v[190:193], v[96:99]
	v_mfma_f32_16x16x32_bf16 v[76:79], v[166:169], v[198:201], v[76:79]
	v_mfma_f32_16x16x32_bf16 v[72:75], v[174:177], v[198:201], v[72:75]
	v_mfma_f32_16x16x32_bf16 v[68:71], v[166:169], v[210:213], v[68:71]
	v_mfma_f32_16x16x32_bf16 v[64:67], v[174:177], v[210:213], v[64:67]
	v_mfma_f32_16x16x32_bf16 v[108:111], v[170:173], v[186:189], v[108:111]
	v_mfma_f32_16x16x32_bf16 v[104:107], v[178:181], v[186:189], v[104:107]
	v_mfma_f32_16x16x32_bf16 v[100:103], v[170:173], v[194:197], v[100:103]
	v_mfma_f32_16x16x32_bf16 v[96:99], v[178:181], v[194:197], v[96:99]
	v_mfma_f32_16x16x32_bf16 v[76:79], v[170:173], v[206:209], v[76:79]
	v_mfma_f32_16x16x32_bf16 v[72:75], v[178:181], v[206:209], v[72:75]
	v_mfma_f32_16x16x32_bf16 v[68:71], v[170:173], v[214:217], v[68:71]
	v_mfma_f32_16x16x32_bf16 v[64:67], v[178:181], v[214:217], v[64:67]
	s_setprio 0
	s_barrier
; #define PG8_STAGE(bufoff, gbase, voff) do { _Pragma("unroll") for (int _i = 0; _i < 2; ++_i) \
;         __builtin_amdgcn_global_load_lds((const unsigned*)((const char*)(gbase) + (voff)[_i]), (PG8_LAS unsigned*)(lds + (bufoff) + ldsw + _i * 8192), 16, 0, 0); } while (0)
; #define PG8_LDA(dst, b, h) do { _Pragma("unroll") for (int m = 0; m < 4; ++m) _Pragma("unroll") for (int k = 0; k < 2; ++k) dst[m][k] = *(const PG8_LAS bf16x8*)(lds + PG8_SA(b, h) + aoff + m * 2048 + k * 1024); } while (0)
; #define PG8_MMA(ai, bj, At, Bt) do { __builtin_amdgcn_s_setprio(1); _Pragma("unroll") for (int m = 0; m < 4; ++m) _Pragma("unroll") for (int n = 0; n < 2; ++n) _Pragma("unroll") for (int k = 0; k < 2; ++k) \
;         acc[ai][bj][m][n] = __builtin_amdgcn_mfma_f32_16x16x32_bf16(Bt[n][k], At[m][k], acc[ai][bj][m][n], 0, 0, 0); __builtin_amdgcn_s_setprio(0); } while (0)
; #define PG8_WAIT_V(n) asm volatile("s_waitcnt vmcnt(" #n ")" ::: "memory")
; #define PG8_WAIT_L(n) asm volatile("s_waitcnt lgkmcnt(" #n ")" ::: "memory")
; #define PG8_BAR __builtin_amdgcn_s_barrier()
; #define PG8_SCHED __builtin_amdgcn_sched_barrier(0)
; template <class Epi, class Sched, bool ALIGN_EPI = false, bool SP2 = false>
; __device__ __forceinline__ void gemm_phase(PG8_LAS unsigned char* lds, const Gemm g, const Sched& S, const Epi& E, const int wv0) {
;     ...
;         for (int t = 0; t < nt; t += 2) {
;             const bool last = (t == nt - 2);
;     ...
;             PG8_LDA(At, 1, 1); PG8_STAGE(PG8_SB(1, 0), b3, voffB); PG8_STAGE(PG8_SB(1, 1), b3 + hstepB, voffB); PG8_STAGE(PG8_SA(1, 0), a3, voffA);
;             PG8_WAIT_V(8); PG8_WAIT_L(0); PG8_BAR; PG8_MMA(1, 0, At, B0); PG8_MMA(1, 1, At, B1); PG8_BAR; PG8_SCHED;
	s_add_i32 s22, s59, s39
	v_lshl_add_u64 v[202:203], v[202:203], 0, s[6:7]
	s_mov_b32 m0, s22
	ds_read_b128 v[182:185], v157 offset:49152
	ds_read_b128 v[186:189], v157 offset:50176
	ds_read_b128 v[190:193], v157 offset:51200
	ds_read_b128 v[194:197], v157 offset:52224
	ds_read_b128 v[198:201], v157 offset:53248
	ds_read_b128 v[206:209], v157 offset:54272
	ds_read_b128 v[210:213], v157 offset:55296
	ds_read_b128 v[214:217], v157 offset:56320
	global_load_lds_dwordx4 v[202:203], off
	s_add_i32 m0, s22, 0x2000
	s_add_u32 s22, s26, 0x160080
	v_lshl_add_u64 v[202:203], v[218:219], 0, s[6:7]
	s_addc_u32 s23, s27, 0
	s_add_i32 s26, s60, s39
	global_load_lds_dwordx4 v[202:203], off
	v_lshl_add_u64 v[202:203], s[22:23], 0, v[130:131]
	s_mov_b32 m0, s26
	s_nop 0
	global_load_lds_dwordx4 v[202:203], off
	v_lshl_add_u64 v[202:203], s[22:23], 0, v[134:135]
	s_add_i32 m0, s26, 0x2000
	s_nop 0
	global_load_lds_dwordx4 v[202:203], off
	v_lshl_add_u64 v[202:203], v[220:221], 0, s[6:7]
	s_mov_b32 m0, s47
	s_nop 0
	global_load_lds_dwordx4 v[202:203], off
	v_lshl_add_u64 v[202:203], v[222:223], 0, s[6:7]
	s_mov_b32 m0, s48
	s_nop 0
	global_load_lds_dwordx4 v[202:203], off
	s_waitcnt vmcnt(8)
	s_waitcnt lgkmcnt(0)
	s_barrier
	s_setprio 1
	v_mfma_f32_16x16x32_bf16 v[60:63], v[144:147], v[182:185], v[60:63]
	v_mfma_f32_16x16x32_bf16 v[56:59], v[158:161], v[182:185], v[56:59]
	v_mfma_f32_16x16x32_bf16 v[52:55], v[144:147], v[190:193], v[52:55]
	v_mfma_f32_16x16x32_bf16 v[48:51], v[158:161], v[190:193], v[48:51]
	v_mfma_f32_16x16x32_bf16 v[28:31], v[144:147], v[198:201], v[28:31]
	v_mfma_f32_16x16x32_bf16 v[24:27], v[158:161], v[198:201], v[24:27]
	v_mfma_f32_16x16x32_bf16 v[20:23], v[144:147], v[210:213], v[20:23]
	v_mfma_f32_16x16x32_bf16 v[16:19], v[158:161], v[210:213], v[16:19]
	v_mfma_f32_16x16x32_bf16 v[60:63], v[148:151], v[186:189], v[60:63]
	v_mfma_f32_16x16x32_bf16 v[56:59], v[162:165], v[186:189], v[56:59]
	v_mfma_f32_16x16x32_bf16 v[52:55], v[148:151], v[194:197], v[52:55]
	v_mfma_f32_16x16x32_bf16 v[48:51], v[162:165], v[194:197], v[48:51]
	v_mfma_f32_16x16x32_bf16 v[28:31], v[148:151], v[206:209], v[28:31]
	v_mfma_f32_16x16x32_bf16 v[24:27], v[162:165], v[206:209], v[24:27]
	v_mfma_f32_16x16x32_bf16 v[20:23], v[148:151], v[214:217], v[20:23]
	v_mfma_f32_16x16x32_bf16 v[16:19], v[162:165], v[214:217], v[16:19]
	v_mfma_f32_16x16x32_bf16 v[44:47], v[166:169], v[182:185], v[44:47]
	v_mfma_f32_16x16x32_bf16 v[40:43], v[174:177], v[182:185], v[40:43]
	v_mfma_f32_16x16x32_bf16 v[36:39], v[166:169], v[190:193], v[36:39]
	v_mfma_f32_16x16x32_bf16 v[32:35], v[174:177], v[190:193], v[32:35]
	v_mfma_f32_16x16x32_bf16 v[12:15], v[166:169], v[198:201], v[12:15]
	v_mfma_f32_16x16x32_bf16 v[8:11], v[174:177], v[198:201], v[8:11]
	v_mfma_f32_16x16x32_bf16 v[4:7], v[166:169], v[210:213], v[4:7]
	v_mfma_f32_16x16x32_bf16 v[0:3], v[174:177], v[210:213], v[0:3]
	v_mfma_f32_16x16x32_bf16 v[44:47], v[170:173], v[186:189], v[44:47]
	v_mfma_f32_16x16x32_bf16 v[40:43], v[178:181], v[186:189], v[40:43]
	v_mfma_f32_16x16x32_bf16 v[36:39], v[170:173], v[194:197], v[36:39]
	v_mfma_f32_16x16x32_bf16 v[32:35], v[178:181], v[194:197], v[32:35]
	v_mfma_f32_16x16x32_bf16 v[12:15], v[170:173], v[206:209], v[12:15]
	v_mfma_f32_16x16x32_bf16 v[8:11], v[178:181], v[206:209], v[8:11]
	v_mfma_f32_16x16x32_bf16 v[4:7], v[170:173], v[214:217], v[4:7]
	v_mfma_f32_16x16x32_bf16 v[0:3], v[178:181], v[214:217], v[0:3]
	s_setprio 0
	s_add_i32 s58, s58, 2
	s_add_u32 s56, s56, 0x100
	s_addc_u32 s57, s57, 0
	s_cmpk_gt_u32 s58, 0x55
	s_mov_b64 s[22:23], s[24:25]
	s_barrier
	s_cbranch_scc0 .LBB0_867
	s_and_b64 vcc, exec, s[8:9]
	s_cbranch_vccz .LBB0_870
	s_barrier

; #define PG8_STAGE(bufoff, gbase, voff) do { _Pragma("unroll") for (int _i = 0; _i < 2; ++_i) \
;         __builtin_amdgcn_global_load_lds((const unsigned*)((const char*)(gbase) + (voff)[_i]), (PG8_LAS unsigned*)(lds + (bufoff) + ldsw + _i * 8192), 16, 0, 0); } while (0)
; #define PG8_LDA(dst, b, h) do { _Pragma("unroll") for (int m = 0; m < 4; ++m) _Pragma("unroll") for (int k = 0; k < 2; ++k) dst[m][k] = *(const PG8_LAS bf16x8*)(lds + PG8_SA(b, h) + aoff + m * 2048 + k * 1024); } while (0)
; #define PG8_LDB(dst, b, h) do { _Pragma("unroll") for (int n = 0; n < 2; ++n) _Pragma("unroll") for (int k = 0; k < 2; ++k) dst[n][k] = *(const PG8_LAS bf16x8*)(lds + PG8_SB(b, h) + boff + n * 2048 + k * 1024); } while (0)
; template <class Epi, class Sched, bool ALIGN_EPI = false, bool SP2 = false>
; __device__ __forceinline__ void gemm_phase(PG8_LAS unsigned char* lds, const Gemm g, const Sched& S, const Epi& E, const int wv0) {
;     ...
;         for (int t = 0; t < nt; t += 2) {
;             const bool last = (t == nt - 2);
;             const char* a1 = cA + (size_t)(t + 1) * kstep;
;             const char* a2 = last ? nA : cA + (size_t)(t + 2) * kstep; const char* b2 = last ? nB : cB + (size_t)(t + 2) * kstep;
;             const char* a3 = a2 + kstep; const char* b3 = b2 + kstep;
;             if constexpr (SP2) {
;             PG8_LDB(B0, 0, 0); PG8_LDB(B1, 0, 1); PG8_SCHED; PG8_LDA(At, 0, 0); PG8_STAGE(PG8_SA(1, 1), a1 + hstepA, voffA);
;             PG8_WAIT_V(8); PG8_WAIT_L(0); PG8_BAR; PG8_MMA(0, 0, At, B0); PG8_MMA(0, 1, At, B1); PG8_BAR; PG8_SCHED;
;             PG8_LDA(At, 0, 1); PG8_STAGE(PG8_SB(0, 0), b2, voffB); PG8_STAGE(PG8_SB(0, 1), b2 + hstepB, voffB); PG8_STAGE(PG8_SA(0, 0), a2, voffA);
;             PG8_WAIT_V(8); PG8_WAIT_L(0); PG8_BAR; PG8_MMA(1, 0, At, B0); PG8_MMA(1, 1, At, B1); PG8_BAR; PG8_SCHED;
;             PG8_LDB(B0, 1, 0); PG8_LDB(B1, 1, 1); PG8_SCHED; PG8_LDA(At, 1, 0); PG8_STAGE(PG8_SA(0, 1), a2 + hstepA, voffA);
;             PG8_WAIT_V(8); PG8_WAIT_L(0); PG8_BAR; PG8_MMA(0, 0, At, B0); PG8_MMA(0, 1, At, B1); PG8_BAR; PG8_SCHED;
;             PG8_LDA(At, 1, 1); PG8_STAGE(PG8_SB(1, 0), b3, voffB); PG8_STAGE(PG8_SB(1, 1), b3 + hstepB, voffB); PG8_STAGE(PG8_SA(1, 0), a3, voffA);
;             PG8_WAIT_V(8); PG8_WAIT_L(0); PG8_BAR; PG8_MMA(1, 0, At, B0); PG8_MMA(1, 1, At, B1); PG8_BAR; PG8_SCHED;
.LBB0_1608:
	ds_read_b128 v[144:147], v155
	ds_read_b128 v[148:151], v155 offset:1024
	ds_read_b128 v[158:161], v155 offset:2048
	ds_read_b128 v[162:165], v155 offset:3072
	ds_read_b128 v[166:169], v156
	ds_read_b128 v[170:173], v156 offset:1024
	ds_read_b128 v[174:177], v156 offset:2048
	ds_read_b128 v[178:181], v156 offset:3072
	s_add_u32 s30, s28, 0xfff80080
	s_addc_u32 s31, s29, -1
	s_cmp_eq_u32 s56, 28
	s_cselect_b32 s35, s23, s31
	s_cselect_b32 s34, s22, s30
	s_cselect_b32 s31, s25, s21
	s_cselect_b32 s30, s24, s19
	v_lshl_add_u64 v[202:203], s[28:29], 0, v[138:139]
	s_add_i32 m0, s27, 0xc000
	ds_read_b128 v[182:185], v157
	ds_read_b128 v[186:189], v157 offset:1024
	ds_read_b128 v[190:193], v157 offset:2048
	ds_read_b128 v[194:197], v157 offset:3072
	ds_read_b128 v[198:201], v157 offset:4096
	ds_read_b128 v[206:209], v157 offset:5120
	ds_read_b128 v[210:213], v157 offset:6144
	ds_read_b128 v[214:217], v157 offset:7168
	global_load_lds_dwordx4 v[202:203], off
	v_lshl_add_u64 v[202:203], s[28:29], 0, v[136:137]
	s_add_i32 m0, s27, 0xe000
	s_nop 0
	global_load_lds_dwordx4 v[202:203], off
	s_waitcnt vmcnt(8)
	s_waitcnt lgkmcnt(0)
	s_barrier
	s_setprio 1
	v_mfma_f32_16x16x32_bf16 v[124:127], v[144:147], v[182:185], v[124:127]
	v_mfma_f32_16x16x32_bf16 v[120:123], v[158:161], v[182:185], v[120:123]
	v_mfma_f32_16x16x32_bf16 v[116:119], v[144:147], v[190:193], v[116:119]
	v_mfma_f32_16x16x32_bf16 v[112:115], v[158:161], v[190:193], v[112:115]
	v_mfma_f32_16x16x32_bf16 v[92:95], v[144:147], v[198:201], v[92:95]
	v_mfma_f32_16x16x32_bf16 v[88:91], v[158:161], v[198:201], v[88:91]
	v_mfma_f32_16x16x32_bf16 v[84:87], v[144:147], v[210:213], v[84:87]
	v_mfma_f32_16x16x32_bf16 v[80:83], v[158:161], v[210:213], v[80:83]
	v_mfma_f32_16x16x32_bf16 v[124:127], v[148:151], v[186:189], v[124:127]
	v_mfma_f32_16x16x32_bf16 v[120:123], v[162:165], v[186:189], v[120:123]
	v_mfma_f32_16x16x32_bf16 v[116:119], v[148:151], v[194:197], v[116:119]
	v_mfma_f32_16x16x32_bf16 v[112:115], v[162:165], v[194:197], v[112:115]
	v_mfma_f32_16x16x32_bf16 v[92:95], v[148:151], v[206:209], v[92:95]
	v_mfma_f32_16x16x32_bf16 v[88:91], v[162:165], v[206:209], v[88:91]
	v_mfma_f32_16x16x32_bf16 v[84:87], v[148:151], v[214:217], v[84:87]
	v_mfma_f32_16x16x32_bf16 v[80:83], v[162:165], v[214:217], v[80:83]
	v_mfma_f32_16x16x32_bf16 v[108:111], v[166:169], v[182:185], v[108:111]
	v_mfma_f32_16x16x32_bf16 v[104:107], v[174:177], v[182:185], v[104:107]
	v_mfma_f32_16x16x32_bf16 v[100:103], v[166:169], v[190:193], v[100:103]
	v_mfma_f32_16x16x32_bf16 v[96:99], v[174:177], v[190:193], v[96:99]
	v_mfma_f32_16x16x32_bf16 v[76:79], v[166:169], v[198:201], v[76:79]
	v_mfma_f32_16x16x32_bf16 v[72:75], v[174:177], v[198:201], v[72:75]
	v_mfma_f32_16x16x32_bf16 v[68:71], v[166:169], v[210:213], v[68:71]
	v_mfma_f32_16x16x32_bf16 v[64:67], v[174:177], v[210:213], v[64:67]
	v_mfma_f32_16x16x32_bf16 v[108:111], v[170:173], v[186:189], v[108:111]
	v_mfma_f32_16x16x32_bf16 v[104:107], v[178:181], v[186:189], v[104:107]
	v_mfma_f32_16x16x32_bf16 v[100:103], v[170:173], v[194:197], v[100:103]
	v_mfma_f32_16x16x32_bf16 v[96:99], v[178:181], v[194:197], v[96:99]
	v_mfma_f32_16x16x32_bf16 v[76:79], v[170:173], v[206:209], v[76:79]
	v_mfma_f32_16x16x32_bf16 v[72:75], v[178:181], v[206:209], v[72:75]
	v_mfma_f32_16x16x32_bf16 v[68:71], v[170:173], v[214:217], v[68:71]
	v_mfma_f32_16x16x32_bf16 v[64:67], v[178:181], v[214:217], v[64:67]
	s_setprio 0
	s_barrier
	s_add_i32 s57, s53, s45
	v_lshl_add_u64 v[202:203], s[30:31], 0, v[130:131]
	s_mov_b32 m0, s57
	ds_read_b128 v[182:185], v157 offset:16384
	ds_read_b128 v[186:189], v157 offset:17408
	ds_read_b128 v[190:193], v157 offset:18432
	ds_read_b128 v[194:197], v157 offset:19456
	ds_read_b128 v[198:201], v157 offset:20480
	ds_read_b128 v[206:209], v157 offset:21504
	ds_read_b128 v[210:213], v157 offset:22528
	ds_read_b128 v[214:217], v157 offset:23552
	global_load_lds_dwordx4 v[202:203], off
	s_add_i32 m0, s57, 0x2000
	s_add_u32 s58, s30, 0x80000
	v_lshl_add_u64 v[218:219], s[30:31], 0, v[134:135]
	s_addc_u32 s59, s31, 0
	s_add_i32 s57, s54, s45
	global_load_lds_dwordx4 v[218:219], off
	v_lshl_add_u64 v[220:221], s[58:59], 0, v[130:131]
	s_mov_b32 m0, s57
	v_lshl_add_u64 v[222:223], s[34:35], 0, v[132:133]
	global_load_lds_dwordx4 v[220:221], off
	v_lshl_add_u64 v[220:221], s[58:59], 0, v[134:135]
	s_add_i32 m0, s57, 0x2000
	s_nop 0
	global_load_lds_dwordx4 v[220:221], off
	v_lshl_add_u64 v[220:221], s[34:35], 0, v[128:129]
	s_mov_b32 m0, s27
	s_nop 0
	global_load_lds_dwordx4 v[220:221], off
	s_mov_b32 m0, s46
	s_nop 0
	global_load_lds_dwordx4 v[222:223], off
	s_waitcnt vmcnt(8)
	s_waitcnt lgkmcnt(0)
	s_barrier
; #define PG8_STAGE(bufoff, gbase, voff) do { _Pragma("unroll") for (int _i = 0; _i < 2; ++_i) \
;         __builtin_amdgcn_global_load_lds((const unsigned*)((const char*)(gbase) + (voff)[_i]), (PG8_LAS unsigned*)(lds + (bufoff) + ldsw + _i * 8192), 16, 0, 0); } while (0)
; #define PG8_LDA(dst, b, h) do { _Pragma("unroll") for (int m = 0; m < 4; ++m) _Pragma("unroll") for (int k = 0; k < 2; ++k) dst[m][k] = *(const PG8_LAS bf16x8*)(lds + PG8_SA(b, h) + aoff + m * 2048 + k * 1024); } while (0)
; #define PG8_LDB(dst, b, h) do { _Pragma("unroll") for (int n = 0; n < 2; ++n) _Pragma("unroll") for (int k = 0; k < 2; ++k) dst[n][k] = *(const PG8_LAS bf16x8*)(lds + PG8_SB(b, h) + boff + n * 2048 + k * 1024); } while (0)
; #define PG8_MMA(ai, bj, At, Bt) do { __builtin_amdgcn_s_setprio(1); _Pragma("unroll") for (int m = 0; m < 4; ++m) _Pragma("unroll") for (int n = 0; n < 2; ++n) _Pragma("unroll") for (int k = 0; k < 2; ++k) \
;         acc[ai][bj][m][n] = __builtin_amdgcn_mfma_f32_16x16x32_bf16(Bt[n][k], At[m][k], acc[ai][bj][m][n], 0, 0, 0); __builtin_amdgcn_s_setprio(0); } while (0)
; #define PG8_WAIT_V(n) asm volatile("s_waitcnt vmcnt(" #n ")" ::: "memory")
; #define PG8_WAIT_L(n) asm volatile("s_waitcnt lgkmcnt(" #n ")" ::: "memory")
; #define PG8_BAR __builtin_amdgcn_s_barrier()
; #define PG8_SCHED __builtin_amdgcn_sched_barrier(0)
; template <class Epi, class Sched, bool ALIGN_EPI = false, bool SP2 = false>
; __device__ __forceinline__ void gemm_phase(PG8_LAS unsigned char* lds, const Gemm g, const Sched& S, const Epi& E, const int wv0) {
;     ...
;             PG8_WAIT_V(8); PG8_WAIT_L(0); PG8_BAR; PG8_MMA(1, 0, At, B0); PG8_MMA(1, 1, At, B1); PG8_BAR; PG8_SCHED;
;             PG8_LDB(B0, 1, 0); PG8_LDB(B1, 1, 1); PG8_SCHED; PG8_LDA(At, 1, 0); PG8_STAGE(PG8_SA(0, 1), a2 + hstepA, voffA);
;             PG8_WAIT_V(8); PG8_WAIT_L(0); PG8_BAR; PG8_MMA(0, 0, At, B0); PG8_MMA(0, 1, At, B1); PG8_BAR; PG8_SCHED;
	s_setprio 1
	v_mfma_f32_16x16x32_bf16 v[60:63], v[144:147], v[182:185], v[60:63]
	v_mfma_f32_16x16x32_bf16 v[56:59], v[158:161], v[182:185], v[56:59]
	v_mfma_f32_16x16x32_bf16 v[52:55], v[144:147], v[190:193], v[52:55]
	v_mfma_f32_16x16x32_bf16 v[48:51], v[158:161], v[190:193], v[48:51]
	v_mfma_f32_16x16x32_bf16 v[28:31], v[144:147], v[198:201], v[28:31]
	v_mfma_f32_16x16x32_bf16 v[24:27], v[158:161], v[198:201], v[24:27]
	v_mfma_f32_16x16x32_bf16 v[20:23], v[144:147], v[210:213], v[20:23]
	v_mfma_f32_16x16x32_bf16 v[16:19], v[158:161], v[210:213], v[16:19]
	v_mfma_f32_16x16x32_bf16 v[60:63], v[148:151], v[186:189], v[60:63]
	v_mfma_f32_16x16x32_bf16 v[56:59], v[162:165], v[186:189], v[56:59]
	v_mfma_f32_16x16x32_bf16 v[52:55], v[148:151], v[194:197], v[52:55]
	v_mfma_f32_16x16x32_bf16 v[48:51], v[162:165], v[194:197], v[48:51]
	v_mfma_f32_16x16x32_bf16 v[28:31], v[148:151], v[206:209], v[28:31]
	v_mfma_f32_16x16x32_bf16 v[24:27], v[162:165], v[206:209], v[24:27]
	v_mfma_f32_16x16x32_bf16 v[20:23], v[148:151], v[214:217], v[20:23]
	v_mfma_f32_16x16x32_bf16 v[16:19], v[162:165], v[214:217], v[16:19]
	v_mfma_f32_16x16x32_bf16 v[44:47], v[166:169], v[182:185], v[44:47]
	v_mfma_f32_16x16x32_bf16 v[40:43], v[174:177], v[182:185], v[40:43]
	v_mfma_f32_16x16x32_bf16 v[36:39], v[166:169], v[190:193], v[36:39]
	v_mfma_f32_16x16x32_bf16 v[32:35], v[174:177], v[190:193], v[32:35]
	v_mfma_f32_16x16x32_bf16 v[12:15], v[166:169], v[198:201], v[12:15]
	v_mfma_f32_16x16x32_bf16 v[8:11], v[174:177], v[198:201], v[8:11]
	v_mfma_f32_16x16x32_bf16 v[4:7], v[166:169], v[210:213], v[4:7]
	v_mfma_f32_16x16x32_bf16 v[0:3], v[174:177], v[210:213], v[0:3]
	v_mfma_f32_16x16x32_bf16 v[44:47], v[170:173], v[186:189], v[44:47]
	v_mfma_f32_16x16x32_bf16 v[40:43], v[178:181], v[186:189], v[40:43]
	v_mfma_f32_16x16x32_bf16 v[36:39], v[170:173], v[194:197], v[36:39]
	v_mfma_f32_16x16x32_bf16 v[32:35], v[178:181], v[194:197], v[32:35]
	v_mfma_f32_16x16x32_bf16 v[12:15], v[170:173], v[206:209], v[12:15]
	v_mfma_f32_16x16x32_bf16 v[8:11], v[178:181], v[206:209], v[8:11]
	v_mfma_f32_16x16x32_bf16 v[4:7], v[170:173], v[214:217], v[4:7]
	v_mfma_f32_16x16x32_bf16 v[0:3], v[178:181], v[214:217], v[0:3]
	s_setprio 0
	s_barrier
	s_add_i32 s57, 0, 0x18000
	s_add_i32 s58, 0, 0x1c000
	v_add_u32_e32 v162, s57, v153
	v_add_u32_e32 v178, s58, v153
	ds_read_b128 v[144:147], v162
	ds_read_b128 v[148:151], v162 offset:1024
	ds_read_b128 v[158:161], v162 offset:2048
	ds_read_b128 v[162:165], v162 offset:3072
	ds_read_b128 v[166:169], v178
	ds_read_b128 v[170:173], v178 offset:1024
	ds_read_b128 v[174:177], v178 offset:2048
	ds_read_b128 v[178:181], v178 offset:3072
	s_add_u32 s34, s34, 0x80000
	s_addc_u32 s35, s35, 0
	s_mov_b32 m0, s47
	v_lshl_add_u64 v[224:225], s[34:35], 0, v[128:129]
	ds_read_b128 v[182:185], v157 offset:32768
	ds_read_b128 v[186:189], v157 offset:33792
	ds_read_b128 v[190:193], v157 offset:34816
	ds_read_b128 v[194:197], v157 offset:35840
	ds_read_b128 v[198:201], v157 offset:36864
	ds_read_b128 v[206:209], v157 offset:37888
	ds_read_b128 v[210:213], v157 offset:38912
	ds_read_b128 v[214:217], v157 offset:39936
	global_load_lds_dwordx4 v[224:225], off
	v_lshl_add_u64 v[224:225], s[34:35], 0, v[132:133]
	s_mov_b32 m0, s48
	s_nop 0
	global_load_lds_dwordx4 v[224:225], off
	s_waitcnt vmcnt(8)
	s_waitcnt lgkmcnt(0)
	s_barrier
	s_setprio 1
	v_mfma_f32_16x16x32_bf16 v[124:127], v[144:147], v[182:185], v[124:127]
	v_mfma_f32_16x16x32_bf16 v[120:123], v[158:161], v[182:185], v[120:123]
	v_mfma_f32_16x16x32_bf16 v[116:119], v[144:147], v[190:193], v[116:119]
	v_mfma_f32_16x16x32_bf16 v[112:115], v[158:161], v[190:193], v[112:115]
	v_mfma_f32_16x16x32_bf16 v[92:95], v[144:147], v[198:201], v[92:95]
	v_mfma_f32_16x16x32_bf16 v[88:91], v[158:161], v[198:201], v[88:91]
	v_mfma_f32_16x16x32_bf16 v[84:87], v[144:147], v[210:213], v[84:87]
	v_mfma_f32_16x16x32_bf16 v[80:83], v[158:161], v[210:213], v[80:83]
	v_mfma_f32_16x16x32_bf16 v[124:127], v[148:151], v[186:189], v[124:127]
	v_mfma_f32_16x16x32_bf16 v[120:123], v[162:165], v[186:189], v[120:123]
	v_mfma_f32_16x16x32_bf16 v[116:119], v[148:151], v[194:197], v[116:119]
	v_mfma_f32_16x16x32_bf16 v[112:115], v[162:165], v[194:197], v[112:115]
	v_mfma_f32_16x16x32_bf16 v[92:95], v[148:151], v[206:209], v[92:95]
	v_mfma_f32_16x16x32_bf16 v[88:91], v[162:165], v[206:209], v[88:91]
	v_mfma_f32_16x16x32_bf16 v[84:87], v[148:151], v[214:217], v[84:87]
	v_mfma_f32_16x16x32_bf16 v[80:83], v[162:165], v[214:217], v[80:83]
	v_mfma_f32_16x16x32_bf16 v[108:111], v[166:169], v[182:185], v[108:111]
	v_mfma_f32_16x16x32_bf16 v[104:107], v[174:177], v[182:185], v[104:107]
	v_mfma_f32_16x16x32_bf16 v[100:103], v[166:169], v[190:193], v[100:103]
	v_mfma_f32_16x16x32_bf16 v[96:99], v[174:177], v[190:193], v[96:99]
	v_mfma_f32_16x16x32_bf16 v[76:79], v[166:169], v[198:201], v[76:79]
	v_mfma_f32_16x16x32_bf16 v[72:75], v[174:177], v[198:201], v[72:75]
	v_mfma_f32_16x16x32_bf16 v[68:71], v[166:169], v[210:213], v[68:71]
	v_mfma_f32_16x16x32_bf16 v[64:67], v[174:177], v[210:213], v[64:67]
	v_mfma_f32_16x16x32_bf16 v[108:111], v[170:173], v[186:189], v[108:111]
	v_mfma_f32_16x16x32_bf16 v[104:107], v[178:181], v[186:189], v[104:107]
	v_mfma_f32_16x16x32_bf16 v[100:103], v[170:173], v[194:197], v[100:103]
	v_mfma_f32_16x16x32_bf16 v[96:99], v[178:181], v[194:197], v[96:99]
	v_mfma_f32_16x16x32_bf16 v[76:79], v[170:173], v[206:209], v[76:79]
	v_mfma_f32_16x16x32_bf16 v[72:75], v[178:181], v[206:209], v[72:75]
	v_mfma_f32_16x16x32_bf16 v[68:71], v[170:173], v[214:217], v[68:71]
	v_mfma_f32_16x16x32_bf16 v[64:67], v[178:181], v[214:217], v[64:67]
	s_setprio 0
	s_barrier
; #define PG8_STAGE(bufoff, gbase, voff) do { _Pragma("unroll") for (int _i = 0; _i < 2; ++_i) \
;         __builtin_amdgcn_global_load_lds((const unsigned*)((const char*)(gbase) + (voff)[_i]), (PG8_LAS unsigned*)(lds + (bufoff) + ldsw + _i * 8192), 16, 0, 0); } while (0)
; #define PG8_LDA(dst, b, h) do { _Pragma("unroll") for (int m = 0; m < 4; ++m) _Pragma("unroll") for (int k = 0; k < 2; ++k) dst[m][k] = *(const PG8_LAS bf16x8*)(lds + PG8_SA(b, h) + aoff + m * 2048 + k * 1024); } while (0)
; #define PG8_MMA(ai, bj, At, Bt) do { __builtin_amdgcn_s_setprio(1); _Pragma("unroll") for (int m = 0; m < 4; ++m) _Pragma("unroll") for (int n = 0; n < 2; ++n) _Pragma("unroll") for (int k = 0; k < 2; ++k) \
;         acc[ai][bj][m][n] = __builtin_amdgcn_mfma_f32_16x16x32_bf16(Bt[n][k], At[m][k], acc[ai][bj][m][n], 0, 0, 0); __builtin_amdgcn_s_setprio(0); } while (0)
; #define PG8_WAIT_V(n) asm volatile("s_waitcnt vmcnt(" #n ")" ::: "memory")
; #define PG8_WAIT_L(n) asm volatile("s_waitcnt lgkmcnt(" #n ")" ::: "memory")
; #define PG8_BAR __builtin_amdgcn_s_barrier()
; #define PG8_SCHED __builtin_amdgcn_sched_barrier(0)
; template <class Epi, class Sched, bool ALIGN_EPI = false, bool SP2 = false>
; __device__ __forceinline__ void gemm_phase(PG8_LAS unsigned char* lds, const Gemm g, const Sched& S, const Epi& E, const int wv0) {
;     ...
;         for (int t = 0; t < nt; t += 2) {
;             const bool last = (t == nt - 2);
;     ...
;             PG8_LDA(At, 1, 1); PG8_STAGE(PG8_SB(1, 0), b3, voffB); PG8_STAGE(PG8_SB(1, 1), b3 + hstepB, voffB); PG8_STAGE(PG8_SA(1, 0), a3, voffA);
;             PG8_WAIT_V(8); PG8_WAIT_L(0); PG8_BAR; PG8_MMA(1, 0, At, B0); PG8_MMA(1, 1, At, B1); PG8_BAR; PG8_SCHED;
	s_add_i32 s34, s57, s45
	v_lshl_add_u64 v[202:203], v[202:203], 0, s[8:9]
	s_mov_b32 m0, s34
	ds_read_b128 v[182:185], v157 offset:49152
	ds_read_b128 v[186:189], v157 offset:50176
	ds_read_b128 v[190:193], v157 offset:51200
	ds_read_b128 v[194:197], v157 offset:52224
	ds_read_b128 v[198:201], v157 offset:53248
	ds_read_b128 v[206:209], v157 offset:54272
	ds_read_b128 v[210:213], v157 offset:55296
	ds_read_b128 v[214:217], v157 offset:56320
	global_load_lds_dwordx4 v[202:203], off
	s_add_i32 m0, s34, 0x2000
	s_add_u32 s30, s30, 0x80080
	v_lshl_add_u64 v[202:203], v[218:219], 0, s[8:9]
	s_addc_u32 s31, s31, 0
	s_add_i32 s34, s58, s45
	global_load_lds_dwordx4 v[202:203], off
	v_lshl_add_u64 v[202:203], s[30:31], 0, v[130:131]
	s_mov_b32 m0, s34
	s_nop 0
	global_load_lds_dwordx4 v[202:203], off
	v_lshl_add_u64 v[202:203], s[30:31], 0, v[134:135]
	s_add_i32 m0, s34, 0x2000
	s_nop 0
	global_load_lds_dwordx4 v[202:203], off
	v_lshl_add_u64 v[202:203], v[220:221], 0, s[8:9]
	s_mov_b32 m0, s50
	s_nop 0
	global_load_lds_dwordx4 v[202:203], off
	v_lshl_add_u64 v[202:203], v[222:223], 0, s[8:9]
	s_mov_b32 m0, s51
	s_nop 0
	global_load_lds_dwordx4 v[202:203], off
	s_waitcnt vmcnt(8)
	s_waitcnt lgkmcnt(0)
	s_barrier
	s_setprio 1
	v_mfma_f32_16x16x32_bf16 v[60:63], v[144:147], v[182:185], v[60:63]
	v_mfma_f32_16x16x32_bf16 v[56:59], v[158:161], v[182:185], v[56:59]
	v_mfma_f32_16x16x32_bf16 v[52:55], v[144:147], v[190:193], v[52:55]
	v_mfma_f32_16x16x32_bf16 v[48:51], v[158:161], v[190:193], v[48:51]
	v_mfma_f32_16x16x32_bf16 v[28:31], v[144:147], v[198:201], v[28:31]
	v_mfma_f32_16x16x32_bf16 v[24:27], v[158:161], v[198:201], v[24:27]
	v_mfma_f32_16x16x32_bf16 v[20:23], v[144:147], v[210:213], v[20:23]
	v_mfma_f32_16x16x32_bf16 v[16:19], v[158:161], v[210:213], v[16:19]
	v_mfma_f32_16x16x32_bf16 v[60:63], v[148:151], v[186:189], v[60:63]
	v_mfma_f32_16x16x32_bf16 v[56:59], v[162:165], v[186:189], v[56:59]
	v_mfma_f32_16x16x32_bf16 v[52:55], v[148:151], v[194:197], v[52:55]
	v_mfma_f32_16x16x32_bf16 v[48:51], v[162:165], v[194:197], v[48:51]
	v_mfma_f32_16x16x32_bf16 v[28:31], v[148:151], v[206:209], v[28:31]
	v_mfma_f32_16x16x32_bf16 v[24:27], v[162:165], v[206:209], v[24:27]
	v_mfma_f32_16x16x32_bf16 v[20:23], v[148:151], v[214:217], v[20:23]
	v_mfma_f32_16x16x32_bf16 v[16:19], v[162:165], v[214:217], v[16:19]
	v_mfma_f32_16x16x32_bf16 v[44:47], v[166:169], v[182:185], v[44:47]
	v_mfma_f32_16x16x32_bf16 v[40:43], v[174:177], v[182:185], v[40:43]
	v_mfma_f32_16x16x32_bf16 v[36:39], v[166:169], v[190:193], v[36:39]
	v_mfma_f32_16x16x32_bf16 v[32:35], v[174:177], v[190:193], v[32:35]
	v_mfma_f32_16x16x32_bf16 v[12:15], v[166:169], v[198:201], v[12:15]
	v_mfma_f32_16x16x32_bf16 v[8:11], v[174:177], v[198:201], v[8:11]
	v_mfma_f32_16x16x32_bf16 v[4:7], v[166:169], v[210:213], v[4:7]
	v_mfma_f32_16x16x32_bf16 v[0:3], v[174:177], v[210:213], v[0:3]
	v_mfma_f32_16x16x32_bf16 v[44:47], v[170:173], v[186:189], v[44:47]
	v_mfma_f32_16x16x32_bf16 v[40:43], v[178:181], v[186:189], v[40:43]
	v_mfma_f32_16x16x32_bf16 v[36:39], v[170:173], v[194:197], v[36:39]
	v_mfma_f32_16x16x32_bf16 v[32:35], v[178:181], v[194:197], v[32:35]
	v_mfma_f32_16x16x32_bf16 v[12:15], v[170:173], v[206:209], v[12:15]
	v_mfma_f32_16x16x32_bf16 v[8:11], v[178:181], v[206:209], v[8:11]
	v_mfma_f32_16x16x32_bf16 v[4:7], v[170:173], v[214:217], v[4:7]
	v_mfma_f32_16x16x32_bf16 v[0:3], v[178:181], v[214:217], v[0:3]
	s_setprio 0
	s_add_i32 s56, s56, 2
	s_add_u32 s19, s19, 0x100
	s_addc_u32 s21, s21, 0
	s_add_u32 s28, s28, 0x100
	s_addc_u32 s29, s29, 0
	s_cmp_gt_u32 s56, 29
	s_barrier
	s_cbranch_scc0 .LBB0_1608
	s_and_b64 vcc, exec, s[10:11]
	s_cbranch_vccz .LBB0_1611
	s_barrier

; #define PG8_STAGE(bufoff, gbase, voff) do { _Pragma("unroll") for (int _i = 0; _i < 2; ++_i) \
;         __builtin_amdgcn_global_load_lds((const unsigned*)((const char*)(gbase) + (voff)[_i]), (PG8_LAS unsigned*)(lds + (bufoff) + ldsw + _i * 8192), 16, 0, 0); } while (0)
; #define PG8_LDA(dst, b, h) do { _Pragma("unroll") for (int m = 0; m < 4; ++m) _Pragma("unroll") for (int k = 0; k < 2; ++k) dst[m][k] = *(const PG8_LAS bf16x8*)(lds + PG8_SA(b, h) + aoff + m * 2048 + k * 1024); } while (0)
; #define PG8_LDB(dst, b, h) do { _Pragma("unroll") for (int n = 0; n < 2; ++n) _Pragma("unroll") for (int k = 0; k < 2; ++k) dst[n][k] = *(const PG8_LAS bf16x8*)(lds + PG8_SB(b, h) + boff + n * 2048 + k * 1024); } while (0)
; template <class Epi, class Sched, bool ALIGN_EPI = false, bool SP2 = false>
; __device__ __forceinline__ void gemm_phase(PG8_LAS unsigned char* lds, const Gemm g, const Sched& S, const Epi& E, const int wv0) {
;     ...
;         for (int t = 0; t < nt; t += 2) {
;             const bool last = (t == nt - 2);
;             const char* a1 = cA + (size_t)(t + 1) * kstep;
;             const char* a2 = last ? nA : cA + (size_t)(t + 2) * kstep; const char* b2 = last ? nB : cB + (size_t)(t + 2) * kstep;
;             const char* a3 = a2 + kstep; const char* b3 = b2 + kstep;
;             if constexpr (SP2) {
;             PG8_LDB(B0, 0, 0); PG8_LDB(B1, 0, 1); PG8_SCHED; PG8_LDA(At, 0, 0); PG8_STAGE(PG8_SA(1, 1), a1 + hstepA, voffA);
;             PG8_WAIT_V(8); PG8_WAIT_L(0); PG8_BAR; PG8_MMA(0, 0, At, B0); PG8_MMA(0, 1, At, B1); PG8_BAR; PG8_SCHED;
;             PG8_LDA(At, 0, 1); PG8_STAGE(PG8_SB(0, 0), b2, voffB); PG8_STAGE(PG8_SB(0, 1), b2 + hstepB, voffB); PG8_STAGE(PG8_SA(0, 0), a2, voffA);
;             PG8_WAIT_V(8); PG8_WAIT_L(0); PG8_BAR; PG8_MMA(1, 0, At, B0); PG8_MMA(1, 1, At, B1); PG8_BAR; PG8_SCHED;
;             PG8_LDB(B0, 1, 0); PG8_LDB(B1, 1, 1); PG8_SCHED; PG8_LDA(At, 1, 0); PG8_STAGE(PG8_SA(0, 1), a2 + hstepA, voffA);
;             PG8_WAIT_V(8); PG8_WAIT_L(0); PG8_BAR; PG8_MMA(0, 0, At, B0); PG8_MMA(0, 1, At, B1); PG8_BAR; PG8_SCHED;
;             PG8_LDA(At, 1, 1); PG8_STAGE(PG8_SB(1, 0), b3, voffB); PG8_STAGE(PG8_SB(1, 1), b3 + hstepB, voffB); PG8_STAGE(PG8_SA(1, 0), a3, voffA);
;             PG8_WAIT_V(8); PG8_WAIT_L(0); PG8_BAR; PG8_MMA(1, 0, At, B0); PG8_MMA(1, 1, At, B1); PG8_BAR; PG8_SCHED;
.LBB0_1808:
	ds_read_b128 v[144:147], v153
	ds_read_b128 v[156:159], v153 offset:1024
	ds_read_b128 v[160:163], v153 offset:2048
	ds_read_b128 v[164:167], v153 offset:3072
	ds_read_b128 v[168:171], v154
	ds_read_b128 v[172:175], v154 offset:1024
	ds_read_b128 v[176:179], v154 offset:2048
	ds_read_b128 v[180:183], v154 offset:3072
	s_add_u32 s18, s16, 0x100
	s_addc_u32 s19, s17, 0
	s_cmpk_eq_i32 s48, 0x54
	s_cselect_b32 s23, s13, s19
	s_cselect_b32 s22, s12, s18
	s_cselect_b32 s21, s15, s47
	s_cselect_b32 s20, s14, s46
	v_lshl_add_u64 v[148:149], s[16:17], 0, v[138:139]
	s_add_i32 m0, s30, 0xc000
	ds_read_b128 v[184:187], v155
	ds_read_b128 v[188:191], v155 offset:1024
	ds_read_b128 v[192:195], v155 offset:2048
	ds_read_b128 v[196:199], v155 offset:3072
	ds_read_b128 v[200:203], v155 offset:4096
	ds_read_b128 v[204:207], v155 offset:5120
	ds_read_b128 v[208:211], v155 offset:6144
	ds_read_b128 v[212:215], v155 offset:7168
	global_load_lds_dwordx4 v[148:149], off
	v_lshl_add_u64 v[148:149], s[16:17], 0, v[136:137]
	s_add_i32 m0, s30, 0xe000
	s_nop 0
	global_load_lds_dwordx4 v[148:149], off
	s_waitcnt vmcnt(8)
	s_waitcnt lgkmcnt(0)
	s_barrier
	s_setprio 1
	v_mfma_f32_16x16x32_bf16 v[124:127], v[144:147], v[184:187], v[124:127]
	v_mfma_f32_16x16x32_bf16 v[120:123], v[160:163], v[184:187], v[120:123]
	v_mfma_f32_16x16x32_bf16 v[116:119], v[144:147], v[192:195], v[116:119]
	v_mfma_f32_16x16x32_bf16 v[112:115], v[160:163], v[192:195], v[112:115]
	v_mfma_f32_16x16x32_bf16 v[92:95], v[144:147], v[200:203], v[92:95]
	v_mfma_f32_16x16x32_bf16 v[88:91], v[160:163], v[200:203], v[88:91]
	v_mfma_f32_16x16x32_bf16 v[84:87], v[144:147], v[208:211], v[84:87]
	v_mfma_f32_16x16x32_bf16 v[80:83], v[160:163], v[208:211], v[80:83]
	v_mfma_f32_16x16x32_bf16 v[124:127], v[156:159], v[188:191], v[124:127]
	v_mfma_f32_16x16x32_bf16 v[120:123], v[164:167], v[188:191], v[120:123]
	v_mfma_f32_16x16x32_bf16 v[116:119], v[156:159], v[196:199], v[116:119]
	v_mfma_f32_16x16x32_bf16 v[112:115], v[164:167], v[196:199], v[112:115]
	v_mfma_f32_16x16x32_bf16 v[92:95], v[156:159], v[204:207], v[92:95]
	v_mfma_f32_16x16x32_bf16 v[88:91], v[164:167], v[204:207], v[88:91]
	v_mfma_f32_16x16x32_bf16 v[84:87], v[156:159], v[212:215], v[84:87]
	v_mfma_f32_16x16x32_bf16 v[80:83], v[164:167], v[212:215], v[80:83]
	v_mfma_f32_16x16x32_bf16 v[108:111], v[168:171], v[184:187], v[108:111]
	v_mfma_f32_16x16x32_bf16 v[104:107], v[176:179], v[184:187], v[104:107]
	v_mfma_f32_16x16x32_bf16 v[100:103], v[168:171], v[192:195], v[100:103]
	v_mfma_f32_16x16x32_bf16 v[96:99], v[176:179], v[192:195], v[96:99]
	v_mfma_f32_16x16x32_bf16 v[76:79], v[168:171], v[200:203], v[76:79]
	v_mfma_f32_16x16x32_bf16 v[72:75], v[176:179], v[200:203], v[72:75]
	v_mfma_f32_16x16x32_bf16 v[68:71], v[168:171], v[208:211], v[68:71]
	v_mfma_f32_16x16x32_bf16 v[64:67], v[176:179], v[208:211], v[64:67]
	v_mfma_f32_16x16x32_bf16 v[108:111], v[172:175], v[188:191], v[108:111]
	v_mfma_f32_16x16x32_bf16 v[104:107], v[180:183], v[188:191], v[104:107]
	v_mfma_f32_16x16x32_bf16 v[100:103], v[172:175], v[196:199], v[100:103]
	v_mfma_f32_16x16x32_bf16 v[96:99], v[180:183], v[196:199], v[96:99]
	v_mfma_f32_16x16x32_bf16 v[76:79], v[172:175], v[204:207], v[76:79]
	v_mfma_f32_16x16x32_bf16 v[72:75], v[180:183], v[204:207], v[72:75]
	v_mfma_f32_16x16x32_bf16 v[68:71], v[172:175], v[212:215], v[68:71]
	v_mfma_f32_16x16x32_bf16 v[64:67], v[180:183], v[212:215], v[64:67]
	s_setprio 0
	s_barrier
	s_add_i32 s16, s40, s29
	v_lshl_add_u64 v[148:149], s[20:21], 0, v[130:131]
	s_mov_b32 m0, s16
	ds_read_b128 v[184:187], v155 offset:16384
	ds_read_b128 v[188:191], v155 offset:17408
	ds_read_b128 v[192:195], v155 offset:18432
	ds_read_b128 v[196:199], v155 offset:19456
	ds_read_b128 v[200:203], v155 offset:20480
	ds_read_b128 v[204:207], v155 offset:21504
	ds_read_b128 v[208:211], v155 offset:22528
	ds_read_b128 v[212:215], v155 offset:23552
	global_load_lds_dwordx4 v[148:149], off
	s_add_i32 m0, s16, 0x2000
	s_add_u32 s16, s20, 0x160000
	v_lshl_add_u64 v[216:217], s[20:21], 0, v[134:135]
	s_addc_u32 s17, s21, 0
	s_add_i32 s49, s41, s29
	global_load_lds_dwordx4 v[216:217], off
	v_lshl_add_u64 v[218:219], s[16:17], 0, v[130:131]
	s_mov_b32 m0, s49
	v_lshl_add_u64 v[220:221], s[22:23], 0, v[132:133]
	global_load_lds_dwordx4 v[218:219], off
	v_lshl_add_u64 v[218:219], s[16:17], 0, v[134:135]
	s_add_i32 m0, s49, 0x2000
	s_nop 0
	global_load_lds_dwordx4 v[218:219], off
	v_lshl_add_u64 v[218:219], s[22:23], 0, v[128:129]
	s_mov_b32 m0, s30
	s_nop 0
	global_load_lds_dwordx4 v[218:219], off
	s_mov_b32 m0, s31
	s_nop 0
	global_load_lds_dwordx4 v[220:221], off
	s_waitcnt vmcnt(8)
	s_waitcnt lgkmcnt(0)
	s_barrier
; #define PG8_STAGE(bufoff, gbase, voff) do { _Pragma("unroll") for (int _i = 0; _i < 2; ++_i) \
;         __builtin_amdgcn_global_load_lds((const unsigned*)((const char*)(gbase) + (voff)[_i]), (PG8_LAS unsigned*)(lds + (bufoff) + ldsw + _i * 8192), 16, 0, 0); } while (0)
; #define PG8_LDA(dst, b, h) do { _Pragma("unroll") for (int m = 0; m < 4; ++m) _Pragma("unroll") for (int k = 0; k < 2; ++k) dst[m][k] = *(const PG8_LAS bf16x8*)(lds + PG8_SA(b, h) + aoff + m * 2048 + k * 1024); } while (0)
; #define PG8_LDB(dst, b, h) do { _Pragma("unroll") for (int n = 0; n < 2; ++n) _Pragma("unroll") for (int k = 0; k < 2; ++k) dst[n][k] = *(const PG8_LAS bf16x8*)(lds + PG8_SB(b, h) + boff + n * 2048 + k * 1024); } while (0)
; #define PG8_MMA(ai, bj, At, Bt) do { __builtin_amdgcn_s_setprio(1); _Pragma("unroll") for (int m = 0; m < 4; ++m) _Pragma("unroll") for (int n = 0; n < 2; ++n) _Pragma("unroll") for (int k = 0; k < 2; ++k) \
;         acc[ai][bj][m][n] = __builtin_amdgcn_mfma_f32_16x16x32_bf16(Bt[n][k], At[m][k], acc[ai][bj][m][n], 0, 0, 0); __builtin_amdgcn_s_setprio(0); } while (0)
; #define PG8_WAIT_V(n) asm volatile("s_waitcnt vmcnt(" #n ")" ::: "memory")
; #define PG8_WAIT_L(n) asm volatile("s_waitcnt lgkmcnt(" #n ")" ::: "memory")
; #define PG8_BAR __builtin_amdgcn_s_barrier()
; #define PG8_SCHED __builtin_amdgcn_sched_barrier(0)
; template <class Epi, class Sched, bool ALIGN_EPI = false, bool SP2 = false>
; __device__ __forceinline__ void gemm_phase(PG8_LAS unsigned char* lds, const Gemm g, const Sched& S, const Epi& E, const int wv0) {
;     ...
;             PG8_WAIT_V(8); PG8_WAIT_L(0); PG8_BAR; PG8_MMA(1, 0, At, B0); PG8_MMA(1, 1, At, B1); PG8_BAR; PG8_SCHED;
;             PG8_LDB(B0, 1, 0); PG8_LDB(B1, 1, 1); PG8_SCHED; PG8_LDA(At, 1, 0); PG8_STAGE(PG8_SA(0, 1), a2 + hstepA, voffA);
;             PG8_WAIT_V(8); PG8_WAIT_L(0); PG8_BAR; PG8_MMA(0, 0, At, B0); PG8_MMA(0, 1, At, B1); PG8_BAR; PG8_SCHED;
	s_setprio 1
	v_mfma_f32_16x16x32_bf16 v[60:63], v[144:147], v[184:187], v[60:63]
	v_mfma_f32_16x16x32_bf16 v[56:59], v[160:163], v[184:187], v[56:59]
	v_mfma_f32_16x16x32_bf16 v[52:55], v[144:147], v[192:195], v[52:55]
	v_mfma_f32_16x16x32_bf16 v[48:51], v[160:163], v[192:195], v[48:51]
	v_mfma_f32_16x16x32_bf16 v[28:31], v[144:147], v[200:203], v[28:31]
	v_mfma_f32_16x16x32_bf16 v[24:27], v[160:163], v[200:203], v[24:27]
	v_mfma_f32_16x16x32_bf16 v[20:23], v[144:147], v[208:211], v[20:23]
	v_mfma_f32_16x16x32_bf16 v[16:19], v[160:163], v[208:211], v[16:19]
	v_mfma_f32_16x16x32_bf16 v[60:63], v[156:159], v[188:191], v[60:63]
	v_mfma_f32_16x16x32_bf16 v[56:59], v[164:167], v[188:191], v[56:59]
	v_mfma_f32_16x16x32_bf16 v[52:55], v[156:159], v[196:199], v[52:55]
	v_mfma_f32_16x16x32_bf16 v[48:51], v[164:167], v[196:199], v[48:51]
	v_mfma_f32_16x16x32_bf16 v[28:31], v[156:159], v[204:207], v[28:31]
	v_mfma_f32_16x16x32_bf16 v[24:27], v[164:167], v[204:207], v[24:27]
	v_mfma_f32_16x16x32_bf16 v[20:23], v[156:159], v[212:215], v[20:23]
	v_mfma_f32_16x16x32_bf16 v[16:19], v[164:167], v[212:215], v[16:19]
	v_mfma_f32_16x16x32_bf16 v[44:47], v[168:171], v[184:187], v[44:47]
	v_mfma_f32_16x16x32_bf16 v[40:43], v[176:179], v[184:187], v[40:43]
	v_mfma_f32_16x16x32_bf16 v[36:39], v[168:171], v[192:195], v[36:39]
	v_mfma_f32_16x16x32_bf16 v[32:35], v[176:179], v[192:195], v[32:35]
	v_mfma_f32_16x16x32_bf16 v[12:15], v[168:171], v[200:203], v[12:15]
	v_mfma_f32_16x16x32_bf16 v[8:11], v[176:179], v[200:203], v[8:11]
	v_mfma_f32_16x16x32_bf16 v[4:7], v[168:171], v[208:211], v[4:7]
	v_mfma_f32_16x16x32_bf16 v[0:3], v[176:179], v[208:211], v[0:3]
	v_mfma_f32_16x16x32_bf16 v[44:47], v[172:175], v[188:191], v[44:47]
	v_mfma_f32_16x16x32_bf16 v[40:43], v[180:183], v[188:191], v[40:43]
	v_mfma_f32_16x16x32_bf16 v[36:39], v[172:175], v[196:199], v[36:39]
	v_mfma_f32_16x16x32_bf16 v[32:35], v[180:183], v[196:199], v[32:35]
	v_mfma_f32_16x16x32_bf16 v[12:15], v[172:175], v[204:207], v[12:15]
	v_mfma_f32_16x16x32_bf16 v[8:11], v[180:183], v[204:207], v[8:11]
	v_mfma_f32_16x16x32_bf16 v[4:7], v[172:175], v[212:215], v[4:7]
	v_mfma_f32_16x16x32_bf16 v[0:3], v[180:183], v[212:215], v[0:3]
	s_setprio 0
	s_barrier
	s_add_i32 s49, 0, 0x18000
	s_add_i32 s50, 0, 0x1c000
	v_add_u32_e32 v164, s49, v151
	v_add_u32_e32 v180, s50, v151
	ds_read_b128 v[144:147], v164
	ds_read_b128 v[156:159], v164 offset:1024
	ds_read_b128 v[160:163], v164 offset:2048
	ds_read_b128 v[164:167], v164 offset:3072
	ds_read_b128 v[168:171], v180
	ds_read_b128 v[172:175], v180 offset:1024
	ds_read_b128 v[176:179], v180 offset:2048
	ds_read_b128 v[180:183], v180 offset:3072
	s_add_u32 s16, s22, 0x160000
	s_addc_u32 s17, s23, 0
	s_mov_b32 m0, s34
	v_lshl_add_u64 v[222:223], s[16:17], 0, v[128:129]
	ds_read_b128 v[184:187], v155 offset:32768
	ds_read_b128 v[188:191], v155 offset:33792
	ds_read_b128 v[192:195], v155 offset:34816
	ds_read_b128 v[196:199], v155 offset:35840
	ds_read_b128 v[200:203], v155 offset:36864
	ds_read_b128 v[204:207], v155 offset:37888
	ds_read_b128 v[208:211], v155 offset:38912
	ds_read_b128 v[212:215], v155 offset:39936
	global_load_lds_dwordx4 v[222:223], off
	v_lshl_add_u64 v[222:223], s[16:17], 0, v[132:133]
	s_mov_b32 m0, s35
	s_nop 0
	global_load_lds_dwordx4 v[222:223], off
	s_waitcnt vmcnt(8)
	s_waitcnt lgkmcnt(0)
	s_barrier
	s_setprio 1
	v_mfma_f32_16x16x32_bf16 v[124:127], v[144:147], v[184:187], v[124:127]
	v_mfma_f32_16x16x32_bf16 v[120:123], v[160:163], v[184:187], v[120:123]
	v_mfma_f32_16x16x32_bf16 v[116:119], v[144:147], v[192:195], v[116:119]
	v_mfma_f32_16x16x32_bf16 v[112:115], v[160:163], v[192:195], v[112:115]
	v_mfma_f32_16x16x32_bf16 v[92:95], v[144:147], v[200:203], v[92:95]
	v_mfma_f32_16x16x32_bf16 v[88:91], v[160:163], v[200:203], v[88:91]
	v_mfma_f32_16x16x32_bf16 v[84:87], v[144:147], v[208:211], v[84:87]
	v_mfma_f32_16x16x32_bf16 v[80:83], v[160:163], v[208:211], v[80:83]
	v_mfma_f32_16x16x32_bf16 v[124:127], v[156:159], v[188:191], v[124:127]
	v_mfma_f32_16x16x32_bf16 v[120:123], v[164:167], v[188:191], v[120:123]
	v_mfma_f32_16x16x32_bf16 v[116:119], v[156:159], v[196:199], v[116:119]
	v_mfma_f32_16x16x32_bf16 v[112:115], v[164:167], v[196:199], v[112:115]
	v_mfma_f32_16x16x32_bf16 v[92:95], v[156:159], v[204:207], v[92:95]
	v_mfma_f32_16x16x32_bf16 v[88:91], v[164:167], v[204:207], v[88:91]
	v_mfma_f32_16x16x32_bf16 v[84:87], v[156:159], v[212:215], v[84:87]
	v_mfma_f32_16x16x32_bf16 v[80:83], v[164:167], v[212:215], v[80:83]
	v_mfma_f32_16x16x32_bf16 v[108:111], v[168:171], v[184:187], v[108:111]
	v_mfma_f32_16x16x32_bf16 v[104:107], v[176:179], v[184:187], v[104:107]
	v_mfma_f32_16x16x32_bf16 v[100:103], v[168:171], v[192:195], v[100:103]
	v_mfma_f32_16x16x32_bf16 v[96:99], v[176:179], v[192:195], v[96:99]
	v_mfma_f32_16x16x32_bf16 v[76:79], v[168:171], v[200:203], v[76:79]
	v_mfma_f32_16x16x32_bf16 v[72:75], v[176:179], v[200:203], v[72:75]
	v_mfma_f32_16x16x32_bf16 v[68:71], v[168:171], v[208:211], v[68:71]
	v_mfma_f32_16x16x32_bf16 v[64:67], v[176:179], v[208:211], v[64:67]
	v_mfma_f32_16x16x32_bf16 v[108:111], v[172:175], v[188:191], v[108:111]
	v_mfma_f32_16x16x32_bf16 v[104:107], v[180:183], v[188:191], v[104:107]
	v_mfma_f32_16x16x32_bf16 v[100:103], v[172:175], v[196:199], v[100:103]
	v_mfma_f32_16x16x32_bf16 v[96:99], v[180:183], v[196:199], v[96:99]
	v_mfma_f32_16x16x32_bf16 v[76:79], v[172:175], v[204:207], v[76:79]
	v_mfma_f32_16x16x32_bf16 v[72:75], v[180:183], v[204:207], v[72:75]
	v_mfma_f32_16x16x32_bf16 v[68:71], v[172:175], v[212:215], v[68:71]
	v_mfma_f32_16x16x32_bf16 v[64:67], v[180:183], v[212:215], v[64:67]
	s_setprio 0
	s_barrier
; #define PG8_STAGE(bufoff, gbase, voff) do { _Pragma("unroll") for (int _i = 0; _i < 2; ++_i) \
;         __builtin_amdgcn_global_load_lds((const unsigned*)((const char*)(gbase) + (voff)[_i]), (PG8_LAS unsigned*)(lds + (bufoff) + ldsw + _i * 8192), 16, 0, 0); } while (0)
; #define PG8_LDA(dst, b, h) do { _Pragma("unroll") for (int m = 0; m < 4; ++m) _Pragma("unroll") for (int k = 0; k < 2; ++k) dst[m][k] = *(const PG8_LAS bf16x8*)(lds + PG8_SA(b, h) + aoff + m * 2048 + k * 1024); } while (0)
; #define PG8_MMA(ai, bj, At, Bt) do { __builtin_amdgcn_s_setprio(1); _Pragma("unroll") for (int m = 0; m < 4; ++m) _Pragma("unroll") for (int n = 0; n < 2; ++n) _Pragma("unroll") for (int k = 0; k < 2; ++k) \
;         acc[ai][bj][m][n] = __builtin_amdgcn_mfma_f32_16x16x32_bf16(Bt[n][k], At[m][k], acc[ai][bj][m][n], 0, 0, 0); __builtin_amdgcn_s_setprio(0); } while (0)
; #define PG8_WAIT_V(n) asm volatile("s_waitcnt vmcnt(" #n ")" ::: "memory")
; #define PG8_WAIT_L(n) asm volatile("s_waitcnt lgkmcnt(" #n ")" ::: "memory")
; #define PG8_BAR __builtin_amdgcn_s_barrier()
; #define PG8_SCHED __builtin_amdgcn_sched_barrier(0)
; template <class Epi, class Sched, bool ALIGN_EPI = false, bool SP2 = false>
; __device__ __forceinline__ void gemm_phase(PG8_LAS unsigned char* lds, const Gemm g, const Sched& S, const Epi& E, const int wv0) {
;     ...
;         for (int t = 0; t < nt; t += 2) {
;             const bool last = (t == nt - 2);
;     ...
;             PG8_LDA(At, 1, 1); PG8_STAGE(PG8_SB(1, 0), b3, voffB); PG8_STAGE(PG8_SB(1, 1), b3 + hstepB, voffB); PG8_STAGE(PG8_SA(1, 0), a3, voffA);
;             PG8_WAIT_V(8); PG8_WAIT_L(0); PG8_BAR; PG8_MMA(1, 0, At, B0); PG8_MMA(1, 1, At, B1); PG8_BAR; PG8_SCHED;
	s_add_i32 s16, s49, s29
	v_lshl_add_u64 v[148:149], v[148:149], 0, s[8:9]
	s_mov_b32 m0, s16
	ds_read_b128 v[184:187], v155 offset:49152
	ds_read_b128 v[188:191], v155 offset:50176
	ds_read_b128 v[192:195], v155 offset:51200
	ds_read_b128 v[196:199], v155 offset:52224
	ds_read_b128 v[200:203], v155 offset:53248
	ds_read_b128 v[204:207], v155 offset:54272
	ds_read_b128 v[208:211], v155 offset:55296
	ds_read_b128 v[212:215], v155 offset:56320
	global_load_lds_dwordx4 v[148:149], off
	s_add_i32 m0, s16, 0x2000
	s_add_u32 s16, s20, 0x160080
	v_lshl_add_u64 v[148:149], v[216:217], 0, s[8:9]
	s_addc_u32 s17, s21, 0
	s_add_i32 s20, s50, s29
	global_load_lds_dwordx4 v[148:149], off
	v_lshl_add_u64 v[148:149], s[16:17], 0, v[130:131]
	s_mov_b32 m0, s20
	s_nop 0
	global_load_lds_dwordx4 v[148:149], off
	v_lshl_add_u64 v[148:149], s[16:17], 0, v[134:135]
	s_add_i32 m0, s20, 0x2000
	s_nop 0
	global_load_lds_dwordx4 v[148:149], off
	v_lshl_add_u64 v[148:149], v[218:219], 0, s[8:9]
	s_mov_b32 m0, s37
	s_nop 0
	global_load_lds_dwordx4 v[148:149], off
	v_lshl_add_u64 v[148:149], v[220:221], 0, s[8:9]
	s_mov_b32 m0, s38
	s_nop 0
	global_load_lds_dwordx4 v[148:149], off
	s_waitcnt vmcnt(8)
	s_waitcnt lgkmcnt(0)
	s_barrier
	s_setprio 1
	v_mfma_f32_16x16x32_bf16 v[60:63], v[144:147], v[184:187], v[60:63]
	v_mfma_f32_16x16x32_bf16 v[56:59], v[160:163], v[184:187], v[56:59]
	v_mfma_f32_16x16x32_bf16 v[52:55], v[144:147], v[192:195], v[52:55]
	v_mfma_f32_16x16x32_bf16 v[48:51], v[160:163], v[192:195], v[48:51]
	v_mfma_f32_16x16x32_bf16 v[28:31], v[144:147], v[200:203], v[28:31]
	v_mfma_f32_16x16x32_bf16 v[24:27], v[160:163], v[200:203], v[24:27]
	v_mfma_f32_16x16x32_bf16 v[20:23], v[144:147], v[208:211], v[20:23]
	v_mfma_f32_16x16x32_bf16 v[16:19], v[160:163], v[208:211], v[16:19]
	v_mfma_f32_16x16x32_bf16 v[60:63], v[156:159], v[188:191], v[60:63]
	v_mfma_f32_16x16x32_bf16 v[56:59], v[164:167], v[188:191], v[56:59]
	v_mfma_f32_16x16x32_bf16 v[52:55], v[156:159], v[196:199], v[52:55]
	v_mfma_f32_16x16x32_bf16 v[48:51], v[164:167], v[196:199], v[48:51]
	v_mfma_f32_16x16x32_bf16 v[28:31], v[156:159], v[204:207], v[28:31]
	v_mfma_f32_16x16x32_bf16 v[24:27], v[164:167], v[204:207], v[24:27]
	v_mfma_f32_16x16x32_bf16 v[20:23], v[156:159], v[212:215], v[20:23]
	v_mfma_f32_16x16x32_bf16 v[16:19], v[164:167], v[212:215], v[16:19]
	v_mfma_f32_16x16x32_bf16 v[44:47], v[168:171], v[184:187], v[44:47]
	v_mfma_f32_16x16x32_bf16 v[40:43], v[176:179], v[184:187], v[40:43]
	v_mfma_f32_16x16x32_bf16 v[36:39], v[168:171], v[192:195], v[36:39]
	v_mfma_f32_16x16x32_bf16 v[32:35], v[176:179], v[192:195], v[32:35]
	v_mfma_f32_16x16x32_bf16 v[12:15], v[168:171], v[200:203], v[12:15]
	v_mfma_f32_16x16x32_bf16 v[8:11], v[176:179], v[200:203], v[8:11]
	v_mfma_f32_16x16x32_bf16 v[4:7], v[168:171], v[208:211], v[4:7]
	v_mfma_f32_16x16x32_bf16 v[0:3], v[176:179], v[208:211], v[0:3]
	v_mfma_f32_16x16x32_bf16 v[44:47], v[172:175], v[188:191], v[44:47]
	v_mfma_f32_16x16x32_bf16 v[40:43], v[180:183], v[188:191], v[40:43]
	v_mfma_f32_16x16x32_bf16 v[36:39], v[172:175], v[196:199], v[36:39]
	v_mfma_f32_16x16x32_bf16 v[32:35], v[180:183], v[196:199], v[32:35]
	v_mfma_f32_16x16x32_bf16 v[12:15], v[172:175], v[204:207], v[12:15]
	v_mfma_f32_16x16x32_bf16 v[8:11], v[180:183], v[204:207], v[8:11]
	v_mfma_f32_16x16x32_bf16 v[4:7], v[172:175], v[212:215], v[4:7]
	v_mfma_f32_16x16x32_bf16 v[0:3], v[180:183], v[212:215], v[0:3]
	s_setprio 0
	s_add_i32 s48, s48, 2
	s_add_u32 s46, s46, 0x100
	s_addc_u32 s47, s47, 0
	s_cmpk_gt_u32 s48, 0x55
	s_mov_b64 s[16:17], s[18:19]
	s_barrier
	s_cbranch_scc0 .LBB0_1808
	s_and_b64 vcc, exec, s[10:11]
	s_cbranch_vccz .LBB0_1811
	s_barrier
